# stack: GEMM MFMA-segment heads without the redundant lgkmcnt(0) and without any s_setprio flip
# baseline (speedup 1.0000x reference)
.LBB0_179:
	s_add_u32 s29, s56, 0xfffc0080
	s_addc_u32 s30, s57, -1
	s_add_i32 s31, 0, 0x10000
	s_cmp_eq_u32 s28, 12
	s_cselect_b32 s61, s6, s30
	s_cselect_b32 s60, s7, s29
	s_cselect_b32 s59, s24, s27
	s_cselect_b32 s58, s25, s26
	s_add_i32 s29, 0, 0x14000
	v_add_u32_e32 v156, s31, v145
	v_add_u32_e32 v162, s29, v145
	ds_read_b128 v[140:143], v156
	ds_read_b128 v[148:151], v156 offset:1024
	ds_read_b128 v[152:155], v156 offset:2048
	ds_read_b128 v[156:159], v156 offset:3072
	ds_read_b128 v[178:181], v162
	ds_read_b128 v[182:185], v162 offset:1024
	ds_read_b128 v[186:189], v162 offset:2048
	ds_read_b128 v[190:193], v162 offset:3072
	v_lshl_add_u64 v[174:175], s[56:57], 0, v[136:137]
	s_add_i32 m0, s65, 0xc000
	ds_read_b128 v[194:197], v147
	ds_read_b128 v[198:201], v147 offset:1024
	ds_read_b128 v[202:205], v147 offset:2048
	ds_read_b128 v[220:223], v147 offset:3072
	ds_read_b128 v[228:231], v147 offset:4096
	ds_read_b128 v[232:235], v147 offset:5120
	ds_read_b128 v[236:239], v147 offset:6144
	ds_read_b128 v[240:243], v147 offset:7168
	global_load_lds_dwordx4 v[174:175], off
	v_lshl_add_u64 v[174:175], s[56:57], 0, v[138:139]
	s_add_i32 m0, s65, 0xe000
	s_nop 0
	global_load_lds_dwordx4 v[174:175], off
	s_waitcnt vmcnt(8)
	s_waitcnt lgkmcnt(0)
	s_barrier
	v_mfma_f32_16x16x32_bf16 v[124:127], v[140:143], v[194:197], v[124:127]
	v_mfma_f32_16x16x32_bf16 v[120:123], v[152:155], v[194:197], v[120:123]
	v_mfma_f32_16x16x32_bf16 v[108:111], v[140:143], v[202:205], v[108:111]
	v_mfma_f32_16x16x32_bf16 v[104:107], v[152:155], v[202:205], v[104:107]
	v_mfma_f32_16x16x32_bf16 v[92:95], v[140:143], v[228:231], v[92:95]
	v_mfma_f32_16x16x32_bf16 v[88:91], v[152:155], v[228:231], v[88:91]
	v_mfma_f32_16x16x32_bf16 v[76:79], v[140:143], v[236:239], v[76:79]
	v_mfma_f32_16x16x32_bf16 v[72:75], v[152:155], v[236:239], v[72:75]
	v_mfma_f32_16x16x32_bf16 v[124:127], v[148:151], v[198:201], v[124:127]
	v_mfma_f32_16x16x32_bf16 v[120:123], v[156:159], v[198:201], v[120:123]
	v_mfma_f32_16x16x32_bf16 v[108:111], v[148:151], v[220:223], v[108:111]
	v_mfma_f32_16x16x32_bf16 v[104:107], v[156:159], v[220:223], v[104:107]
	v_mfma_f32_16x16x32_bf16 v[92:95], v[148:151], v[232:235], v[92:95]
	v_mfma_f32_16x16x32_bf16 v[88:91], v[156:159], v[232:235], v[88:91]
	v_mfma_f32_16x16x32_bf16 v[76:79], v[148:151], v[240:243], v[76:79]
	v_mfma_f32_16x16x32_bf16 v[72:75], v[156:159], v[240:243], v[72:75]
	v_mfma_f32_16x16x32_bf16 v[116:119], v[178:181], v[194:197], v[116:119]
	v_mfma_f32_16x16x32_bf16 v[112:115], v[186:189], v[194:197], v[112:115]
	v_mfma_f32_16x16x32_bf16 v[100:103], v[178:181], v[202:205], v[100:103]
	v_mfma_f32_16x16x32_bf16 v[96:99], v[186:189], v[202:205], v[96:99]
	v_mfma_f32_16x16x32_bf16 v[84:87], v[178:181], v[228:231], v[84:87]
	v_mfma_f32_16x16x32_bf16 v[80:83], v[186:189], v[228:231], v[80:83]
	v_mfma_f32_16x16x32_bf16 v[68:71], v[178:181], v[236:239], v[68:71]
	v_mfma_f32_16x16x32_bf16 v[64:67], v[186:189], v[236:239], v[64:67]
	v_mfma_f32_16x16x32_bf16 v[116:119], v[182:185], v[198:201], v[116:119]
	v_mfma_f32_16x16x32_bf16 v[112:115], v[190:193], v[198:201], v[112:115]
	v_mfma_f32_16x16x32_bf16 v[100:103], v[182:185], v[220:223], v[100:103]
	v_mfma_f32_16x16x32_bf16 v[96:99], v[190:193], v[220:223], v[96:99]
	v_mfma_f32_16x16x32_bf16 v[84:87], v[182:185], v[232:235], v[84:87]
	v_mfma_f32_16x16x32_bf16 v[80:83], v[190:193], v[232:235], v[80:83]
	v_mfma_f32_16x16x32_bf16 v[68:71], v[182:185], v[240:243], v[68:71]
	v_mfma_f32_16x16x32_bf16 v[64:67], v[190:193], v[240:243], v[64:67]
	s_barrier
	s_add_i32 s30, s31, s64
	v_lshl_add_u64 v[174:175], s[58:59], 0, v[132:133]
	s_mov_b32 m0, s30
	ds_read_b128 v[194:197], v147 offset:16384
	ds_read_b128 v[198:201], v147 offset:17408
	ds_read_b128 v[202:205], v147 offset:18432
	ds_read_b128 v[220:223], v147 offset:19456
	ds_read_b128 v[228:231], v147 offset:20480
	ds_read_b128 v[232:235], v147 offset:21504
	ds_read_b128 v[236:239], v147 offset:22528
	ds_read_b128 v[240:243], v147 offset:23552
	global_load_lds_dwordx4 v[174:175], off
	s_add_i32 m0, s30, 0x2000
	s_add_u32 s30, s58, 0x40000
	v_lshl_add_u64 v[176:177], s[58:59], 0, v[128:129]
	s_addc_u32 s31, s59, 0
	s_add_i32 s29, s29, s64
	global_load_lds_dwordx4 v[176:177], off
	v_lshl_add_u64 v[244:245], s[30:31], 0, v[132:133]
	s_mov_b32 m0, s29
	v_lshl_add_u64 v[246:247], s[60:61], 0, v[130:131]
	global_load_lds_dwordx4 v[244:245], off
	v_lshl_add_u64 v[244:245], s[30:31], 0, v[128:129]
	s_add_i32 m0, s29, 0x2000
	s_nop 0
	global_load_lds_dwordx4 v[244:245], off
	v_lshl_add_u64 v[244:245], s[60:61], 0, v[134:135]
	s_mov_b32 m0, s65
	s_nop 0
	global_load_lds_dwordx4 v[244:245], off
	s_mov_b32 m0, s66
	s_nop 0
	global_load_lds_dwordx4 v[246:247], off
	s_waitcnt vmcnt(8)
	s_waitcnt lgkmcnt(0)
	s_barrier
	v_mfma_f32_16x16x32_bf16 v[60:63], v[140:143], v[194:197], v[60:63]
	v_mfma_f32_16x16x32_bf16 v[56:59], v[152:155], v[194:197], v[56:59]
	v_mfma_f32_16x16x32_bf16 v[44:47], v[140:143], v[202:205], v[44:47]
	v_mfma_f32_16x16x32_bf16 v[40:43], v[152:155], v[202:205], v[40:43]
	v_mfma_f32_16x16x32_bf16 v[28:31], v[140:143], v[228:231], v[28:31]
	v_mfma_f32_16x16x32_bf16 v[24:27], v[152:155], v[228:231], v[24:27]
	v_mfma_f32_16x16x32_bf16 v[12:15], v[140:143], v[236:239], v[12:15]
	v_mfma_f32_16x16x32_bf16 v[8:11], v[152:155], v[236:239], v[8:11]
	v_mfma_f32_16x16x32_bf16 v[60:63], v[148:151], v[198:201], v[60:63]
	v_mfma_f32_16x16x32_bf16 v[56:59], v[156:159], v[198:201], v[56:59]
	v_mfma_f32_16x16x32_bf16 v[44:47], v[148:151], v[220:223], v[44:47]
	v_mfma_f32_16x16x32_bf16 v[40:43], v[156:159], v[220:223], v[40:43]
	v_mfma_f32_16x16x32_bf16 v[28:31], v[148:151], v[232:235], v[28:31]
	v_mfma_f32_16x16x32_bf16 v[24:27], v[156:159], v[232:235], v[24:27]
	v_mfma_f32_16x16x32_bf16 v[12:15], v[148:151], v[240:243], v[12:15]
	v_mfma_f32_16x16x32_bf16 v[8:11], v[156:159], v[240:243], v[8:11]
	v_mfma_f32_16x16x32_bf16 v[52:55], v[178:181], v[194:197], v[52:55]
	v_mfma_f32_16x16x32_bf16 v[48:51], v[186:189], v[194:197], v[48:51]
	v_mfma_f32_16x16x32_bf16 v[36:39], v[178:181], v[202:205], v[36:39]
	v_mfma_f32_16x16x32_bf16 v[32:35], v[186:189], v[202:205], v[32:35]
	v_mfma_f32_16x16x32_bf16 v[20:23], v[178:181], v[228:231], v[20:23]
	v_mfma_f32_16x16x32_bf16 v[16:19], v[186:189], v[228:231], v[16:19]
	v_mfma_f32_16x16x32_bf16 v[4:7], v[178:181], v[236:239], v[4:7]
	v_mfma_f32_16x16x32_bf16 v[0:3], v[186:189], v[236:239], v[0:3]
	v_mfma_f32_16x16x32_bf16 v[52:55], v[182:185], v[198:201], v[52:55]
	v_mfma_f32_16x16x32_bf16 v[48:51], v[190:193], v[198:201], v[48:51]
	v_mfma_f32_16x16x32_bf16 v[36:39], v[182:185], v[220:223], v[36:39]
	v_mfma_f32_16x16x32_bf16 v[32:35], v[190:193], v[220:223], v[32:35]
	v_mfma_f32_16x16x32_bf16 v[20:23], v[182:185], v[232:235], v[20:23]
	v_mfma_f32_16x16x32_bf16 v[16:19], v[190:193], v[232:235], v[16:19]
	v_mfma_f32_16x16x32_bf16 v[4:7], v[182:185], v[240:243], v[4:7]
	v_mfma_f32_16x16x32_bf16 v[0:3], v[190:193], v[240:243], v[0:3]
	s_barrier
	s_add_i32 s29, 0, 0x18000
	s_add_i32 s49, 0, 0x1c000
	v_add_u32_e32 v156, s29, v145
	v_add_u32_e32 v162, s49, v145
	ds_read_b128 v[140:143], v156
	ds_read_b128 v[148:151], v156 offset:1024
	ds_read_b128 v[152:155], v156 offset:2048
	ds_read_b128 v[156:159], v156 offset:3072
	ds_read_b128 v[178:181], v162
	ds_read_b128 v[182:185], v162 offset:1024
	ds_read_b128 v[186:189], v162 offset:2048
	ds_read_b128 v[190:193], v162 offset:3072
	s_add_u32 s30, s60, 0x40000
	s_addc_u32 s31, s61, 0
	s_mov_b32 m0, s67
	v_lshl_add_u64 v[248:249], s[30:31], 0, v[134:135]
	ds_read_b128 v[194:197], v147 offset:32768
	ds_read_b128 v[198:201], v147 offset:33792
	ds_read_b128 v[202:205], v147 offset:34816
	ds_read_b128 v[220:223], v147 offset:35840
	ds_read_b128 v[228:231], v147 offset:36864
	ds_read_b128 v[232:235], v147 offset:37888
	ds_read_b128 v[236:239], v147 offset:38912
	ds_read_b128 v[240:243], v147 offset:39936
	global_load_lds_dwordx4 v[248:249], off
	v_lshl_add_u64 v[248:249], s[30:31], 0, v[130:131]
	s_mov_b32 m0, s68
	s_nop 0
	global_load_lds_dwordx4 v[248:249], off
	s_waitcnt vmcnt(8)
	s_waitcnt lgkmcnt(0)
	s_barrier
	v_mfma_f32_16x16x32_bf16 v[124:127], v[140:143], v[194:197], v[124:127]
	v_mfma_f32_16x16x32_bf16 v[120:123], v[152:155], v[194:197], v[120:123]
	v_mfma_f32_16x16x32_bf16 v[108:111], v[140:143], v[202:205], v[108:111]
	v_mfma_f32_16x16x32_bf16 v[104:107], v[152:155], v[202:205], v[104:107]
	v_mfma_f32_16x16x32_bf16 v[92:95], v[140:143], v[228:231], v[92:95]
	v_mfma_f32_16x16x32_bf16 v[88:91], v[152:155], v[228:231], v[88:91]
	v_mfma_f32_16x16x32_bf16 v[76:79], v[140:143], v[236:239], v[76:79]
	v_mfma_f32_16x16x32_bf16 v[72:75], v[152:155], v[236:239], v[72:75]
	v_mfma_f32_16x16x32_bf16 v[124:127], v[148:151], v[198:201], v[124:127]
	v_mfma_f32_16x16x32_bf16 v[120:123], v[156:159], v[198:201], v[120:123]
	v_mfma_f32_16x16x32_bf16 v[108:111], v[148:151], v[220:223], v[108:111]
	v_mfma_f32_16x16x32_bf16 v[104:107], v[156:159], v[220:223], v[104:107]
	v_mfma_f32_16x16x32_bf16 v[92:95], v[148:151], v[232:235], v[92:95]
	v_mfma_f32_16x16x32_bf16 v[88:91], v[156:159], v[232:235], v[88:91]
	v_mfma_f32_16x16x32_bf16 v[76:79], v[148:151], v[240:243], v[76:79]
	v_mfma_f32_16x16x32_bf16 v[72:75], v[156:159], v[240:243], v[72:75]
	v_mfma_f32_16x16x32_bf16 v[116:119], v[178:181], v[194:197], v[116:119]
	v_mfma_f32_16x16x32_bf16 v[112:115], v[186:189], v[194:197], v[112:115]
	v_mfma_f32_16x16x32_bf16 v[100:103], v[178:181], v[202:205], v[100:103]
	v_mfma_f32_16x16x32_bf16 v[96:99], v[186:189], v[202:205], v[96:99]
	v_mfma_f32_16x16x32_bf16 v[84:87], v[178:181], v[228:231], v[84:87]
	v_mfma_f32_16x16x32_bf16 v[80:83], v[186:189], v[228:231], v[80:83]
	v_mfma_f32_16x16x32_bf16 v[68:71], v[178:181], v[236:239], v[68:71]
	v_mfma_f32_16x16x32_bf16 v[64:67], v[186:189], v[236:239], v[64:67]
	v_mfma_f32_16x16x32_bf16 v[116:119], v[182:185], v[198:201], v[116:119]
	v_mfma_f32_16x16x32_bf16 v[112:115], v[190:193], v[198:201], v[112:115]
	v_mfma_f32_16x16x32_bf16 v[100:103], v[182:185], v[220:223], v[100:103]
	v_mfma_f32_16x16x32_bf16 v[96:99], v[190:193], v[220:223], v[96:99]
	v_mfma_f32_16x16x32_bf16 v[84:87], v[182:185], v[232:235], v[84:87]
	v_mfma_f32_16x16x32_bf16 v[80:83], v[190:193], v[232:235], v[80:83]
	v_mfma_f32_16x16x32_bf16 v[68:71], v[182:185], v[240:243], v[68:71]
	v_mfma_f32_16x16x32_bf16 v[64:67], v[190:193], v[240:243], v[64:67]
	s_barrier
	s_add_i32 s29, s29, s64
	v_lshl_add_u64 v[174:175], v[174:175], 0, s[4:5]
	s_mov_b32 m0, s29
	ds_read_b128 v[194:197], v147 offset:49152
	ds_read_b128 v[198:201], v147 offset:50176
	ds_read_b128 v[202:205], v147 offset:51200
	ds_read_b128 v[220:223], v147 offset:52224
	ds_read_b128 v[228:231], v147 offset:53248
	ds_read_b128 v[232:235], v147 offset:54272
	ds_read_b128 v[236:239], v147 offset:55296
	ds_read_b128 v[240:243], v147 offset:56320
	global_load_lds_dwordx4 v[174:175], off
	s_add_i32 m0, s29, 0x2000
	s_add_u32 s30, s58, 0x40080
	v_lshl_add_u64 v[174:175], v[176:177], 0, s[4:5]
	s_addc_u32 s31, s59, 0
	s_add_i32 s29, s49, s64
	global_load_lds_dwordx4 v[174:175], off
	v_lshl_add_u64 v[174:175], s[30:31], 0, v[132:133]
	s_mov_b32 m0, s29
	s_nop 0
	global_load_lds_dwordx4 v[174:175], off
	v_lshl_add_u64 v[174:175], s[30:31], 0, v[128:129]
	s_add_i32 m0, s29, 0x2000
	s_nop 0
	global_load_lds_dwordx4 v[174:175], off
	v_lshl_add_u64 v[174:175], v[244:245], 0, s[4:5]
	s_mov_b32 m0, s73
	s_nop 0
	global_load_lds_dwordx4 v[174:175], off
	v_lshl_add_u64 v[174:175], v[246:247], 0, s[4:5]
	s_mov_b32 m0, s74
	s_nop 0
	global_load_lds_dwordx4 v[174:175], off
	s_waitcnt vmcnt(8)
	s_waitcnt lgkmcnt(0)
	s_barrier
	v_mfma_f32_16x16x32_bf16 v[60:63], v[140:143], v[194:197], v[60:63]
	v_mfma_f32_16x16x32_bf16 v[56:59], v[152:155], v[194:197], v[56:59]
	v_mfma_f32_16x16x32_bf16 v[44:47], v[140:143], v[202:205], v[44:47]
	v_mfma_f32_16x16x32_bf16 v[40:43], v[152:155], v[202:205], v[40:43]
	v_mfma_f32_16x16x32_bf16 v[28:31], v[140:143], v[228:231], v[28:31]
	v_mfma_f32_16x16x32_bf16 v[24:27], v[152:155], v[228:231], v[24:27]
	v_mfma_f32_16x16x32_bf16 v[12:15], v[140:143], v[236:239], v[12:15]
	v_mfma_f32_16x16x32_bf16 v[8:11], v[152:155], v[236:239], v[8:11]
	v_mfma_f32_16x16x32_bf16 v[60:63], v[148:151], v[198:201], v[60:63]
	v_mfma_f32_16x16x32_bf16 v[56:59], v[156:159], v[198:201], v[56:59]
	v_mfma_f32_16x16x32_bf16 v[44:47], v[148:151], v[220:223], v[44:47]
	v_mfma_f32_16x16x32_bf16 v[40:43], v[156:159], v[220:223], v[40:43]
	v_mfma_f32_16x16x32_bf16 v[28:31], v[148:151], v[232:235], v[28:31]
	v_mfma_f32_16x16x32_bf16 v[24:27], v[156:159], v[232:235], v[24:27]
	v_mfma_f32_16x16x32_bf16 v[12:15], v[148:151], v[240:243], v[12:15]
	v_mfma_f32_16x16x32_bf16 v[8:11], v[156:159], v[240:243], v[8:11]
	v_mfma_f32_16x16x32_bf16 v[52:55], v[178:181], v[194:197], v[52:55]
	v_mfma_f32_16x16x32_bf16 v[48:51], v[186:189], v[194:197], v[48:51]
	v_mfma_f32_16x16x32_bf16 v[36:39], v[178:181], v[202:205], v[36:39]
	v_mfma_f32_16x16x32_bf16 v[32:35], v[186:189], v[202:205], v[32:35]
	v_mfma_f32_16x16x32_bf16 v[20:23], v[178:181], v[228:231], v[20:23]
	v_mfma_f32_16x16x32_bf16 v[16:19], v[186:189], v[228:231], v[16:19]
	v_mfma_f32_16x16x32_bf16 v[4:7], v[178:181], v[236:239], v[4:7]
	v_mfma_f32_16x16x32_bf16 v[0:3], v[186:189], v[236:239], v[0:3]
	v_mfma_f32_16x16x32_bf16 v[52:55], v[182:185], v[198:201], v[52:55]
	v_mfma_f32_16x16x32_bf16 v[48:51], v[190:193], v[198:201], v[48:51]
	v_mfma_f32_16x16x32_bf16 v[36:39], v[182:185], v[220:223], v[36:39]
	v_mfma_f32_16x16x32_bf16 v[32:35], v[190:193], v[220:223], v[32:35]
	v_mfma_f32_16x16x32_bf16 v[20:23], v[182:185], v[232:235], v[20:23]
	v_mfma_f32_16x16x32_bf16 v[16:19], v[190:193], v[232:235], v[16:19]
	v_mfma_f32_16x16x32_bf16 v[4:7], v[182:185], v[240:243], v[4:7]
	v_mfma_f32_16x16x32_bf16 v[0:3], v[190:193], v[240:243], v[0:3]
	s_barrier
	s_add_i32 s28, s28, 2
	s_add_u32 s56, s56, 0x100
	s_addc_u32 s57, s57, 0
	s_add_u32 s26, s26, 0x100
	s_addc_u32 s27, s27, 0
	s_cmp_gt_u32 s28, 13
	s_cbranch_scc0 .LBB0_179
	s_and_b64 vcc, exec, s[46:47]
	s_cbranch_vccz .LBB0_182
	s_barrier

.LBB0_204:
	s_add_u32 s28, s42, 0xfffc0080
	s_addc_u32 s29, s43, -1
	s_add_i32 s30, 0, 0x10000
	s_cmp_eq_u32 s27, 12
	s_cselect_b32 s63, s6, s29
	s_cselect_b32 s62, s7, s28
	s_cselect_b32 s61, s23, s26
	s_cselect_b32 s60, s24, s25
	s_add_i32 s31, 0, 0x14000
	v_add_u32_e32 v140, s30, v221
	v_add_u32_e32 v156, s31, v221
	ds_read_b128 v[128:131], v140
	ds_read_b128 v[132:135], v140 offset:1024
	ds_read_b128 v[136:139], v140 offset:2048
	ds_read_b128 v[140:143], v140 offset:3072
	ds_read_b128 v[144:147], v156
	ds_read_b128 v[148:151], v156 offset:1024
	ds_read_b128 v[152:155], v156 offset:2048
	ds_read_b128 v[156:159], v156 offset:3072
	v_lshl_add_u64 v[174:175], s[42:43], 0, v[184:185]
	s_add_i32 m0, s67, 0xc000
	ds_read_b128 v[188:191], v223
	ds_read_b128 v[192:195], v223 offset:1024
	ds_read_b128 v[196:199], v223 offset:2048
	ds_read_b128 v[200:203], v223 offset:3072
	ds_read_b128 v[228:231], v223 offset:4096
	ds_read_b128 v[232:235], v223 offset:5120
	ds_read_b128 v[236:239], v223 offset:6144
	ds_read_b128 v[240:243], v223 offset:7168
	global_load_lds_dwordx4 v[174:175], off
	v_lshl_add_u64 v[174:175], s[42:43], 0, v[186:187]
	s_add_i32 m0, s67, 0xe000
	s_nop 0
	global_load_lds_dwordx4 v[174:175], off
	s_waitcnt vmcnt(8)
	s_waitcnt lgkmcnt(0)
	s_barrier
	v_mfma_f32_16x16x32_bf16 v[124:127], v[128:131], v[188:191], v[124:127]
	v_mfma_f32_16x16x32_bf16 v[120:123], v[136:139], v[188:191], v[120:123]
	v_mfma_f32_16x16x32_bf16 v[116:119], v[128:131], v[196:199], v[116:119]
	v_mfma_f32_16x16x32_bf16 v[108:111], v[136:139], v[196:199], v[108:111]
	v_mfma_f32_16x16x32_bf16 v[100:103], v[128:131], v[228:231], v[100:103]
	v_mfma_f32_16x16x32_bf16 v[92:95], v[136:139], v[228:231], v[92:95]
	v_mfma_f32_16x16x32_bf16 v[84:87], v[128:131], v[236:239], v[84:87]
	v_mfma_f32_16x16x32_bf16 v[76:79], v[136:139], v[236:239], v[76:79]
	v_mfma_f32_16x16x32_bf16 v[124:127], v[132:135], v[192:195], v[124:127]
	v_mfma_f32_16x16x32_bf16 v[120:123], v[140:143], v[192:195], v[120:123]
	v_mfma_f32_16x16x32_bf16 v[116:119], v[132:135], v[200:203], v[116:119]
	v_mfma_f32_16x16x32_bf16 v[108:111], v[140:143], v[200:203], v[108:111]
	v_mfma_f32_16x16x32_bf16 v[100:103], v[132:135], v[232:235], v[100:103]
	v_mfma_f32_16x16x32_bf16 v[92:95], v[140:143], v[232:235], v[92:95]
	v_mfma_f32_16x16x32_bf16 v[84:87], v[132:135], v[240:243], v[84:87]
	v_mfma_f32_16x16x32_bf16 v[76:79], v[140:143], v[240:243], v[76:79]
	v_mfma_f32_16x16x32_bf16 v[112:115], v[144:147], v[188:191], v[112:115]
	v_mfma_f32_16x16x32_bf16 v[104:107], v[152:155], v[188:191], v[104:107]
	v_mfma_f32_16x16x32_bf16 v[96:99], v[144:147], v[196:199], v[96:99]
	v_mfma_f32_16x16x32_bf16 v[88:91], v[152:155], v[196:199], v[88:91]
	v_mfma_f32_16x16x32_bf16 v[80:83], v[144:147], v[228:231], v[80:83]
	v_mfma_f32_16x16x32_bf16 v[72:75], v[152:155], v[228:231], v[72:75]
	v_mfma_f32_16x16x32_bf16 v[68:71], v[144:147], v[236:239], v[68:71]
	v_mfma_f32_16x16x32_bf16 v[64:67], v[152:155], v[236:239], v[64:67]
	v_mfma_f32_16x16x32_bf16 v[112:115], v[148:151], v[192:195], v[112:115]
	v_mfma_f32_16x16x32_bf16 v[104:107], v[156:159], v[192:195], v[104:107]
	v_mfma_f32_16x16x32_bf16 v[96:99], v[148:151], v[200:203], v[96:99]
	v_mfma_f32_16x16x32_bf16 v[88:91], v[156:159], v[200:203], v[88:91]
	v_mfma_f32_16x16x32_bf16 v[80:83], v[148:151], v[232:235], v[80:83]
	v_mfma_f32_16x16x32_bf16 v[72:75], v[156:159], v[232:235], v[72:75]
	v_mfma_f32_16x16x32_bf16 v[68:71], v[148:151], v[240:243], v[68:71]
	v_mfma_f32_16x16x32_bf16 v[64:67], v[156:159], v[240:243], v[64:67]
	s_barrier
	s_add_i32 s28, s30, s66
	v_lshl_add_u64 v[174:175], s[60:61], 0, v[162:163]
	s_mov_b32 m0, s28
	ds_read_b128 v[188:191], v223 offset:16384
	ds_read_b128 v[192:195], v223 offset:17408
	ds_read_b128 v[196:199], v223 offset:18432
	ds_read_b128 v[200:203], v223 offset:19456
	ds_read_b128 v[228:231], v223 offset:20480
	ds_read_b128 v[232:235], v223 offset:21504
	ds_read_b128 v[236:239], v223 offset:22528
	ds_read_b128 v[240:243], v223 offset:23552
	global_load_lds_dwordx4 v[174:175], off
	s_add_i32 m0, s28, 0x2000
	s_add_u32 s28, s60, 0x40000
	v_lshl_add_u64 v[176:177], s[60:61], 0, v[178:179]
	s_addc_u32 s29, s61, 0
	s_add_i32 s30, s31, s66
	global_load_lds_dwordx4 v[176:177], off
	v_lshl_add_u64 v[204:205], s[28:29], 0, v[162:163]
	s_mov_b32 m0, s30
	v_lshl_add_u64 v[244:245], s[62:63], 0, v[180:181]
	global_load_lds_dwordx4 v[204:205], off
	v_lshl_add_u64 v[204:205], s[28:29], 0, v[178:179]
	s_add_i32 m0, s30, 0x2000
	s_nop 0
	global_load_lds_dwordx4 v[204:205], off
	v_lshl_add_u64 v[204:205], s[62:63], 0, v[182:183]
	s_mov_b32 m0, s67
	s_nop 0
	global_load_lds_dwordx4 v[204:205], off
	s_mov_b32 m0, s68
	s_nop 0
	global_load_lds_dwordx4 v[244:245], off
	s_waitcnt vmcnt(8)
	s_waitcnt lgkmcnt(0)
	s_barrier
	v_mfma_f32_16x16x32_bf16 v[60:63], v[128:131], v[188:191], v[60:63]
	v_mfma_f32_16x16x32_bf16 v[56:59], v[136:139], v[188:191], v[56:59]
	v_mfma_f32_16x16x32_bf16 v[52:55], v[128:131], v[196:199], v[52:55]
	v_mfma_f32_16x16x32_bf16 v[44:47], v[136:139], v[196:199], v[44:47]
	v_mfma_f32_16x16x32_bf16 v[36:39], v[128:131], v[228:231], v[36:39]
	v_mfma_f32_16x16x32_bf16 v[28:31], v[136:139], v[228:231], v[28:31]
	v_mfma_f32_16x16x32_bf16 v[20:23], v[128:131], v[236:239], v[20:23]
	v_mfma_f32_16x16x32_bf16 v[12:15], v[136:139], v[236:239], v[12:15]
	v_mfma_f32_16x16x32_bf16 v[60:63], v[132:135], v[192:195], v[60:63]
	v_mfma_f32_16x16x32_bf16 v[56:59], v[140:143], v[192:195], v[56:59]
	v_mfma_f32_16x16x32_bf16 v[52:55], v[132:135], v[200:203], v[52:55]
	v_mfma_f32_16x16x32_bf16 v[44:47], v[140:143], v[200:203], v[44:47]
	v_mfma_f32_16x16x32_bf16 v[36:39], v[132:135], v[232:235], v[36:39]
	v_mfma_f32_16x16x32_bf16 v[28:31], v[140:143], v[232:235], v[28:31]
	v_mfma_f32_16x16x32_bf16 v[20:23], v[132:135], v[240:243], v[20:23]
	v_mfma_f32_16x16x32_bf16 v[12:15], v[140:143], v[240:243], v[12:15]
	v_mfma_f32_16x16x32_bf16 v[48:51], v[144:147], v[188:191], v[48:51]
	v_mfma_f32_16x16x32_bf16 v[40:43], v[152:155], v[188:191], v[40:43]
	v_mfma_f32_16x16x32_bf16 v[32:35], v[144:147], v[196:199], v[32:35]
	v_mfma_f32_16x16x32_bf16 v[24:27], v[152:155], v[196:199], v[24:27]
	v_mfma_f32_16x16x32_bf16 v[16:19], v[144:147], v[228:231], v[16:19]
	v_mfma_f32_16x16x32_bf16 v[8:11], v[152:155], v[228:231], v[8:11]
	v_mfma_f32_16x16x32_bf16 v[4:7], v[144:147], v[236:239], v[4:7]
	v_mfma_f32_16x16x32_bf16 v[0:3], v[152:155], v[236:239], v[0:3]
	v_mfma_f32_16x16x32_bf16 v[48:51], v[148:151], v[192:195], v[48:51]
	v_mfma_f32_16x16x32_bf16 v[40:43], v[156:159], v[192:195], v[40:43]
	v_mfma_f32_16x16x32_bf16 v[32:35], v[148:151], v[200:203], v[32:35]
	v_mfma_f32_16x16x32_bf16 v[24:27], v[156:159], v[200:203], v[24:27]
	v_mfma_f32_16x16x32_bf16 v[16:19], v[148:151], v[232:235], v[16:19]
	v_mfma_f32_16x16x32_bf16 v[8:11], v[156:159], v[232:235], v[8:11]
	v_mfma_f32_16x16x32_bf16 v[4:7], v[148:151], v[240:243], v[4:7]
	v_mfma_f32_16x16x32_bf16 v[0:3], v[156:159], v[240:243], v[0:3]
	s_barrier
	s_add_i32 s30, 0, 0x18000
	s_add_i32 s31, 0, 0x1c000
	v_add_u32_e32 v140, s30, v221
	v_add_u32_e32 v156, s31, v221
	ds_read_b128 v[128:131], v140
	ds_read_b128 v[132:135], v140 offset:1024
	ds_read_b128 v[136:139], v140 offset:2048
	ds_read_b128 v[140:143], v140 offset:3072
	ds_read_b128 v[144:147], v156
	ds_read_b128 v[148:151], v156 offset:1024
	ds_read_b128 v[152:155], v156 offset:2048
	ds_read_b128 v[156:159], v156 offset:3072
	s_add_u32 s28, s62, 0x40000
	s_addc_u32 s29, s63, 0
	s_mov_b32 m0, s69
	v_lshl_add_u64 v[246:247], s[28:29], 0, v[182:183]
	ds_read_b128 v[188:191], v223 offset:32768
	ds_read_b128 v[192:195], v223 offset:33792
	ds_read_b128 v[196:199], v223 offset:34816
	ds_read_b128 v[200:203], v223 offset:35840
	ds_read_b128 v[228:231], v223 offset:36864
	ds_read_b128 v[232:235], v223 offset:37888
	ds_read_b128 v[236:239], v223 offset:38912
	ds_read_b128 v[240:243], v223 offset:39936
	global_load_lds_dwordx4 v[246:247], off
	v_lshl_add_u64 v[246:247], s[28:29], 0, v[180:181]
	s_mov_b32 m0, s70
	s_nop 0
	global_load_lds_dwordx4 v[246:247], off
	s_waitcnt vmcnt(8)
	s_waitcnt lgkmcnt(0)
	s_barrier
	v_mfma_f32_16x16x32_bf16 v[124:127], v[128:131], v[188:191], v[124:127]
	v_mfma_f32_16x16x32_bf16 v[120:123], v[136:139], v[188:191], v[120:123]
	v_mfma_f32_16x16x32_bf16 v[116:119], v[128:131], v[196:199], v[116:119]
	v_mfma_f32_16x16x32_bf16 v[108:111], v[136:139], v[196:199], v[108:111]
	v_mfma_f32_16x16x32_bf16 v[100:103], v[128:131], v[228:231], v[100:103]
	v_mfma_f32_16x16x32_bf16 v[92:95], v[136:139], v[228:231], v[92:95]
	v_mfma_f32_16x16x32_bf16 v[84:87], v[128:131], v[236:239], v[84:87]
	v_mfma_f32_16x16x32_bf16 v[76:79], v[136:139], v[236:239], v[76:79]
	v_mfma_f32_16x16x32_bf16 v[124:127], v[132:135], v[192:195], v[124:127]
	v_mfma_f32_16x16x32_bf16 v[120:123], v[140:143], v[192:195], v[120:123]
	v_mfma_f32_16x16x32_bf16 v[116:119], v[132:135], v[200:203], v[116:119]
	v_mfma_f32_16x16x32_bf16 v[108:111], v[140:143], v[200:203], v[108:111]
	v_mfma_f32_16x16x32_bf16 v[100:103], v[132:135], v[232:235], v[100:103]
	v_mfma_f32_16x16x32_bf16 v[92:95], v[140:143], v[232:235], v[92:95]
	v_mfma_f32_16x16x32_bf16 v[84:87], v[132:135], v[240:243], v[84:87]
	v_mfma_f32_16x16x32_bf16 v[76:79], v[140:143], v[240:243], v[76:79]
	v_mfma_f32_16x16x32_bf16 v[112:115], v[144:147], v[188:191], v[112:115]
	v_mfma_f32_16x16x32_bf16 v[104:107], v[152:155], v[188:191], v[104:107]
	v_mfma_f32_16x16x32_bf16 v[96:99], v[144:147], v[196:199], v[96:99]
	v_mfma_f32_16x16x32_bf16 v[88:91], v[152:155], v[196:199], v[88:91]
	v_mfma_f32_16x16x32_bf16 v[80:83], v[144:147], v[228:231], v[80:83]
	v_mfma_f32_16x16x32_bf16 v[72:75], v[152:155], v[228:231], v[72:75]
	v_mfma_f32_16x16x32_bf16 v[68:71], v[144:147], v[236:239], v[68:71]
	v_mfma_f32_16x16x32_bf16 v[64:67], v[152:155], v[236:239], v[64:67]
	v_mfma_f32_16x16x32_bf16 v[112:115], v[148:151], v[192:195], v[112:115]
	v_mfma_f32_16x16x32_bf16 v[104:107], v[156:159], v[192:195], v[104:107]
	v_mfma_f32_16x16x32_bf16 v[96:99], v[148:151], v[200:203], v[96:99]
	v_mfma_f32_16x16x32_bf16 v[88:91], v[156:159], v[200:203], v[88:91]
	v_mfma_f32_16x16x32_bf16 v[80:83], v[148:151], v[232:235], v[80:83]
	v_mfma_f32_16x16x32_bf16 v[72:75], v[156:159], v[232:235], v[72:75]
	v_mfma_f32_16x16x32_bf16 v[68:71], v[148:151], v[240:243], v[68:71]
	v_mfma_f32_16x16x32_bf16 v[64:67], v[156:159], v[240:243], v[64:67]
	s_barrier
	s_add_i32 s28, s30, s66
	v_lshl_add_u64 v[174:175], v[174:175], 0, s[4:5]
	s_mov_b32 m0, s28
	ds_read_b128 v[188:191], v223 offset:49152
	ds_read_b128 v[192:195], v223 offset:50176
	ds_read_b128 v[196:199], v223 offset:51200
	ds_read_b128 v[200:203], v223 offset:52224
	ds_read_b128 v[228:231], v223 offset:53248
	ds_read_b128 v[232:235], v223 offset:54272
	ds_read_b128 v[236:239], v223 offset:55296
	ds_read_b128 v[240:243], v223 offset:56320
	global_load_lds_dwordx4 v[174:175], off
	s_add_i32 m0, s28, 0x2000
	s_add_u32 s28, s60, 0x40080
	v_lshl_add_u64 v[174:175], v[176:177], 0, s[4:5]
	s_addc_u32 s29, s61, 0
	s_add_i32 s30, s31, s66
	global_load_lds_dwordx4 v[174:175], off
	v_lshl_add_u64 v[174:175], s[28:29], 0, v[162:163]
	s_mov_b32 m0, s30
	s_nop 0
	global_load_lds_dwordx4 v[174:175], off
	v_lshl_add_u64 v[174:175], s[28:29], 0, v[178:179]
	s_add_i32 m0, s30, 0x2000
	s_nop 0
	global_load_lds_dwordx4 v[174:175], off
	v_lshl_add_u64 v[174:175], v[204:205], 0, s[4:5]
	s_mov_b32 m0, s71
	s_nop 0
	global_load_lds_dwordx4 v[174:175], off
	v_lshl_add_u64 v[174:175], v[244:245], 0, s[4:5]
	s_mov_b32 m0, s72
	s_nop 0
	global_load_lds_dwordx4 v[174:175], off
	s_waitcnt vmcnt(8)
	s_waitcnt lgkmcnt(0)
	s_barrier
	v_mfma_f32_16x16x32_bf16 v[60:63], v[128:131], v[188:191], v[60:63]
	v_mfma_f32_16x16x32_bf16 v[56:59], v[136:139], v[188:191], v[56:59]
	v_mfma_f32_16x16x32_bf16 v[52:55], v[128:131], v[196:199], v[52:55]
	v_mfma_f32_16x16x32_bf16 v[44:47], v[136:139], v[196:199], v[44:47]
	v_mfma_f32_16x16x32_bf16 v[36:39], v[128:131], v[228:231], v[36:39]
	v_mfma_f32_16x16x32_bf16 v[28:31], v[136:139], v[228:231], v[28:31]
	v_mfma_f32_16x16x32_bf16 v[20:23], v[128:131], v[236:239], v[20:23]
	v_mfma_f32_16x16x32_bf16 v[12:15], v[136:139], v[236:239], v[12:15]
	v_mfma_f32_16x16x32_bf16 v[60:63], v[132:135], v[192:195], v[60:63]
	v_mfma_f32_16x16x32_bf16 v[56:59], v[140:143], v[192:195], v[56:59]
	v_mfma_f32_16x16x32_bf16 v[52:55], v[132:135], v[200:203], v[52:55]
	v_mfma_f32_16x16x32_bf16 v[44:47], v[140:143], v[200:203], v[44:47]
	v_mfma_f32_16x16x32_bf16 v[36:39], v[132:135], v[232:235], v[36:39]
	v_mfma_f32_16x16x32_bf16 v[28:31], v[140:143], v[232:235], v[28:31]
	v_mfma_f32_16x16x32_bf16 v[20:23], v[132:135], v[240:243], v[20:23]
	v_mfma_f32_16x16x32_bf16 v[12:15], v[140:143], v[240:243], v[12:15]
	v_mfma_f32_16x16x32_bf16 v[48:51], v[144:147], v[188:191], v[48:51]
	v_mfma_f32_16x16x32_bf16 v[40:43], v[152:155], v[188:191], v[40:43]
	v_mfma_f32_16x16x32_bf16 v[32:35], v[144:147], v[196:199], v[32:35]
	v_mfma_f32_16x16x32_bf16 v[24:27], v[152:155], v[196:199], v[24:27]
	v_mfma_f32_16x16x32_bf16 v[16:19], v[144:147], v[228:231], v[16:19]
	v_mfma_f32_16x16x32_bf16 v[8:11], v[152:155], v[228:231], v[8:11]
	v_mfma_f32_16x16x32_bf16 v[4:7], v[144:147], v[236:239], v[4:7]
	v_mfma_f32_16x16x32_bf16 v[0:3], v[152:155], v[236:239], v[0:3]
	v_mfma_f32_16x16x32_bf16 v[48:51], v[148:151], v[192:195], v[48:51]
	v_mfma_f32_16x16x32_bf16 v[40:43], v[156:159], v[192:195], v[40:43]
	v_mfma_f32_16x16x32_bf16 v[32:35], v[148:151], v[200:203], v[32:35]
	v_mfma_f32_16x16x32_bf16 v[24:27], v[156:159], v[200:203], v[24:27]
	v_mfma_f32_16x16x32_bf16 v[16:19], v[148:151], v[232:235], v[16:19]
	v_mfma_f32_16x16x32_bf16 v[8:11], v[156:159], v[232:235], v[8:11]
	v_mfma_f32_16x16x32_bf16 v[4:7], v[148:151], v[240:243], v[4:7]
	v_mfma_f32_16x16x32_bf16 v[0:3], v[156:159], v[240:243], v[0:3]
	s_barrier
	s_add_i32 s27, s27, 2
	s_add_u32 s42, s42, 0x100
	s_addc_u32 s43, s43, 0
	s_add_u32 s25, s25, 0x100
	s_addc_u32 s26, s26, 0
	s_cmp_gt_u32 s27, 13
	s_cbranch_scc0 .LBB0_204
	s_and_b64 vcc, exec, s[50:51]
	s_cbranch_vccz .LBB0_207
	s_barrier

.LBB0_502:
	s_add_i32 s62, 0, 0x10000
	s_add_i32 s61, 0, 0x14000
	v_add_u32_e32 v19, s62, v16
	v_add_u32_e32 v20, s61, v16
	ds_read_b128 v[22:25], v19
	ds_read_b128 v[26:29], v19 offset:1024
	ds_read_b128 v[30:33], v19 offset:2048
	ds_read_b128 v[34:37], v19 offset:3072
	ds_read_b128 v[38:41], v20
	ds_read_b128 v[42:45], v20 offset:1024
	ds_read_b128 v[46:49], v20 offset:2048
	ds_read_b128 v[50:53], v20 offset:3072
	s_add_u32 s58, s50, 0x18080
	s_addc_u32 s59, s51, 0
	s_add_i32 s65, s26, 0xc000
	v_lshl_add_u64 v[78:79], s[58:59], 0, v[6:7]
	s_mov_b32 m0, s65
	s_add_i32 s57, s26, 0xe000
	ds_read_b128 v[8:11], v17
	ds_read_b128 v[12:15], v17 offset:1024
	ds_read_b128 v[54:57], v17 offset:2048
	ds_read_b128 v[58:61], v17 offset:3072
	ds_read_b128 v[62:65], v17 offset:4096
	ds_read_b128 v[66:69], v17 offset:5120
	ds_read_b128 v[70:73], v17 offset:6144
	ds_read_b128 v[74:77], v17 offset:7168
	global_load_lds_dwordx4 v[78:79], off
	v_lshl_add_u64 v[78:79], s[58:59], 0, v[2:3]
	s_mov_b32 m0, s57
	s_nop 0
	global_load_lds_dwordx4 v[78:79], off
	s_waitcnt vmcnt(8)
	s_waitcnt lgkmcnt(0)
	s_barrier
	v_mfma_f32_16x16x32_bf16 v[78:81], v[22:25], v[8:11], 0
	v_mfma_f32_16x16x32_bf16 v[82:85], v[30:33], v[8:11], 0
	v_mfma_f32_16x16x32_bf16 v[86:89], v[22:25], v[54:57], 0
	v_mfma_f32_16x16x32_bf16 v[90:93], v[30:33], v[54:57], 0
	v_mfma_f32_16x16x32_bf16 v[94:97], v[22:25], v[62:65], 0
	v_mfma_f32_16x16x32_bf16 v[98:101], v[30:33], v[62:65], 0
	v_mfma_f32_16x16x32_bf16 v[102:105], v[22:25], v[70:73], 0
	v_mfma_f32_16x16x32_bf16 v[106:109], v[30:33], v[70:73], 0
	v_mfma_f32_16x16x32_bf16 v[78:81], v[26:29], v[12:15], v[78:81]
	v_mfma_f32_16x16x32_bf16 v[82:85], v[34:37], v[12:15], v[82:85]
	v_mfma_f32_16x16x32_bf16 v[86:89], v[26:29], v[58:61], v[86:89]
	v_mfma_f32_16x16x32_bf16 v[90:93], v[34:37], v[58:61], v[90:93]
	v_mfma_f32_16x16x32_bf16 v[94:97], v[26:29], v[66:69], v[94:97]
	v_mfma_f32_16x16x32_bf16 v[98:101], v[34:37], v[66:69], v[98:101]
	v_mfma_f32_16x16x32_bf16 v[102:105], v[26:29], v[74:77], v[102:105]
	v_mfma_f32_16x16x32_bf16 v[106:109], v[34:37], v[74:77], v[106:109]
	v_mfma_f32_16x16x32_bf16 v[110:113], v[38:41], v[8:11], 0
	v_mfma_f32_16x16x32_bf16 v[8:11], v[46:49], v[8:11], 0
	v_mfma_f32_16x16x32_bf16 v[114:117], v[50:53], v[12:15], v[8:11]
	v_mfma_f32_16x16x32_bf16 v[8:11], v[38:41], v[54:57], 0
	v_mfma_f32_16x16x32_bf16 v[118:121], v[42:45], v[58:61], v[8:11]
	v_mfma_f32_16x16x32_bf16 v[8:11], v[46:49], v[54:57], 0
	v_mfma_f32_16x16x32_bf16 v[54:57], v[50:53], v[58:61], v[8:11]
	v_mfma_f32_16x16x32_bf16 v[8:11], v[38:41], v[62:65], 0
	v_mfma_f32_16x16x32_bf16 v[58:61], v[42:45], v[66:69], v[8:11]
	v_mfma_f32_16x16x32_bf16 v[8:11], v[46:49], v[62:65], 0
	v_mfma_f32_16x16x32_bf16 v[62:65], v[50:53], v[66:69], v[8:11]
	v_mfma_f32_16x16x32_bf16 v[8:11], v[38:41], v[70:73], 0
	v_mfma_f32_16x16x32_bf16 v[66:69], v[42:45], v[74:77], v[8:11]
	v_mfma_f32_16x16x32_bf16 v[8:11], v[46:49], v[70:73], 0
	v_mfma_f32_16x16x32_bf16 v[110:113], v[42:45], v[12:15], v[110:113]
	v_mfma_f32_16x16x32_bf16 v[70:73], v[50:53], v[74:77], v[8:11]
	s_barrier
	s_nop 3
	v_lshl_add_u64 v[8:9], s[52:53], 0, v[4:5]
	s_mov_b64 s[68:69], 0x100
	s_add_i32 s62, s62, s25
	v_lshl_add_u64 v[10:11], v[8:9], 0, s[68:69]
	s_mov_b32 m0, s62
	s_add_i32 s58, s62, 0x2000
	ds_read_b128 v[74:77], v17 offset:16384
	ds_read_b128 v[122:125], v17 offset:17408
	ds_read_b128 v[126:129], v17 offset:18432
	ds_read_b128 v[130:133], v17 offset:19456
	ds_read_b128 v[134:137], v17 offset:20480
	ds_read_b128 v[138:141], v17 offset:21504
	ds_read_b128 v[142:145], v17 offset:22528
	ds_read_b128 v[146:149], v17 offset:23552
	global_load_lds_dwordx4 v[10:11], off
	v_lshl_add_u64 v[10:11], s[52:53], 0, v[0:1]
	s_add_u32 s66, s52, 0x18100
	v_lshl_add_u64 v[12:13], v[10:11], 0, s[68:69]
	s_mov_b32 m0, s58
	s_addc_u32 s67, s53, 0
	s_add_i32 s59, s61, s25
	global_load_lds_dwordx4 v[12:13], off
	v_lshl_add_u64 v[12:13], s[66:67], 0, v[4:5]
	s_mov_b32 m0, s59
	s_add_i32 s61, s59, 0x2000
	global_load_lds_dwordx4 v[12:13], off
	v_lshl_add_u64 v[12:13], s[66:67], 0, v[0:1]
	s_mov_b32 m0, s61
	s_nop 0
	global_load_lds_dwordx4 v[12:13], off
	v_lshl_add_u64 v[12:13], s[50:51], 0, v[6:7]
	v_lshl_add_u64 v[14:15], v[12:13], 0, s[68:69]
	s_mov_b32 m0, s26
	s_nop 0
	global_load_lds_dwordx4 v[14:15], off
	v_lshl_add_u64 v[14:15], s[50:51], 0, v[2:3]
	v_lshl_add_u64 v[150:151], v[14:15], 0, s[68:69]
	s_mov_b32 m0, s27
	s_nop 0
	global_load_lds_dwordx4 v[150:151], off
	s_waitcnt vmcnt(8)
	s_waitcnt lgkmcnt(0)
	s_barrier
	v_mfma_f32_16x16x32_bf16 v[150:153], v[22:25], v[74:77], 0
	v_mfma_f32_16x16x32_bf16 v[178:181], v[22:25], v[126:129], 0
	v_mfma_f32_16x16x32_bf16 v[186:189], v[22:25], v[134:137], 0
	v_mfma_f32_16x16x32_bf16 v[22:25], v[22:25], v[142:145], 0
	v_mfma_f32_16x16x32_bf16 v[150:153], v[26:29], v[122:125], v[150:153]
	v_mfma_f32_16x16x32_bf16 v[154:157], v[30:33], v[74:77], 0
	v_mfma_f32_16x16x32_bf16 v[178:181], v[26:29], v[130:133], v[178:181]
	v_mfma_f32_16x16x32_bf16 v[182:185], v[30:33], v[126:129], 0
	v_mfma_f32_16x16x32_bf16 v[186:189], v[26:29], v[138:141], v[186:189]
	v_mfma_f32_16x16x32_bf16 v[190:193], v[30:33], v[134:137], 0
	v_mfma_f32_16x16x32_bf16 v[24:27], v[26:29], v[146:149], v[22:25]
	v_mfma_f32_16x16x32_bf16 v[28:31], v[30:33], v[142:145], 0
	v_mfma_f32_16x16x32_bf16 v[154:157], v[34:37], v[122:125], v[154:157]
	v_mfma_f32_16x16x32_bf16 v[182:185], v[34:37], v[130:133], v[182:185]
	v_mfma_f32_16x16x32_bf16 v[190:193], v[34:37], v[138:141], v[190:193]
	v_mfma_f32_16x16x32_bf16 v[28:31], v[34:37], v[146:149], v[28:31]
	v_mfma_f32_16x16x32_bf16 v[32:35], v[38:41], v[74:77], 0
	v_mfma_f32_16x16x32_bf16 v[74:77], v[46:49], v[74:77], 0
	v_mfma_f32_16x16x32_bf16 v[32:35], v[42:45], v[122:125], v[32:35]
	v_mfma_f32_16x16x32_bf16 v[74:77], v[50:53], v[122:125], v[74:77]
	v_mfma_f32_16x16x32_bf16 v[122:125], v[38:41], v[126:129], 0
	v_mfma_f32_16x16x32_bf16 v[126:129], v[46:49], v[126:129], 0
	v_mfma_f32_16x16x32_bf16 v[122:125], v[42:45], v[130:133], v[122:125]
	v_mfma_f32_16x16x32_bf16 v[126:129], v[50:53], v[130:133], v[126:129]
	v_mfma_f32_16x16x32_bf16 v[130:133], v[38:41], v[134:137], 0
	v_mfma_f32_16x16x32_bf16 v[36:39], v[38:41], v[142:145], 0
	v_mfma_f32_16x16x32_bf16 v[130:133], v[42:45], v[138:141], v[130:133]
	v_mfma_f32_16x16x32_bf16 v[134:137], v[46:49], v[134:137], 0
	v_mfma_f32_16x16x32_bf16 v[36:39], v[42:45], v[146:149], v[36:39]
	v_mfma_f32_16x16x32_bf16 v[40:43], v[46:49], v[142:145], 0
	v_mfma_f32_16x16x32_bf16 v[134:137], v[50:53], v[138:141], v[134:137]
	v_mfma_f32_16x16x32_bf16 v[40:43], v[50:53], v[146:149], v[40:43]
	s_barrier
	s_add_i32 s63, 0, 0x18000
	s_add_i32 s64, 0, 0x1c000
	v_add_u32_e32 v21, s63, v16
	v_add_u32_e32 v22, s64, v16
	ds_read_b128 v[44:47], v21
	ds_read_b128 v[48:51], v21 offset:1024
	ds_read_b128 v[138:141], v21 offset:2048
	ds_read_b128 v[142:145], v21 offset:3072
	ds_read_b128 v[146:149], v22
	ds_read_b128 v[194:197], v22 offset:1024
	ds_read_b128 v[198:201], v22 offset:2048
	ds_read_b128 v[202:205], v22 offset:3072
	s_add_u32 s66, s50, 0x18100
	s_addc_u32 s67, s51, 0
	s_mov_b32 m0, s28
	v_lshl_add_u64 v[52:53], s[66:67], 0, v[6:7]
	ds_read_b128 v[220:223], v17 offset:32768
	ds_read_b128 v[228:231], v17 offset:33792
	ds_read_b128 v[232:235], v17 offset:34816
	ds_read_b128 v[236:239], v17 offset:35840
	ds_read_b128 v[240:243], v17 offset:36864
	ds_read_b128 v[244:247], v17 offset:37888
	ds_read_b128 v[248:251], v17 offset:38912
	ds_read_b128 v[174:177], v17 offset:39936
	global_load_lds_dwordx4 v[52:53], off
	v_lshl_add_u64 v[52:53], s[66:67], 0, v[2:3]
	s_mov_b32 m0, s29
	s_nop 0
	global_load_lds_dwordx4 v[52:53], off
	s_waitcnt vmcnt(8)
	s_waitcnt lgkmcnt(0)
	s_barrier
	v_mfma_f32_16x16x32_bf16 v[78:81], v[44:47], v[220:223], v[78:81]
	v_mfma_f32_16x16x32_bf16 v[82:85], v[138:141], v[220:223], v[82:85]
	v_mfma_f32_16x16x32_bf16 v[86:89], v[44:47], v[232:235], v[86:89]
	v_mfma_f32_16x16x32_bf16 v[90:93], v[138:141], v[232:235], v[90:93]
	v_mfma_f32_16x16x32_bf16 v[94:97], v[44:47], v[240:243], v[94:97]
	v_mfma_f32_16x16x32_bf16 v[98:101], v[138:141], v[240:243], v[98:101]
	v_mfma_f32_16x16x32_bf16 v[102:105], v[44:47], v[248:251], v[102:105]
	v_mfma_f32_16x16x32_bf16 v[106:109], v[138:141], v[248:251], v[106:109]
	v_mfma_f32_16x16x32_bf16 v[78:81], v[48:51], v[228:231], v[78:81]
	v_mfma_f32_16x16x32_bf16 v[82:85], v[142:145], v[228:231], v[82:85]
	v_mfma_f32_16x16x32_bf16 v[86:89], v[48:51], v[236:239], v[86:89]
	v_mfma_f32_16x16x32_bf16 v[90:93], v[142:145], v[236:239], v[90:93]
	v_mfma_f32_16x16x32_bf16 v[94:97], v[48:51], v[244:247], v[94:97]
	v_mfma_f32_16x16x32_bf16 v[98:101], v[142:145], v[244:247], v[98:101]
	v_mfma_f32_16x16x32_bf16 v[102:105], v[48:51], v[174:177], v[102:105]
	v_mfma_f32_16x16x32_bf16 v[106:109], v[142:145], v[174:177], v[106:109]
	v_mfma_f32_16x16x32_bf16 v[110:113], v[146:149], v[220:223], v[110:113]
	v_mfma_f32_16x16x32_bf16 v[114:117], v[198:201], v[220:223], v[114:117]
	v_mfma_f32_16x16x32_bf16 v[118:121], v[146:149], v[232:235], v[118:121]
	v_mfma_f32_16x16x32_bf16 v[52:55], v[198:201], v[232:235], v[54:57]
	v_mfma_f32_16x16x32_bf16 v[56:59], v[146:149], v[240:243], v[58:61]
	v_mfma_f32_16x16x32_bf16 v[60:63], v[198:201], v[240:243], v[62:65]
	v_mfma_f32_16x16x32_bf16 v[64:67], v[146:149], v[248:251], v[66:69]
	v_mfma_f32_16x16x32_bf16 v[68:71], v[198:201], v[248:251], v[70:73]
	v_mfma_f32_16x16x32_bf16 v[110:113], v[194:197], v[228:231], v[110:113]
	v_mfma_f32_16x16x32_bf16 v[114:117], v[202:205], v[228:231], v[114:117]
	v_mfma_f32_16x16x32_bf16 v[118:121], v[194:197], v[236:239], v[118:121]
	v_mfma_f32_16x16x32_bf16 v[52:55], v[202:205], v[236:239], v[52:55]
	v_mfma_f32_16x16x32_bf16 v[56:59], v[194:197], v[244:247], v[56:59]
	v_mfma_f32_16x16x32_bf16 v[60:63], v[202:205], v[244:247], v[60:63]
	v_mfma_f32_16x16x32_bf16 v[64:67], v[194:197], v[174:177], v[64:67]
	v_mfma_f32_16x16x32_bf16 v[68:71], v[202:205], v[174:177], v[68:71]
	s_barrier
	s_add_i32 s67, s63, s25
	s_mov_b64 s[70:71], 0x180
	s_add_i32 s63, s67, 0x2000
	v_lshl_add_u64 v[72:73], v[8:9], 0, s[70:71]
	s_mov_b32 m0, s67
	s_add_u32 s68, s52, 0x18180
	ds_read_b128 v[174:177], v17 offset:49152
	ds_read_b128 v[220:223], v17 offset:50176
	ds_read_b128 v[228:231], v17 offset:51200
	ds_read_b128 v[232:235], v17 offset:52224
	ds_read_b128 v[236:239], v17 offset:53248
	ds_read_b128 v[240:243], v17 offset:54272
	ds_read_b128 v[244:247], v17 offset:55296
	ds_read_b128 v[248:251], v17 offset:56320
	global_load_lds_dwordx4 v[72:73], off
	v_lshl_add_u64 v[72:73], v[10:11], 0, s[70:71]
	s_mov_b32 m0, s63
	s_addc_u32 s69, s53, 0
	s_add_i32 s64, s64, s25
	global_load_lds_dwordx4 v[72:73], off
	v_lshl_add_u64 v[72:73], s[68:69], 0, v[4:5]
	s_mov_b32 m0, s64
	s_add_i32 s66, s64, 0x2000
	global_load_lds_dwordx4 v[72:73], off
	v_lshl_add_u64 v[72:73], s[68:69], 0, v[0:1]
	s_mov_b32 m0, s66
	s_nop 0
	global_load_lds_dwordx4 v[72:73], off
	v_lshl_add_u64 v[72:73], v[12:13], 0, s[70:71]
	s_mov_b32 m0, s30
	s_nop 0
	global_load_lds_dwordx4 v[72:73], off
	v_lshl_add_u64 v[72:73], v[14:15], 0, s[70:71]
	s_mov_b32 m0, s31
	s_nop 0
	global_load_lds_dwordx4 v[72:73], off
	s_waitcnt vmcnt(8)
	s_waitcnt lgkmcnt(0)
	s_barrier
	v_mfma_f32_16x16x32_bf16 v[150:153], v[44:47], v[174:177], v[150:153]
	v_mfma_f32_16x16x32_bf16 v[154:157], v[138:141], v[174:177], v[154:157]
	v_mfma_f32_16x16x32_bf16 v[178:181], v[44:47], v[228:231], v[178:181]
	v_mfma_f32_16x16x32_bf16 v[182:185], v[138:141], v[228:231], v[182:185]
	v_mfma_f32_16x16x32_bf16 v[186:189], v[44:47], v[236:239], v[186:189]
	v_mfma_f32_16x16x32_bf16 v[190:193], v[138:141], v[236:239], v[190:193]
	v_mfma_f32_16x16x32_bf16 v[24:27], v[44:47], v[244:247], v[24:27]
	v_mfma_f32_16x16x32_bf16 v[28:31], v[138:141], v[244:247], v[28:31]
	v_mfma_f32_16x16x32_bf16 v[150:153], v[48:51], v[220:223], v[150:153]
	v_mfma_f32_16x16x32_bf16 v[154:157], v[142:145], v[220:223], v[154:157]
	v_mfma_f32_16x16x32_bf16 v[178:181], v[48:51], v[232:235], v[178:181]
	v_mfma_f32_16x16x32_bf16 v[182:185], v[142:145], v[232:235], v[182:185]
	v_mfma_f32_16x16x32_bf16 v[186:189], v[48:51], v[240:243], v[186:189]
	v_mfma_f32_16x16x32_bf16 v[190:193], v[142:145], v[240:243], v[190:193]
	v_mfma_f32_16x16x32_bf16 v[24:27], v[48:51], v[248:251], v[24:27]
	v_mfma_f32_16x16x32_bf16 v[28:31], v[142:145], v[248:251], v[28:31]
	v_mfma_f32_16x16x32_bf16 v[32:35], v[146:149], v[174:177], v[32:35]
	v_mfma_f32_16x16x32_bf16 v[44:47], v[198:201], v[174:177], v[74:77]
	v_mfma_f32_16x16x32_bf16 v[48:51], v[146:149], v[228:231], v[122:125]
	v_mfma_f32_16x16x32_bf16 v[72:75], v[198:201], v[228:231], v[126:129]
	v_mfma_f32_16x16x32_bf16 v[122:125], v[146:149], v[236:239], v[130:133]
	v_mfma_f32_16x16x32_bf16 v[126:129], v[198:201], v[236:239], v[134:137]
	v_mfma_f32_16x16x32_bf16 v[36:39], v[146:149], v[244:247], v[36:39]
	v_mfma_f32_16x16x32_bf16 v[40:43], v[198:201], v[244:247], v[40:43]
	v_mfma_f32_16x16x32_bf16 v[32:35], v[194:197], v[220:223], v[32:35]
	v_mfma_f32_16x16x32_bf16 v[44:47], v[202:205], v[220:223], v[44:47]
	v_mfma_f32_16x16x32_bf16 v[48:51], v[194:197], v[232:235], v[48:51]
	v_mfma_f32_16x16x32_bf16 v[72:75], v[202:205], v[232:235], v[72:75]
	v_mfma_f32_16x16x32_bf16 v[122:125], v[194:197], v[240:243], v[122:125]
	v_mfma_f32_16x16x32_bf16 v[126:129], v[202:205], v[240:243], v[126:129]
	v_mfma_f32_16x16x32_bf16 v[36:39], v[194:197], v[248:251], v[36:39]
	v_mfma_f32_16x16x32_bf16 v[40:43], v[202:205], v[248:251], v[40:43]
	s_barrier
	ds_read_b128 v[130:133], v19
	ds_read_b128 v[134:137], v19 offset:1024
	ds_read_b128 v[138:141], v19 offset:2048
	ds_read_b128 v[142:145], v19 offset:3072
	ds_read_b128 v[146:149], v20
	ds_read_b128 v[174:177], v20 offset:1024
	ds_read_b128 v[194:197], v20 offset:2048
	ds_read_b128 v[198:201], v20 offset:3072
	s_add_u32 s68, s50, 0x18180
	s_addc_u32 s69, s51, 0
	s_mov_b32 m0, s65
	v_lshl_add_u64 v[76:77], s[68:69], 0, v[6:7]
	ds_read_b128 v[202:205], v17
	ds_read_b128 v[220:223], v17 offset:1024
	ds_read_b128 v[228:231], v17 offset:2048
	ds_read_b128 v[232:235], v17 offset:3072
	ds_read_b128 v[236:239], v17 offset:4096
	ds_read_b128 v[240:243], v17 offset:5120
	ds_read_b128 v[244:247], v17 offset:6144
	ds_read_b128 v[248:251], v17 offset:7168
	global_load_lds_dwordx4 v[76:77], off
	v_lshl_add_u64 v[76:77], s[68:69], 0, v[2:3]
	s_mov_b32 m0, s57
	s_nop 0
	global_load_lds_dwordx4 v[76:77], off
	s_waitcnt vmcnt(8)
	s_waitcnt lgkmcnt(0)
	s_barrier
	v_mfma_f32_16x16x32_bf16 v[76:79], v[130:133], v[202:205], v[78:81]
	v_mfma_f32_16x16x32_bf16 v[80:83], v[138:141], v[202:205], v[82:85]
	v_mfma_f32_16x16x32_bf16 v[84:87], v[130:133], v[228:231], v[86:89]
	v_mfma_f32_16x16x32_bf16 v[88:91], v[138:141], v[228:231], v[90:93]
	v_mfma_f32_16x16x32_bf16 v[92:95], v[130:133], v[236:239], v[94:97]
	v_mfma_f32_16x16x32_bf16 v[96:99], v[138:141], v[236:239], v[98:101]
	v_mfma_f32_16x16x32_bf16 v[100:103], v[130:133], v[244:247], v[102:105]
	v_mfma_f32_16x16x32_bf16 v[104:107], v[138:141], v[244:247], v[106:109]
	v_mfma_f32_16x16x32_bf16 v[76:79], v[134:137], v[220:223], v[76:79]
	v_mfma_f32_16x16x32_bf16 v[80:83], v[142:145], v[220:223], v[80:83]
	v_mfma_f32_16x16x32_bf16 v[84:87], v[134:137], v[232:235], v[84:87]
	v_mfma_f32_16x16x32_bf16 v[88:91], v[142:145], v[232:235], v[88:91]
	v_mfma_f32_16x16x32_bf16 v[92:95], v[134:137], v[240:243], v[92:95]
	v_mfma_f32_16x16x32_bf16 v[96:99], v[142:145], v[240:243], v[96:99]
	v_mfma_f32_16x16x32_bf16 v[100:103], v[134:137], v[248:251], v[100:103]
	v_mfma_f32_16x16x32_bf16 v[104:107], v[142:145], v[248:251], v[104:107]
	v_mfma_f32_16x16x32_bf16 v[108:111], v[146:149], v[202:205], v[110:113]
	v_mfma_f32_16x16x32_bf16 v[112:115], v[194:197], v[202:205], v[114:117]
	v_mfma_f32_16x16x32_bf16 v[116:119], v[146:149], v[228:231], v[118:121]
	v_mfma_f32_16x16x32_bf16 v[52:55], v[194:197], v[228:231], v[52:55]
	v_mfma_f32_16x16x32_bf16 v[56:59], v[146:149], v[236:239], v[56:59]
	v_mfma_f32_16x16x32_bf16 v[60:63], v[194:197], v[236:239], v[60:63]
	v_mfma_f32_16x16x32_bf16 v[64:67], v[146:149], v[244:247], v[64:67]
	v_mfma_f32_16x16x32_bf16 v[68:71], v[194:197], v[244:247], v[68:71]
	v_mfma_f32_16x16x32_bf16 v[108:111], v[174:177], v[220:223], v[108:111]
	v_mfma_f32_16x16x32_bf16 v[112:115], v[198:201], v[220:223], v[112:115]
	v_mfma_f32_16x16x32_bf16 v[116:119], v[174:177], v[232:235], v[116:119]
	v_mfma_f32_16x16x32_bf16 v[52:55], v[198:201], v[232:235], v[52:55]
	v_mfma_f32_16x16x32_bf16 v[56:59], v[174:177], v[240:243], v[56:59]
	v_mfma_f32_16x16x32_bf16 v[60:63], v[198:201], v[240:243], v[60:63]
	v_mfma_f32_16x16x32_bf16 v[64:67], v[174:177], v[248:251], v[64:67]
	v_mfma_f32_16x16x32_bf16 v[68:71], v[198:201], v[248:251], v[68:71]
	s_barrier
	s_mov_b64 s[70:71], 0x200
	s_mov_b32 m0, s62
	v_lshl_add_u64 v[120:121], v[8:9], 0, s[70:71]
	s_add_u32 s68, s52, 0x18200
	ds_read_b128 v[202:205], v17 offset:16384
	ds_read_b128 v[220:223], v17 offset:17408
	ds_read_b128 v[228:231], v17 offset:18432
	ds_read_b128 v[232:235], v17 offset:19456
	ds_read_b128 v[236:239], v17 offset:20480
	ds_read_b128 v[240:243], v17 offset:21504
	ds_read_b128 v[244:247], v17 offset:22528
	ds_read_b128 v[248:251], v17 offset:23552
	global_load_lds_dwordx4 v[120:121], off
	v_lshl_add_u64 v[120:121], v[10:11], 0, s[70:71]
	s_mov_b32 m0, s58
	s_addc_u32 s69, s53, 0
	global_load_lds_dwordx4 v[120:121], off
	v_lshl_add_u64 v[120:121], s[68:69], 0, v[4:5]
	s_mov_b32 m0, s59
	s_nop 0
	global_load_lds_dwordx4 v[120:121], off
	v_lshl_add_u64 v[120:121], s[68:69], 0, v[0:1]
	s_mov_b32 m0, s61
	s_nop 0
	global_load_lds_dwordx4 v[120:121], off
	v_lshl_add_u64 v[120:121], v[12:13], 0, s[70:71]
	s_mov_b32 m0, s26
	s_nop 0
	global_load_lds_dwordx4 v[120:121], off
	v_lshl_add_u64 v[120:121], v[14:15], 0, s[70:71]
	s_mov_b32 m0, s27
	s_nop 0
	global_load_lds_dwordx4 v[120:121], off
	s_waitcnt vmcnt(8)
	s_waitcnt lgkmcnt(0)
	s_barrier
	v_mfma_f32_16x16x32_bf16 v[150:153], v[130:133], v[202:205], v[150:153]
	v_mfma_f32_16x16x32_bf16 v[154:157], v[138:141], v[202:205], v[154:157]
	v_mfma_f32_16x16x32_bf16 v[178:181], v[130:133], v[228:231], v[178:181]
	v_mfma_f32_16x16x32_bf16 v[182:185], v[138:141], v[228:231], v[182:185]
	v_mfma_f32_16x16x32_bf16 v[186:189], v[130:133], v[236:239], v[186:189]
	v_mfma_f32_16x16x32_bf16 v[190:193], v[138:141], v[236:239], v[190:193]
	v_mfma_f32_16x16x32_bf16 v[24:27], v[130:133], v[244:247], v[24:27]
	v_mfma_f32_16x16x32_bf16 v[28:31], v[138:141], v[244:247], v[28:31]
	v_mfma_f32_16x16x32_bf16 v[150:153], v[134:137], v[220:223], v[150:153]
	v_mfma_f32_16x16x32_bf16 v[154:157], v[142:145], v[220:223], v[154:157]
	v_mfma_f32_16x16x32_bf16 v[178:181], v[134:137], v[232:235], v[178:181]
	v_mfma_f32_16x16x32_bf16 v[182:185], v[142:145], v[232:235], v[182:185]
	v_mfma_f32_16x16x32_bf16 v[186:189], v[134:137], v[240:243], v[186:189]
	v_mfma_f32_16x16x32_bf16 v[190:193], v[142:145], v[240:243], v[190:193]
	v_mfma_f32_16x16x32_bf16 v[24:27], v[134:137], v[248:251], v[24:27]
	v_mfma_f32_16x16x32_bf16 v[28:31], v[142:145], v[248:251], v[28:31]
	v_mfma_f32_16x16x32_bf16 v[32:35], v[146:149], v[202:205], v[32:35]
	v_mfma_f32_16x16x32_bf16 v[44:47], v[194:197], v[202:205], v[44:47]
	v_mfma_f32_16x16x32_bf16 v[48:51], v[146:149], v[228:231], v[48:51]
	v_mfma_f32_16x16x32_bf16 v[72:75], v[194:197], v[228:231], v[72:75]
	v_mfma_f32_16x16x32_bf16 v[120:123], v[146:149], v[236:239], v[122:125]
	v_mfma_f32_16x16x32_bf16 v[124:127], v[194:197], v[236:239], v[126:129]
	v_mfma_f32_16x16x32_bf16 v[36:39], v[146:149], v[244:247], v[36:39]
	v_mfma_f32_16x16x32_bf16 v[40:43], v[194:197], v[244:247], v[40:43]
	v_mfma_f32_16x16x32_bf16 v[32:35], v[174:177], v[220:223], v[32:35]
	v_mfma_f32_16x16x32_bf16 v[44:47], v[198:201], v[220:223], v[44:47]
	v_mfma_f32_16x16x32_bf16 v[48:51], v[174:177], v[232:235], v[48:51]
	v_mfma_f32_16x16x32_bf16 v[72:75], v[198:201], v[232:235], v[72:75]
	v_mfma_f32_16x16x32_bf16 v[120:123], v[174:177], v[240:243], v[120:123]
	v_mfma_f32_16x16x32_bf16 v[124:127], v[198:201], v[240:243], v[124:127]
	v_mfma_f32_16x16x32_bf16 v[36:39], v[174:177], v[248:251], v[36:39]
	v_mfma_f32_16x16x32_bf16 v[40:43], v[198:201], v[248:251], v[40:43]
	s_barrier
	ds_read_b128 v[128:131], v21
	ds_read_b128 v[132:135], v21 offset:1024
	ds_read_b128 v[136:139], v21 offset:2048
	ds_read_b128 v[140:143], v21 offset:3072
	ds_read_b128 v[144:147], v22
	ds_read_b128 v[174:177], v22 offset:1024
	ds_read_b128 v[194:197], v22 offset:2048
	ds_read_b128 v[198:201], v22 offset:3072
	s_add_u32 s68, s50, 0x18200
	s_addc_u32 s69, s51, 0
	s_mov_b32 m0, s28
	v_lshl_add_u64 v[148:149], s[68:69], 0, v[6:7]
	ds_read_b128 v[202:205], v17 offset:32768
	ds_read_b128 v[220:223], v17 offset:33792
	ds_read_b128 v[228:231], v17 offset:34816
	ds_read_b128 v[232:235], v17 offset:35840
	ds_read_b128 v[236:239], v17 offset:36864
	ds_read_b128 v[240:243], v17 offset:37888
	ds_read_b128 v[244:247], v17 offset:38912
	ds_read_b128 v[248:251], v17 offset:39936
	global_load_lds_dwordx4 v[148:149], off
	v_lshl_add_u64 v[148:149], s[68:69], 0, v[2:3]
	s_mov_b32 m0, s29
	s_nop 0
	global_load_lds_dwordx4 v[148:149], off
	s_waitcnt vmcnt(8)
	s_waitcnt lgkmcnt(0)
	s_barrier
	v_mfma_f32_16x16x32_bf16 v[76:79], v[128:131], v[202:205], v[76:79]
	v_mfma_f32_16x16x32_bf16 v[80:83], v[136:139], v[202:205], v[80:83]
	v_mfma_f32_16x16x32_bf16 v[84:87], v[128:131], v[228:231], v[84:87]
	v_mfma_f32_16x16x32_bf16 v[88:91], v[136:139], v[228:231], v[88:91]
	v_mfma_f32_16x16x32_bf16 v[92:95], v[128:131], v[236:239], v[92:95]
	v_mfma_f32_16x16x32_bf16 v[96:99], v[136:139], v[236:239], v[96:99]
	v_mfma_f32_16x16x32_bf16 v[100:103], v[128:131], v[244:247], v[100:103]
	v_mfma_f32_16x16x32_bf16 v[104:107], v[136:139], v[244:247], v[104:107]
	v_mfma_f32_16x16x32_bf16 v[76:79], v[132:135], v[220:223], v[76:79]
	v_mfma_f32_16x16x32_bf16 v[80:83], v[140:143], v[220:223], v[80:83]
	v_mfma_f32_16x16x32_bf16 v[84:87], v[132:135], v[232:235], v[84:87]
	v_mfma_f32_16x16x32_bf16 v[88:91], v[140:143], v[232:235], v[88:91]
	v_mfma_f32_16x16x32_bf16 v[92:95], v[132:135], v[240:243], v[92:95]
	v_mfma_f32_16x16x32_bf16 v[96:99], v[140:143], v[240:243], v[96:99]
	v_mfma_f32_16x16x32_bf16 v[100:103], v[132:135], v[248:251], v[100:103]
	v_mfma_f32_16x16x32_bf16 v[104:107], v[140:143], v[248:251], v[104:107]
	v_mfma_f32_16x16x32_bf16 v[108:111], v[144:147], v[202:205], v[108:111]
	v_mfma_f32_16x16x32_bf16 v[112:115], v[194:197], v[202:205], v[112:115]
	v_mfma_f32_16x16x32_bf16 v[116:119], v[144:147], v[228:231], v[116:119]
	v_mfma_f32_16x16x32_bf16 v[52:55], v[194:197], v[228:231], v[52:55]
	v_mfma_f32_16x16x32_bf16 v[56:59], v[144:147], v[236:239], v[56:59]
	v_mfma_f32_16x16x32_bf16 v[60:63], v[194:197], v[236:239], v[60:63]
	v_mfma_f32_16x16x32_bf16 v[64:67], v[144:147], v[244:247], v[64:67]
	v_mfma_f32_16x16x32_bf16 v[68:71], v[194:197], v[244:247], v[68:71]
	v_mfma_f32_16x16x32_bf16 v[108:111], v[174:177], v[220:223], v[108:111]
	v_mfma_f32_16x16x32_bf16 v[112:115], v[198:201], v[220:223], v[112:115]
	v_mfma_f32_16x16x32_bf16 v[116:119], v[174:177], v[232:235], v[116:119]
	v_mfma_f32_16x16x32_bf16 v[52:55], v[198:201], v[232:235], v[52:55]
	v_mfma_f32_16x16x32_bf16 v[56:59], v[174:177], v[240:243], v[56:59]
	v_mfma_f32_16x16x32_bf16 v[60:63], v[198:201], v[240:243], v[60:63]
	v_mfma_f32_16x16x32_bf16 v[64:67], v[174:177], v[248:251], v[64:67]
	v_mfma_f32_16x16x32_bf16 v[68:71], v[198:201], v[248:251], v[68:71]
	s_barrier
	s_mov_b64 s[68:69], 0x280
	s_mov_b32 m0, s67
	v_lshl_add_u64 v[8:9], v[8:9], 0, s[68:69]
	s_add_u32 s52, s52, 0x18280
	ds_read_b128 v[202:205], v17 offset:49152
	ds_read_b128 v[220:223], v17 offset:50176
	ds_read_b128 v[228:231], v17 offset:51200
	ds_read_b128 v[232:235], v17 offset:52224
	ds_read_b128 v[236:239], v17 offset:53248
	ds_read_b128 v[240:243], v17 offset:54272
	ds_read_b128 v[244:247], v17 offset:55296
	ds_read_b128 v[248:251], v17 offset:56320
	global_load_lds_dwordx4 v[8:9], off
	v_lshl_add_u64 v[8:9], v[10:11], 0, s[68:69]
	s_mov_b32 m0, s63
	s_addc_u32 s53, s53, 0
	global_load_lds_dwordx4 v[8:9], off
	v_lshl_add_u64 v[8:9], s[52:53], 0, v[4:5]
	s_mov_b32 m0, s64
	s_nop 0
	global_load_lds_dwordx4 v[8:9], off
	v_lshl_add_u64 v[8:9], s[52:53], 0, v[0:1]
	s_mov_b32 m0, s66
	s_nop 0
	global_load_lds_dwordx4 v[8:9], off
	v_lshl_add_u64 v[8:9], v[12:13], 0, s[68:69]
	s_mov_b32 m0, s30
	s_nop 0
	global_load_lds_dwordx4 v[8:9], off
	v_lshl_add_u64 v[8:9], v[14:15], 0, s[68:69]
	s_mov_b32 m0, s31
	s_nop 0
	global_load_lds_dwordx4 v[8:9], off
	s_waitcnt vmcnt(8)
	s_waitcnt lgkmcnt(0)
	s_barrier
	v_mfma_f32_16x16x32_bf16 v[8:11], v[128:131], v[202:205], v[150:153]
	v_mfma_f32_16x16x32_bf16 v[12:15], v[136:139], v[202:205], v[154:157]
	v_mfma_f32_16x16x32_bf16 v[148:151], v[128:131], v[228:231], v[178:181]
	v_mfma_f32_16x16x32_bf16 v[152:155], v[136:139], v[228:231], v[182:185]
	v_mfma_f32_16x16x32_bf16 v[156:159], v[128:131], v[236:239], v[186:189]
	v_mfma_f32_16x16x32_bf16 v[178:181], v[136:139], v[236:239], v[190:193]
	v_mfma_f32_16x16x32_bf16 v[24:27], v[128:131], v[244:247], v[24:27]
	v_mfma_f32_16x16x32_bf16 v[28:31], v[136:139], v[244:247], v[28:31]
	v_mfma_f32_16x16x32_bf16 v[8:11], v[132:135], v[220:223], v[8:11]
	v_mfma_f32_16x16x32_bf16 v[12:15], v[140:143], v[220:223], v[12:15]
	v_mfma_f32_16x16x32_bf16 v[148:151], v[132:135], v[232:235], v[148:151]
	v_mfma_f32_16x16x32_bf16 v[152:155], v[140:143], v[232:235], v[152:155]
	v_mfma_f32_16x16x32_bf16 v[156:159], v[132:135], v[240:243], v[156:159]
	v_mfma_f32_16x16x32_bf16 v[178:181], v[140:143], v[240:243], v[178:181]
	v_mfma_f32_16x16x32_bf16 v[24:27], v[132:135], v[248:251], v[24:27]
	v_mfma_f32_16x16x32_bf16 v[28:31], v[140:143], v[248:251], v[28:31]
	v_mfma_f32_16x16x32_bf16 v[32:35], v[144:147], v[202:205], v[32:35]
	v_mfma_f32_16x16x32_bf16 v[44:47], v[194:197], v[202:205], v[44:47]
	v_mfma_f32_16x16x32_bf16 v[48:51], v[144:147], v[228:231], v[48:51]
	v_mfma_f32_16x16x32_bf16 v[72:75], v[194:197], v[228:231], v[72:75]
	v_mfma_f32_16x16x32_bf16 v[120:123], v[144:147], v[236:239], v[120:123]
	v_mfma_f32_16x16x32_bf16 v[124:127], v[194:197], v[236:239], v[124:127]
	v_mfma_f32_16x16x32_bf16 v[36:39], v[144:147], v[244:247], v[36:39]
	v_mfma_f32_16x16x32_bf16 v[40:43], v[194:197], v[244:247], v[40:43]
	v_mfma_f32_16x16x32_bf16 v[32:35], v[174:177], v[220:223], v[32:35]
	v_mfma_f32_16x16x32_bf16 v[44:47], v[198:201], v[220:223], v[44:47]
	v_mfma_f32_16x16x32_bf16 v[48:51], v[174:177], v[232:235], v[48:51]
	v_mfma_f32_16x16x32_bf16 v[72:75], v[198:201], v[232:235], v[72:75]
	v_mfma_f32_16x16x32_bf16 v[120:123], v[174:177], v[240:243], v[120:123]
	v_mfma_f32_16x16x32_bf16 v[124:127], v[198:201], v[240:243], v[124:127]
	v_mfma_f32_16x16x32_bf16 v[36:39], v[174:177], v[248:251], v[36:39]
	v_mfma_f32_16x16x32_bf16 v[40:43], v[198:201], v[248:251], v[40:43]
	s_barrier
	ds_read_b128 v[128:131], v19
	ds_read_b128 v[132:135], v19 offset:1024
	ds_read_b128 v[136:139], v19 offset:2048
	ds_read_b128 v[140:143], v19 offset:3072
	ds_read_b128 v[144:147], v20
	ds_read_b128 v[174:177], v20 offset:1024
	ds_read_b128 v[182:185], v20 offset:2048
	ds_read_b128 v[186:189], v20 offset:3072
	s_add_u32 s50, s50, 0x18280
	s_addc_u32 s51, s51, 0
	s_mov_b32 m0, s65
	v_lshl_add_u64 v[240:241], s[50:51], 0, v[6:7]
	ds_read_b128 v[190:193], v17
	ds_read_b128 v[194:197], v17 offset:1024
	ds_read_b128 v[198:201], v17 offset:2048
	ds_read_b128 v[202:205], v17 offset:3072
	ds_read_b128 v[220:223], v17 offset:4096
	ds_read_b128 v[228:231], v17 offset:5120
	ds_read_b128 v[232:235], v17 offset:6144
	ds_read_b128 v[236:239], v17 offset:7168
	global_load_lds_dwordx4 v[240:241], off
	v_lshl_add_u64 v[240:241], s[50:51], 0, v[2:3]
	s_mov_b32 m0, s57
	s_nop 0
	global_load_lds_dwordx4 v[240:241], off
	s_waitcnt vmcnt(8)
	s_waitcnt lgkmcnt(0)
	s_barrier
	v_mfma_f32_16x16x32_bf16 v[76:79], v[128:131], v[190:193], v[76:79]
	v_mfma_f32_16x16x32_bf16 v[80:83], v[136:139], v[190:193], v[80:83]
	v_mfma_f32_16x16x32_bf16 v[84:87], v[128:131], v[198:201], v[84:87]
	v_mfma_f32_16x16x32_bf16 v[88:91], v[136:139], v[198:201], v[88:91]
	v_mfma_f32_16x16x32_bf16 v[92:95], v[128:131], v[220:223], v[92:95]
	v_mfma_f32_16x16x32_bf16 v[96:99], v[136:139], v[220:223], v[96:99]
	v_mfma_f32_16x16x32_bf16 v[100:103], v[128:131], v[232:235], v[100:103]
	v_mfma_f32_16x16x32_bf16 v[104:107], v[136:139], v[232:235], v[104:107]
	v_mfma_f32_16x16x32_bf16 v[76:79], v[132:135], v[194:197], v[76:79]
	v_mfma_f32_16x16x32_bf16 v[80:83], v[140:143], v[194:197], v[80:83]
	v_mfma_f32_16x16x32_bf16 v[84:87], v[132:135], v[202:205], v[84:87]
	v_mfma_f32_16x16x32_bf16 v[88:91], v[140:143], v[202:205], v[88:91]
	v_mfma_f32_16x16x32_bf16 v[92:95], v[132:135], v[228:231], v[92:95]
	v_mfma_f32_16x16x32_bf16 v[96:99], v[140:143], v[228:231], v[96:99]
	v_mfma_f32_16x16x32_bf16 v[100:103], v[132:135], v[236:239], v[100:103]
	v_mfma_f32_16x16x32_bf16 v[104:107], v[140:143], v[236:239], v[104:107]
	v_mfma_f32_16x16x32_bf16 v[108:111], v[144:147], v[190:193], v[108:111]
	v_mfma_f32_16x16x32_bf16 v[112:115], v[182:185], v[190:193], v[112:115]
	v_mfma_f32_16x16x32_bf16 v[116:119], v[144:147], v[198:201], v[116:119]
	v_mfma_f32_16x16x32_bf16 v[52:55], v[182:185], v[198:201], v[52:55]
	v_mfma_f32_16x16x32_bf16 v[56:59], v[144:147], v[220:223], v[56:59]
	v_mfma_f32_16x16x32_bf16 v[60:63], v[182:185], v[220:223], v[60:63]
	v_mfma_f32_16x16x32_bf16 v[64:67], v[144:147], v[232:235], v[64:67]
	v_mfma_f32_16x16x32_bf16 v[68:71], v[182:185], v[232:235], v[68:71]
	v_mfma_f32_16x16x32_bf16 v[108:111], v[174:177], v[194:197], v[108:111]
	v_mfma_f32_16x16x32_bf16 v[112:115], v[186:189], v[194:197], v[112:115]
	v_mfma_f32_16x16x32_bf16 v[116:119], v[174:177], v[202:205], v[116:119]
	v_mfma_f32_16x16x32_bf16 v[52:55], v[186:189], v[202:205], v[52:55]
	v_mfma_f32_16x16x32_bf16 v[56:59], v[174:177], v[228:231], v[56:59]
	v_mfma_f32_16x16x32_bf16 v[60:63], v[186:189], v[228:231], v[60:63]
	v_mfma_f32_16x16x32_bf16 v[64:67], v[174:177], v[236:239], v[64:67]
	v_mfma_f32_16x16x32_bf16 v[68:71], v[186:189], v[236:239], v[68:71]
	s_barrier
	s_mov_b32 m0, s62
	v_lshl_add_u64 v[240:241], s[44:45], 0, v[4:5]
	s_add_u32 s50, s44, 0x18000
	ds_read_b128 v[190:193], v17 offset:16384
	ds_read_b128 v[194:197], v17 offset:17408
	ds_read_b128 v[198:201], v17 offset:18432
	ds_read_b128 v[202:205], v17 offset:19456
	ds_read_b128 v[220:223], v17 offset:20480
	ds_read_b128 v[228:231], v17 offset:21504
	ds_read_b128 v[232:235], v17 offset:22528
	ds_read_b128 v[236:239], v17 offset:23552
	global_load_lds_dwordx4 v[240:241], off
	v_lshl_add_u64 v[242:243], s[44:45], 0, v[0:1]
	s_mov_b32 m0, s58
	s_addc_u32 s51, s45, 0
	global_load_lds_dwordx4 v[242:243], off
	v_lshl_add_u64 v[244:245], s[50:51], 0, v[4:5]
	s_mov_b32 m0, s59
	v_lshl_add_u64 v[246:247], s[42:43], 0, v[2:3]
	global_load_lds_dwordx4 v[244:245], off
	v_lshl_add_u64 v[244:245], s[50:51], 0, v[0:1]
	s_mov_b32 m0, s61
	s_nop 0
	global_load_lds_dwordx4 v[244:245], off
	v_lshl_add_u64 v[244:245], s[42:43], 0, v[6:7]
	s_mov_b32 m0, s26
	s_nop 0
	global_load_lds_dwordx4 v[244:245], off
	s_mov_b32 m0, s27
	s_nop 0
	global_load_lds_dwordx4 v[246:247], off
	s_waitcnt vmcnt(8)
	s_waitcnt lgkmcnt(0)
	s_barrier
	v_mfma_f32_16x16x32_bf16 v[8:11], v[128:131], v[190:193], v[8:11]
	v_mfma_f32_16x16x32_bf16 v[12:15], v[136:139], v[190:193], v[12:15]
	v_mfma_f32_16x16x32_bf16 v[148:151], v[128:131], v[198:201], v[148:151]
	v_mfma_f32_16x16x32_bf16 v[152:155], v[136:139], v[198:201], v[152:155]
	v_mfma_f32_16x16x32_bf16 v[156:159], v[128:131], v[220:223], v[156:159]
	v_mfma_f32_16x16x32_bf16 v[178:181], v[136:139], v[220:223], v[178:181]
	v_mfma_f32_16x16x32_bf16 v[24:27], v[128:131], v[232:235], v[24:27]
	v_mfma_f32_16x16x32_bf16 v[28:31], v[136:139], v[232:235], v[28:31]
	v_mfma_f32_16x16x32_bf16 v[8:11], v[132:135], v[194:197], v[8:11]
	v_mfma_f32_16x16x32_bf16 v[12:15], v[140:143], v[194:197], v[12:15]
	v_mfma_f32_16x16x32_bf16 v[148:151], v[132:135], v[202:205], v[148:151]
	v_mfma_f32_16x16x32_bf16 v[152:155], v[140:143], v[202:205], v[152:155]
	v_mfma_f32_16x16x32_bf16 v[156:159], v[132:135], v[228:231], v[156:159]
	v_mfma_f32_16x16x32_bf16 v[178:181], v[140:143], v[228:231], v[178:181]
	v_mfma_f32_16x16x32_bf16 v[24:27], v[132:135], v[236:239], v[24:27]
	v_mfma_f32_16x16x32_bf16 v[28:31], v[140:143], v[236:239], v[28:31]
	v_mfma_f32_16x16x32_bf16 v[32:35], v[144:147], v[190:193], v[32:35]
	v_mfma_f32_16x16x32_bf16 v[44:47], v[182:185], v[190:193], v[44:47]
	v_mfma_f32_16x16x32_bf16 v[48:51], v[144:147], v[198:201], v[48:51]
	v_mfma_f32_16x16x32_bf16 v[72:75], v[182:185], v[198:201], v[72:75]
	v_mfma_f32_16x16x32_bf16 v[120:123], v[144:147], v[220:223], v[120:123]
	v_mfma_f32_16x16x32_bf16 v[124:127], v[182:185], v[220:223], v[124:127]
	v_mfma_f32_16x16x32_bf16 v[36:39], v[144:147], v[232:235], v[36:39]
	v_mfma_f32_16x16x32_bf16 v[40:43], v[182:185], v[232:235], v[40:43]
	v_mfma_f32_16x16x32_bf16 v[32:35], v[174:177], v[194:197], v[32:35]
	v_mfma_f32_16x16x32_bf16 v[44:47], v[186:189], v[194:197], v[44:47]
	v_mfma_f32_16x16x32_bf16 v[48:51], v[174:177], v[202:205], v[48:51]
	v_mfma_f32_16x16x32_bf16 v[72:75], v[186:189], v[202:205], v[72:75]
	v_mfma_f32_16x16x32_bf16 v[120:123], v[174:177], v[228:231], v[120:123]
	v_mfma_f32_16x16x32_bf16 v[124:127], v[186:189], v[228:231], v[124:127]
	v_mfma_f32_16x16x32_bf16 v[36:39], v[174:177], v[236:239], v[36:39]
	v_mfma_f32_16x16x32_bf16 v[40:43], v[186:189], v[236:239], v[40:43]
	s_barrier
	ds_read_b128 v[128:131], v21
	ds_read_b128 v[132:135], v21 offset:1024
	ds_read_b128 v[136:139], v21 offset:2048
	ds_read_b128 v[140:143], v21 offset:3072
	ds_read_b128 v[144:147], v22
	ds_read_b128 v[174:177], v22 offset:1024
	ds_read_b128 v[182:185], v22 offset:2048
	ds_read_b128 v[20:23], v22 offset:3072
	s_add_u32 s50, s42, 0x18000
	s_addc_u32 s51, s43, 0
	s_mov_b32 m0, s28
	v_lshl_add_u64 v[236:237], s[50:51], 0, v[6:7]
	ds_read_b128 v[186:189], v17 offset:32768
	ds_read_b128 v[190:193], v17 offset:33792
	ds_read_b128 v[194:197], v17 offset:34816
	ds_read_b128 v[198:201], v17 offset:35840
	ds_read_b128 v[202:205], v17 offset:36864
	ds_read_b128 v[220:223], v17 offset:37888
	ds_read_b128 v[228:231], v17 offset:38912
	ds_read_b128 v[232:235], v17 offset:39936
	global_load_lds_dwordx4 v[236:237], off
	v_lshl_add_u64 v[236:237], s[50:51], 0, v[2:3]
	s_mov_b32 m0, s29
	s_nop 0
	global_load_lds_dwordx4 v[236:237], off
	s_waitcnt vmcnt(8)
	s_waitcnt lgkmcnt(0)
	s_barrier
	v_mfma_f32_16x16x32_bf16 v[76:79], v[128:131], v[186:189], v[76:79]
	v_mfma_f32_16x16x32_bf16 v[80:83], v[136:139], v[186:189], v[80:83]
	v_mfma_f32_16x16x32_bf16 v[84:87], v[128:131], v[194:197], v[84:87]
	v_mfma_f32_16x16x32_bf16 v[88:91], v[136:139], v[194:197], v[88:91]
	v_mfma_f32_16x16x32_bf16 v[92:95], v[128:131], v[202:205], v[92:95]
	v_mfma_f32_16x16x32_bf16 v[96:99], v[136:139], v[202:205], v[96:99]
	v_mfma_f32_16x16x32_bf16 v[100:103], v[128:131], v[228:231], v[100:103]
	v_mfma_f32_16x16x32_bf16 v[104:107], v[136:139], v[228:231], v[104:107]
	v_mfma_f32_16x16x32_bf16 v[76:79], v[132:135], v[190:193], v[76:79]
	v_mfma_f32_16x16x32_bf16 v[80:83], v[140:143], v[190:193], v[80:83]
	v_mfma_f32_16x16x32_bf16 v[84:87], v[132:135], v[198:201], v[84:87]
	v_mfma_f32_16x16x32_bf16 v[88:91], v[140:143], v[198:201], v[88:91]
	v_mfma_f32_16x16x32_bf16 v[92:95], v[132:135], v[220:223], v[92:95]
	v_mfma_f32_16x16x32_bf16 v[96:99], v[140:143], v[220:223], v[96:99]
	v_mfma_f32_16x16x32_bf16 v[100:103], v[132:135], v[232:235], v[100:103]
	v_mfma_f32_16x16x32_bf16 v[104:107], v[140:143], v[232:235], v[104:107]
	v_mfma_f32_16x16x32_bf16 v[108:111], v[144:147], v[186:189], v[108:111]
	v_mfma_f32_16x16x32_bf16 v[112:115], v[182:185], v[186:189], v[112:115]
	v_mfma_f32_16x16x32_bf16 v[116:119], v[144:147], v[194:197], v[116:119]
	v_mfma_f32_16x16x32_bf16 v[52:55], v[182:185], v[194:197], v[52:55]
	v_mfma_f32_16x16x32_bf16 v[56:59], v[144:147], v[202:205], v[56:59]
	v_mfma_f32_16x16x32_bf16 v[60:63], v[182:185], v[202:205], v[60:63]
	v_mfma_f32_16x16x32_bf16 v[64:67], v[144:147], v[228:231], v[64:67]
	v_mfma_f32_16x16x32_bf16 v[68:71], v[182:185], v[228:231], v[68:71]
	v_mfma_f32_16x16x32_bf16 v[108:111], v[174:177], v[190:193], v[108:111]
	v_mfma_f32_16x16x32_bf16 v[112:115], v[20:23], v[190:193], v[112:115]
	v_mfma_f32_16x16x32_bf16 v[116:119], v[174:177], v[198:201], v[116:119]
	v_mfma_f32_16x16x32_bf16 v[52:55], v[20:23], v[198:201], v[52:55]
	v_mfma_f32_16x16x32_bf16 v[56:59], v[174:177], v[220:223], v[56:59]
	v_mfma_f32_16x16x32_bf16 v[60:63], v[20:23], v[220:223], v[60:63]
	v_mfma_f32_16x16x32_bf16 v[64:67], v[174:177], v[232:235], v[64:67]
	v_mfma_f32_16x16x32_bf16 v[68:71], v[20:23], v[232:235], v[68:71]
	s_barrier
	s_mov_b32 m0, s67
	v_lshl_add_u64 v[236:237], v[240:241], 0, s[4:5]
	s_add_u32 s50, s44, 0x18080
	ds_read_b128 v[186:189], v17 offset:49152
	ds_read_b128 v[190:193], v17 offset:50176
	ds_read_b128 v[194:197], v17 offset:51200
	ds_read_b128 v[198:201], v17 offset:52224
	ds_read_b128 v[202:205], v17 offset:53248
	ds_read_b128 v[220:223], v17 offset:54272
	ds_read_b128 v[228:231], v17 offset:55296
	ds_read_b128 v[232:235], v17 offset:56320
	global_load_lds_dwordx4 v[236:237], off
	v_lshl_add_u64 v[236:237], v[242:243], 0, s[4:5]
	s_mov_b32 m0, s63
	s_addc_u32 s51, s45, 0
	global_load_lds_dwordx4 v[236:237], off
	v_lshl_add_u64 v[236:237], s[50:51], 0, v[4:5]
	s_mov_b32 m0, s64
	s_nop 0
	global_load_lds_dwordx4 v[236:237], off
	v_lshl_add_u64 v[236:237], s[50:51], 0, v[0:1]
	s_mov_b32 m0, s66
	s_nop 0
	global_load_lds_dwordx4 v[236:237], off
	v_lshl_add_u64 v[236:237], v[244:245], 0, s[4:5]
	s_mov_b32 m0, s30
	s_nop 0
	global_load_lds_dwordx4 v[236:237], off
	v_lshl_add_u64 v[236:237], v[246:247], 0, s[4:5]
	s_mov_b32 m0, s31
	s_nop 0
	global_load_lds_dwordx4 v[236:237], off
	s_waitcnt vmcnt(8)
	s_waitcnt lgkmcnt(0)
	s_barrier
	v_mfma_f32_16x16x32_bf16 v[8:11], v[128:131], v[186:189], v[8:11]
	v_mfma_f32_16x16x32_bf16 v[12:15], v[136:139], v[186:189], v[12:15]
	v_mfma_f32_16x16x32_bf16 v[148:151], v[128:131], v[194:197], v[148:151]
	v_mfma_f32_16x16x32_bf16 v[152:155], v[136:139], v[194:197], v[152:155]
	v_mfma_f32_16x16x32_bf16 v[156:159], v[128:131], v[202:205], v[156:159]
	v_mfma_f32_16x16x32_bf16 v[178:181], v[136:139], v[202:205], v[178:181]
	v_mfma_f32_16x16x32_bf16 v[24:27], v[128:131], v[228:231], v[24:27]
	v_mfma_f32_16x16x32_bf16 v[28:31], v[136:139], v[228:231], v[28:31]
	v_mfma_f32_16x16x32_bf16 v[8:11], v[132:135], v[190:193], v[8:11]
	v_mfma_f32_16x16x32_bf16 v[12:15], v[140:143], v[190:193], v[12:15]
	v_mfma_f32_16x16x32_bf16 v[148:151], v[132:135], v[198:201], v[148:151]
	v_mfma_f32_16x16x32_bf16 v[152:155], v[140:143], v[198:201], v[152:155]
	v_mfma_f32_16x16x32_bf16 v[156:159], v[132:135], v[220:223], v[156:159]
	v_mfma_f32_16x16x32_bf16 v[178:181], v[140:143], v[220:223], v[178:181]
	v_mfma_f32_16x16x32_bf16 v[24:27], v[132:135], v[232:235], v[24:27]
	v_mfma_f32_16x16x32_bf16 v[28:31], v[140:143], v[232:235], v[28:31]
	v_mfma_f32_16x16x32_bf16 v[32:35], v[144:147], v[186:189], v[32:35]
	v_mfma_f32_16x16x32_bf16 v[44:47], v[182:185], v[186:189], v[44:47]
	v_mfma_f32_16x16x32_bf16 v[48:51], v[144:147], v[194:197], v[48:51]
	v_mfma_f32_16x16x32_bf16 v[72:75], v[182:185], v[194:197], v[72:75]
	v_mfma_f32_16x16x32_bf16 v[120:123], v[144:147], v[202:205], v[120:123]
	v_mfma_f32_16x16x32_bf16 v[124:127], v[182:185], v[202:205], v[124:127]
	v_mfma_f32_16x16x32_bf16 v[36:39], v[144:147], v[228:231], v[36:39]
	v_mfma_f32_16x16x32_bf16 v[40:43], v[182:185], v[228:231], v[40:43]
	v_mfma_f32_16x16x32_bf16 v[32:35], v[174:177], v[190:193], v[32:35]
	v_mfma_f32_16x16x32_bf16 v[44:47], v[20:23], v[190:193], v[44:47]
	v_mfma_f32_16x16x32_bf16 v[48:51], v[174:177], v[198:201], v[48:51]
	v_mfma_f32_16x16x32_bf16 v[72:75], v[20:23], v[198:201], v[72:75]
	v_mfma_f32_16x16x32_bf16 v[120:123], v[174:177], v[220:223], v[120:123]
	v_mfma_f32_16x16x32_bf16 v[124:127], v[20:23], v[220:223], v[124:127]
	v_mfma_f32_16x16x32_bf16 v[36:39], v[174:177], v[232:235], v[36:39]
	v_mfma_f32_16x16x32_bf16 v[20:23], v[20:23], v[232:235], v[40:43]
	s_barrier
	s_lshl_b32 s50, s55, 8
	s_lshl_b32 s51, s56, 19
	s_add_i32 s50, s50, s51
	v_add_u32_e32 v162, s50, v18
	v_lshl_add_u64 v[128:129], v[162:163], 1, s[46:47]
	v_cvt_pk_bf16_f32 v40, v76, v77
	v_cvt_pk_bf16_f32 v41, v78, v79
	v_cvt_pk_bf16_f32 v42, v80, v81
	v_cvt_pk_bf16_f32 v43, v82, v83
	global_store_dwordx4 v[128:129], v[40:43], off
	v_cvt_pk_bf16_f32 v8, v8, v9
	v_cvt_pk_bf16_f32 v9, v10, v11
	v_cvt_pk_bf16_f32 v40, v108, v109
	v_cvt_pk_bf16_f32 v41, v110, v111
	v_cvt_pk_bf16_f32 v42, v112, v113
	v_cvt_pk_bf16_f32 v43, v114, v115
	global_store_dwordx4 v[128:129], v[40:43], off offset:256
	v_cvt_pk_bf16_f32 v10, v12, v13
	v_cvt_pk_bf16_f32 v11, v14, v15
	v_add_u32_e32 v40, 0x8000, v162
	v_mov_b32_e32 v41, v163
	v_lshl_add_u64 v[76:77], v[40:41], 1, s[46:47]
	v_cvt_pk_bf16_f32 v40, v84, v85
	v_cvt_pk_bf16_f32 v41, v86, v87
	v_cvt_pk_bf16_f32 v42, v88, v89
	v_cvt_pk_bf16_f32 v43, v90, v91
	global_store_dwordx4 v[76:77], v[40:43], off
	s_add_i32 s54, s54, s82
	s_andn2_b64 vcc, exec, s[40:41]
	v_cvt_pk_bf16_f32 v40, v116, v117
	v_cvt_pk_bf16_f32 v41, v118, v119
	v_cvt_pk_bf16_f32 v42, v52, v53
	v_cvt_pk_bf16_f32 v43, v54, v55
	global_store_dwordx4 v[76:77], v[40:43], off offset:256
	s_mov_b32 s55, s6
	s_mov_b32 s56, s7
	v_add_u32_e32 v40, 0x10000, v162
	v_mov_b32_e32 v41, v163
	v_lshl_add_u64 v[52:53], v[40:41], 1, s[46:47]
	v_cvt_pk_bf16_f32 v40, v92, v93
	v_cvt_pk_bf16_f32 v41, v94, v95
	v_cvt_pk_bf16_f32 v42, v96, v97
	v_cvt_pk_bf16_f32 v43, v98, v99
	global_store_dwordx4 v[52:53], v[40:43], off
	s_mov_b64 s[52:53], s[44:45]
	s_mov_b64 s[50:51], s[42:43]
	v_cvt_pk_bf16_f32 v40, v56, v57
	v_cvt_pk_bf16_f32 v41, v58, v59
	v_cvt_pk_bf16_f32 v42, v60, v61
	v_cvt_pk_bf16_f32 v43, v62, v63
	global_store_dwordx4 v[52:53], v[40:43], off offset:256
	s_nop 1
	v_add_u32_e32 v40, 0x18000, v162
	v_mov_b32_e32 v41, v163
	v_lshl_add_u64 v[52:53], v[40:41], 1, s[46:47]
	v_cvt_pk_bf16_f32 v40, v100, v101
	v_cvt_pk_bf16_f32 v41, v102, v103
	v_cvt_pk_bf16_f32 v42, v104, v105
	v_cvt_pk_bf16_f32 v43, v106, v107
	global_store_dwordx4 v[52:53], v[40:43], off
	s_nop 1
	v_cvt_pk_bf16_f32 v40, v64, v65
	v_cvt_pk_bf16_f32 v41, v66, v67
	v_cvt_pk_bf16_f32 v42, v68, v69
	v_cvt_pk_bf16_f32 v43, v70, v71
	global_store_dwordx4 v[52:53], v[40:43], off offset:256
	s_nop 1
	v_add_u32_e32 v40, 0x40000, v162
	v_mov_b32_e32 v41, v163
	v_lshl_add_u64 v[40:41], v[40:41], 1, s[46:47]
	global_store_dwordx4 v[40:41], v[8:11], off
	s_nop 1
	v_cvt_pk_bf16_f32 v8, v32, v33
	v_cvt_pk_bf16_f32 v9, v34, v35
	v_cvt_pk_bf16_f32 v10, v44, v45
	v_cvt_pk_bf16_f32 v11, v46, v47
	global_store_dwordx4 v[40:41], v[8:11], off offset:256
	s_nop 1
	v_add_u32_e32 v8, 0x48000, v162
	v_mov_b32_e32 v9, v163
	v_lshl_add_u64 v[12:13], v[8:9], 1, s[46:47]
	v_cvt_pk_bf16_f32 v8, v148, v149
	v_cvt_pk_bf16_f32 v9, v150, v151
	v_cvt_pk_bf16_f32 v10, v152, v153
	v_cvt_pk_bf16_f32 v11, v154, v155
	global_store_dwordx4 v[12:13], v[8:11], off
	s_nop 1
	v_cvt_pk_bf16_f32 v8, v48, v49
	v_cvt_pk_bf16_f32 v9, v50, v51
	v_cvt_pk_bf16_f32 v10, v72, v73
	v_cvt_pk_bf16_f32 v11, v74, v75
	global_store_dwordx4 v[12:13], v[8:11], off offset:256
	s_nop 1
	v_add_u32_e32 v8, 0x50000, v162
	v_mov_b32_e32 v9, v163
	v_lshl_add_u64 v[12:13], v[8:9], 1, s[46:47]
	v_cvt_pk_bf16_f32 v8, v156, v157
	v_cvt_pk_bf16_f32 v9, v158, v159
	v_cvt_pk_bf16_f32 v10, v178, v179
	v_cvt_pk_bf16_f32 v11, v180, v181
	global_store_dwordx4 v[12:13], v[8:11], off
	v_add_u32_e32 v162, 0x58000, v162
	s_nop 0
	v_cvt_pk_bf16_f32 v8, v120, v121
	v_cvt_pk_bf16_f32 v9, v122, v123
	v_cvt_pk_bf16_f32 v10, v124, v125
	v_cvt_pk_bf16_f32 v11, v126, v127
	global_store_dwordx4 v[12:13], v[8:11], off offset:256
	v_lshl_add_u64 v[12:13], v[162:163], 1, s[46:47]
	s_nop 0
	v_cvt_pk_bf16_f32 v8, v24, v25
	v_cvt_pk_bf16_f32 v9, v26, v27
	v_cvt_pk_bf16_f32 v10, v28, v29
	v_cvt_pk_bf16_f32 v11, v30, v31
	global_store_dwordx4 v[12:13], v[8:11], off
	s_nop 1
	v_cvt_pk_bf16_f32 v8, v36, v37
	v_cvt_pk_bf16_f32 v9, v38, v39
	v_cvt_pk_bf16_f32 v10, v20, v21
	v_cvt_pk_bf16_f32 v11, v22, v23
	global_store_dwordx4 v[12:13], v[8:11], off offset:256
	s_cbranch_vccz .LBB0_513

.LBB0_771:
	s_add_u32 s55, s60, 0xfffc0080
	s_addc_u32 s62, s61, -1
	s_add_i32 s72, 0, 0x10000
	s_cmp_eq_u32 s53, 12
	s_cselect_b32 s65, s6, s62
	s_cselect_b32 s64, s7, s55
	s_cselect_b32 s63, s28, s31
	s_cselect_b32 s62, s29, s30
	s_add_i32 s55, 0, 0x14000
	v_add_u32_e32 v156, s72, v145
	v_add_u32_e32 v162, s55, v145
	ds_read_b128 v[140:143], v156
	ds_read_b128 v[148:151], v156 offset:1024
	ds_read_b128 v[152:155], v156 offset:2048
	ds_read_b128 v[156:159], v156 offset:3072
	ds_read_b128 v[174:177], v162
	ds_read_b128 v[178:181], v162 offset:1024
	ds_read_b128 v[182:185], v162 offset:2048
	ds_read_b128 v[186:189], v162 offset:3072
	v_lshl_add_u64 v[240:241], s[60:61], 0, v[136:137]
	s_add_i32 m0, s25, 0xc000
	ds_read_b128 v[190:193], v147
	ds_read_b128 v[194:197], v147 offset:1024
	ds_read_b128 v[198:201], v147 offset:2048
	ds_read_b128 v[202:205], v147 offset:3072
	ds_read_b128 v[220:223], v147 offset:4096
	ds_read_b128 v[228:231], v147 offset:5120
	ds_read_b128 v[232:235], v147 offset:6144
	ds_read_b128 v[236:239], v147 offset:7168
	global_load_lds_dwordx4 v[240:241], off
	v_lshl_add_u64 v[240:241], s[60:61], 0, v[138:139]
	s_add_i32 m0, s25, 0xe000
	s_nop 0
	global_load_lds_dwordx4 v[240:241], off
	s_waitcnt vmcnt(8)
	s_waitcnt lgkmcnt(0)
	s_barrier
	v_mfma_f32_16x16x32_bf16 v[124:127], v[140:143], v[190:193], v[124:127]
	v_mfma_f32_16x16x32_bf16 v[120:123], v[152:155], v[190:193], v[120:123]
	v_mfma_f32_16x16x32_bf16 v[108:111], v[140:143], v[198:201], v[108:111]
	v_mfma_f32_16x16x32_bf16 v[104:107], v[152:155], v[198:201], v[104:107]
	v_mfma_f32_16x16x32_bf16 v[92:95], v[140:143], v[220:223], v[92:95]
	v_mfma_f32_16x16x32_bf16 v[88:91], v[152:155], v[220:223], v[88:91]
	v_mfma_f32_16x16x32_bf16 v[76:79], v[140:143], v[232:235], v[76:79]
	v_mfma_f32_16x16x32_bf16 v[72:75], v[152:155], v[232:235], v[72:75]
	v_mfma_f32_16x16x32_bf16 v[124:127], v[148:151], v[194:197], v[124:127]
	v_mfma_f32_16x16x32_bf16 v[120:123], v[156:159], v[194:197], v[120:123]
	v_mfma_f32_16x16x32_bf16 v[108:111], v[148:151], v[202:205], v[108:111]
	v_mfma_f32_16x16x32_bf16 v[104:107], v[156:159], v[202:205], v[104:107]
	v_mfma_f32_16x16x32_bf16 v[92:95], v[148:151], v[228:231], v[92:95]
	v_mfma_f32_16x16x32_bf16 v[88:91], v[156:159], v[228:231], v[88:91]
	v_mfma_f32_16x16x32_bf16 v[76:79], v[148:151], v[236:239], v[76:79]
	v_mfma_f32_16x16x32_bf16 v[72:75], v[156:159], v[236:239], v[72:75]
	v_mfma_f32_16x16x32_bf16 v[116:119], v[174:177], v[190:193], v[116:119]
	v_mfma_f32_16x16x32_bf16 v[112:115], v[182:185], v[190:193], v[112:115]
	v_mfma_f32_16x16x32_bf16 v[100:103], v[174:177], v[198:201], v[100:103]
	v_mfma_f32_16x16x32_bf16 v[96:99], v[182:185], v[198:201], v[96:99]
	v_mfma_f32_16x16x32_bf16 v[84:87], v[174:177], v[220:223], v[84:87]
	v_mfma_f32_16x16x32_bf16 v[80:83], v[182:185], v[220:223], v[80:83]
	v_mfma_f32_16x16x32_bf16 v[68:71], v[174:177], v[232:235], v[68:71]
	v_mfma_f32_16x16x32_bf16 v[64:67], v[182:185], v[232:235], v[64:67]
	v_mfma_f32_16x16x32_bf16 v[116:119], v[178:181], v[194:197], v[116:119]
	v_mfma_f32_16x16x32_bf16 v[112:115], v[186:189], v[194:197], v[112:115]
	v_mfma_f32_16x16x32_bf16 v[100:103], v[178:181], v[202:205], v[100:103]
	v_mfma_f32_16x16x32_bf16 v[96:99], v[186:189], v[202:205], v[96:99]
	v_mfma_f32_16x16x32_bf16 v[84:87], v[178:181], v[228:231], v[84:87]
	v_mfma_f32_16x16x32_bf16 v[80:83], v[186:189], v[228:231], v[80:83]
	v_mfma_f32_16x16x32_bf16 v[68:71], v[178:181], v[236:239], v[68:71]
	v_mfma_f32_16x16x32_bf16 v[64:67], v[186:189], v[236:239], v[64:67]
	s_barrier
	s_add_i32 s72, s72, s24
	v_lshl_add_u64 v[240:241], s[62:63], 0, v[132:133]
	s_mov_b32 m0, s72
	ds_read_b128 v[190:193], v147 offset:16384
	ds_read_b128 v[194:197], v147 offset:17408
	ds_read_b128 v[198:201], v147 offset:18432
	ds_read_b128 v[202:205], v147 offset:19456
	ds_read_b128 v[220:223], v147 offset:20480
	ds_read_b128 v[228:231], v147 offset:21504
	ds_read_b128 v[232:235], v147 offset:22528
	ds_read_b128 v[236:239], v147 offset:23552
	global_load_lds_dwordx4 v[240:241], off
	s_add_i32 m0, s72, 0x2000
	s_add_u32 s72, s62, 0x40000
	v_lshl_add_u64 v[242:243], s[62:63], 0, v[128:129]
	s_addc_u32 s73, s63, 0
	s_add_i32 s55, s55, s24
	global_load_lds_dwordx4 v[242:243], off
	v_lshl_add_u64 v[244:245], s[72:73], 0, v[132:133]
	s_mov_b32 m0, s55
	v_lshl_add_u64 v[246:247], s[64:65], 0, v[130:131]
	global_load_lds_dwordx4 v[244:245], off
	v_lshl_add_u64 v[244:245], s[72:73], 0, v[128:129]
	s_add_i32 m0, s55, 0x2000
	s_nop 0
	global_load_lds_dwordx4 v[244:245], off
	v_lshl_add_u64 v[244:245], s[64:65], 0, v[134:135]
	s_mov_b32 m0, s25
	s_nop 0
	global_load_lds_dwordx4 v[244:245], off
	s_mov_b32 m0, s66
	s_nop 0
	global_load_lds_dwordx4 v[246:247], off
	s_waitcnt vmcnt(8)
	s_waitcnt lgkmcnt(0)
	s_barrier
	v_mfma_f32_16x16x32_bf16 v[60:63], v[140:143], v[190:193], v[60:63]
	v_mfma_f32_16x16x32_bf16 v[56:59], v[152:155], v[190:193], v[56:59]
	v_mfma_f32_16x16x32_bf16 v[44:47], v[140:143], v[198:201], v[44:47]
	v_mfma_f32_16x16x32_bf16 v[40:43], v[152:155], v[198:201], v[40:43]
	v_mfma_f32_16x16x32_bf16 v[28:31], v[140:143], v[220:223], v[28:31]
	v_mfma_f32_16x16x32_bf16 v[24:27], v[152:155], v[220:223], v[24:27]
	v_mfma_f32_16x16x32_bf16 v[12:15], v[140:143], v[232:235], v[12:15]
	v_mfma_f32_16x16x32_bf16 v[8:11], v[152:155], v[232:235], v[8:11]
	v_mfma_f32_16x16x32_bf16 v[60:63], v[148:151], v[194:197], v[60:63]
	v_mfma_f32_16x16x32_bf16 v[56:59], v[156:159], v[194:197], v[56:59]
	v_mfma_f32_16x16x32_bf16 v[44:47], v[148:151], v[202:205], v[44:47]
	v_mfma_f32_16x16x32_bf16 v[40:43], v[156:159], v[202:205], v[40:43]
	v_mfma_f32_16x16x32_bf16 v[28:31], v[148:151], v[228:231], v[28:31]
	v_mfma_f32_16x16x32_bf16 v[24:27], v[156:159], v[228:231], v[24:27]
	v_mfma_f32_16x16x32_bf16 v[12:15], v[148:151], v[236:239], v[12:15]
	v_mfma_f32_16x16x32_bf16 v[8:11], v[156:159], v[236:239], v[8:11]
	v_mfma_f32_16x16x32_bf16 v[52:55], v[174:177], v[190:193], v[52:55]
	v_mfma_f32_16x16x32_bf16 v[48:51], v[182:185], v[190:193], v[48:51]
	v_mfma_f32_16x16x32_bf16 v[36:39], v[174:177], v[198:201], v[36:39]
	v_mfma_f32_16x16x32_bf16 v[32:35], v[182:185], v[198:201], v[32:35]
	v_mfma_f32_16x16x32_bf16 v[20:23], v[174:177], v[220:223], v[20:23]
	v_mfma_f32_16x16x32_bf16 v[16:19], v[182:185], v[220:223], v[16:19]
	v_mfma_f32_16x16x32_bf16 v[4:7], v[174:177], v[232:235], v[4:7]
	v_mfma_f32_16x16x32_bf16 v[0:3], v[182:185], v[232:235], v[0:3]
	v_mfma_f32_16x16x32_bf16 v[52:55], v[178:181], v[194:197], v[52:55]
	v_mfma_f32_16x16x32_bf16 v[48:51], v[186:189], v[194:197], v[48:51]
	v_mfma_f32_16x16x32_bf16 v[36:39], v[178:181], v[202:205], v[36:39]
	v_mfma_f32_16x16x32_bf16 v[32:35], v[186:189], v[202:205], v[32:35]
	v_mfma_f32_16x16x32_bf16 v[20:23], v[178:181], v[228:231], v[20:23]
	v_mfma_f32_16x16x32_bf16 v[16:19], v[186:189], v[228:231], v[16:19]
	v_mfma_f32_16x16x32_bf16 v[4:7], v[178:181], v[236:239], v[4:7]
	v_mfma_f32_16x16x32_bf16 v[0:3], v[186:189], v[236:239], v[0:3]
	s_barrier
	s_add_i32 s55, 0, 0x18000
	s_add_i32 s72, 0, 0x1c000
	v_add_u32_e32 v156, s55, v145
	v_add_u32_e32 v162, s72, v145
	ds_read_b128 v[140:143], v156
	ds_read_b128 v[148:151], v156 offset:1024
	ds_read_b128 v[152:155], v156 offset:2048
	ds_read_b128 v[156:159], v156 offset:3072
	ds_read_b128 v[174:177], v162
	ds_read_b128 v[178:181], v162 offset:1024
	ds_read_b128 v[182:185], v162 offset:2048
	ds_read_b128 v[186:189], v162 offset:3072
	s_add_u32 s64, s64, 0x40000
	s_addc_u32 s65, s65, 0
	s_mov_b32 m0, s67
	v_lshl_add_u64 v[248:249], s[64:65], 0, v[134:135]
	ds_read_b128 v[190:193], v147 offset:32768
	ds_read_b128 v[194:197], v147 offset:33792
	ds_read_b128 v[198:201], v147 offset:34816
	ds_read_b128 v[202:205], v147 offset:35840
	ds_read_b128 v[220:223], v147 offset:36864
	ds_read_b128 v[228:231], v147 offset:37888
	ds_read_b128 v[232:235], v147 offset:38912
	ds_read_b128 v[236:239], v147 offset:39936
	global_load_lds_dwordx4 v[248:249], off
	v_lshl_add_u64 v[248:249], s[64:65], 0, v[130:131]
	s_mov_b32 m0, s68
	s_nop 0
	global_load_lds_dwordx4 v[248:249], off
	s_waitcnt vmcnt(8)
	s_waitcnt lgkmcnt(0)
	s_barrier
	v_mfma_f32_16x16x32_bf16 v[124:127], v[140:143], v[190:193], v[124:127]
	v_mfma_f32_16x16x32_bf16 v[120:123], v[152:155], v[190:193], v[120:123]
	v_mfma_f32_16x16x32_bf16 v[108:111], v[140:143], v[198:201], v[108:111]
	v_mfma_f32_16x16x32_bf16 v[104:107], v[152:155], v[198:201], v[104:107]
	v_mfma_f32_16x16x32_bf16 v[92:95], v[140:143], v[220:223], v[92:95]
	v_mfma_f32_16x16x32_bf16 v[88:91], v[152:155], v[220:223], v[88:91]
	v_mfma_f32_16x16x32_bf16 v[76:79], v[140:143], v[232:235], v[76:79]
	v_mfma_f32_16x16x32_bf16 v[72:75], v[152:155], v[232:235], v[72:75]
	v_mfma_f32_16x16x32_bf16 v[124:127], v[148:151], v[194:197], v[124:127]
	v_mfma_f32_16x16x32_bf16 v[120:123], v[156:159], v[194:197], v[120:123]
	v_mfma_f32_16x16x32_bf16 v[108:111], v[148:151], v[202:205], v[108:111]
	v_mfma_f32_16x16x32_bf16 v[104:107], v[156:159], v[202:205], v[104:107]
	v_mfma_f32_16x16x32_bf16 v[92:95], v[148:151], v[228:231], v[92:95]
	v_mfma_f32_16x16x32_bf16 v[88:91], v[156:159], v[228:231], v[88:91]
	v_mfma_f32_16x16x32_bf16 v[76:79], v[148:151], v[236:239], v[76:79]
	v_mfma_f32_16x16x32_bf16 v[72:75], v[156:159], v[236:239], v[72:75]
	v_mfma_f32_16x16x32_bf16 v[116:119], v[174:177], v[190:193], v[116:119]
	v_mfma_f32_16x16x32_bf16 v[112:115], v[182:185], v[190:193], v[112:115]
	v_mfma_f32_16x16x32_bf16 v[100:103], v[174:177], v[198:201], v[100:103]
	v_mfma_f32_16x16x32_bf16 v[96:99], v[182:185], v[198:201], v[96:99]
	v_mfma_f32_16x16x32_bf16 v[84:87], v[174:177], v[220:223], v[84:87]
	v_mfma_f32_16x16x32_bf16 v[80:83], v[182:185], v[220:223], v[80:83]
	v_mfma_f32_16x16x32_bf16 v[68:71], v[174:177], v[232:235], v[68:71]
	v_mfma_f32_16x16x32_bf16 v[64:67], v[182:185], v[232:235], v[64:67]
	v_mfma_f32_16x16x32_bf16 v[116:119], v[178:181], v[194:197], v[116:119]
	v_mfma_f32_16x16x32_bf16 v[112:115], v[186:189], v[194:197], v[112:115]
	v_mfma_f32_16x16x32_bf16 v[100:103], v[178:181], v[202:205], v[100:103]
	v_mfma_f32_16x16x32_bf16 v[96:99], v[186:189], v[202:205], v[96:99]
	v_mfma_f32_16x16x32_bf16 v[84:87], v[178:181], v[228:231], v[84:87]
	v_mfma_f32_16x16x32_bf16 v[80:83], v[186:189], v[228:231], v[80:83]
	v_mfma_f32_16x16x32_bf16 v[68:71], v[178:181], v[236:239], v[68:71]
	v_mfma_f32_16x16x32_bf16 v[64:67], v[186:189], v[236:239], v[64:67]
	s_barrier
	s_add_i32 s55, s55, s24
	v_lshl_add_u64 v[240:241], v[240:241], 0, s[4:5]
	s_mov_b32 m0, s55
	ds_read_b128 v[190:193], v147 offset:49152
	ds_read_b128 v[194:197], v147 offset:50176
	ds_read_b128 v[198:201], v147 offset:51200
	ds_read_b128 v[202:205], v147 offset:52224
	ds_read_b128 v[220:223], v147 offset:53248
	ds_read_b128 v[228:231], v147 offset:54272
	ds_read_b128 v[232:235], v147 offset:55296
	ds_read_b128 v[236:239], v147 offset:56320
	global_load_lds_dwordx4 v[240:241], off
	s_add_i32 m0, s55, 0x2000
	s_add_u32 s62, s62, 0x40080
	v_lshl_add_u64 v[240:241], v[242:243], 0, s[4:5]
	s_addc_u32 s63, s63, 0
	s_add_i32 s55, s72, s24
	global_load_lds_dwordx4 v[240:241], off
	v_lshl_add_u64 v[240:241], s[62:63], 0, v[132:133]
	s_mov_b32 m0, s55
	s_nop 0
	global_load_lds_dwordx4 v[240:241], off
	v_lshl_add_u64 v[240:241], s[62:63], 0, v[128:129]
	s_add_i32 m0, s55, 0x2000
	s_nop 0
	global_load_lds_dwordx4 v[240:241], off
	v_lshl_add_u64 v[240:241], v[244:245], 0, s[4:5]
	s_mov_b32 m0, s69
	s_nop 0
	global_load_lds_dwordx4 v[240:241], off
	v_lshl_add_u64 v[240:241], v[246:247], 0, s[4:5]
	s_mov_b32 m0, s70
	s_nop 0
	global_load_lds_dwordx4 v[240:241], off
	s_waitcnt vmcnt(8)
	s_waitcnt lgkmcnt(0)
	s_barrier
	v_mfma_f32_16x16x32_bf16 v[60:63], v[140:143], v[190:193], v[60:63]
	v_mfma_f32_16x16x32_bf16 v[56:59], v[152:155], v[190:193], v[56:59]
	v_mfma_f32_16x16x32_bf16 v[44:47], v[140:143], v[198:201], v[44:47]
	v_mfma_f32_16x16x32_bf16 v[40:43], v[152:155], v[198:201], v[40:43]
	v_mfma_f32_16x16x32_bf16 v[28:31], v[140:143], v[220:223], v[28:31]
	v_mfma_f32_16x16x32_bf16 v[24:27], v[152:155], v[220:223], v[24:27]
	v_mfma_f32_16x16x32_bf16 v[12:15], v[140:143], v[232:235], v[12:15]
	v_mfma_f32_16x16x32_bf16 v[8:11], v[152:155], v[232:235], v[8:11]
	v_mfma_f32_16x16x32_bf16 v[60:63], v[148:151], v[194:197], v[60:63]
	v_mfma_f32_16x16x32_bf16 v[56:59], v[156:159], v[194:197], v[56:59]
	v_mfma_f32_16x16x32_bf16 v[44:47], v[148:151], v[202:205], v[44:47]
	v_mfma_f32_16x16x32_bf16 v[40:43], v[156:159], v[202:205], v[40:43]
	v_mfma_f32_16x16x32_bf16 v[28:31], v[148:151], v[228:231], v[28:31]
	v_mfma_f32_16x16x32_bf16 v[24:27], v[156:159], v[228:231], v[24:27]
	v_mfma_f32_16x16x32_bf16 v[12:15], v[148:151], v[236:239], v[12:15]
	v_mfma_f32_16x16x32_bf16 v[8:11], v[156:159], v[236:239], v[8:11]
	v_mfma_f32_16x16x32_bf16 v[52:55], v[174:177], v[190:193], v[52:55]
	v_mfma_f32_16x16x32_bf16 v[48:51], v[182:185], v[190:193], v[48:51]
	v_mfma_f32_16x16x32_bf16 v[36:39], v[174:177], v[198:201], v[36:39]
	v_mfma_f32_16x16x32_bf16 v[32:35], v[182:185], v[198:201], v[32:35]
	v_mfma_f32_16x16x32_bf16 v[20:23], v[174:177], v[220:223], v[20:23]
	v_mfma_f32_16x16x32_bf16 v[16:19], v[182:185], v[220:223], v[16:19]
	v_mfma_f32_16x16x32_bf16 v[4:7], v[174:177], v[232:235], v[4:7]
	v_mfma_f32_16x16x32_bf16 v[0:3], v[182:185], v[232:235], v[0:3]
	v_mfma_f32_16x16x32_bf16 v[52:55], v[178:181], v[194:197], v[52:55]
	v_mfma_f32_16x16x32_bf16 v[48:51], v[186:189], v[194:197], v[48:51]
	v_mfma_f32_16x16x32_bf16 v[36:39], v[178:181], v[202:205], v[36:39]
	v_mfma_f32_16x16x32_bf16 v[32:35], v[186:189], v[202:205], v[32:35]
	v_mfma_f32_16x16x32_bf16 v[20:23], v[178:181], v[228:231], v[20:23]
	v_mfma_f32_16x16x32_bf16 v[16:19], v[186:189], v[228:231], v[16:19]
	v_mfma_f32_16x16x32_bf16 v[4:7], v[178:181], v[236:239], v[4:7]
	v_mfma_f32_16x16x32_bf16 v[0:3], v[186:189], v[236:239], v[0:3]
	s_barrier
	s_add_i32 s53, s53, 2
	s_add_u32 s60, s60, 0x100
	s_addc_u32 s61, s61, 0
	s_add_u32 s30, s30, 0x100
	s_addc_u32 s31, s31, 0
	s_cmp_gt_u32 s53, 13
	s_cbranch_scc0 .LBB0_771
	s_and_b64 vcc, exec, s[48:49]
	s_mov_b64 s[30:31], s[34:35]
	s_cbranch_vccz .LBB0_774
	s_barrier

.LBB0_858:
	s_add_u32 s61, s66, 0xfffe0080
	s_addc_u32 s68, s67, -1
	s_add_i32 s83, 0, 0x10000
	s_cmp_eq_u32 s59, 4
	s_cselect_b32 s71, s6, s68
	s_cselect_b32 s70, s7, s61
	v_add_u32_e32 v136, s83, v157
	s_cselect_b32 s69, s28, s31
	s_cselect_b32 s68, s29, s30
	s_add_i32 s61, 0, 0x14000
	ds_read_b128 v[128:131], v136
	ds_read_b128 v[132:135], v136 offset:1024
	ds_read_b128 v[148:151], v136 offset:2048
	ds_read_b128 v[152:155], v136 offset:3072
	v_add_u32_e32 v136, s61, v157
	ds_read_b128 v[174:177], v136
	ds_read_b128 v[178:181], v136 offset:1024
	ds_read_b128 v[182:185], v136 offset:2048
	ds_read_b128 v[186:189], v136 offset:3072
	v_lshl_add_u64 v[136:137], s[66:67], 0, v[144:145]
	s_add_i32 m0, s25, 0xc000
	ds_read_b128 v[190:193], v159
	ds_read_b128 v[194:197], v159 offset:1024
	ds_read_b128 v[198:201], v159 offset:2048
	ds_read_b128 v[202:205], v159 offset:3072
	ds_read_b128 v[220:223], v159 offset:4096
	ds_read_b128 v[228:231], v159 offset:5120
	ds_read_b128 v[232:235], v159 offset:6144
	ds_read_b128 v[236:239], v159 offset:7168
	global_load_lds_dwordx4 v[136:137], off
	v_lshl_add_u64 v[136:137], s[66:67], 0, v[146:147]
	s_add_i32 m0, s25, 0xe000
	s_nop 0
	global_load_lds_dwordx4 v[136:137], off
	s_waitcnt vmcnt(8)
	s_waitcnt lgkmcnt(0)
	s_barrier
	v_mfma_f32_16x16x32_bf16 v[124:127], v[128:131], v[190:193], v[124:127]
	v_mfma_f32_16x16x32_bf16 v[120:123], v[148:151], v[190:193], v[120:123]
	v_mfma_f32_16x16x32_bf16 v[108:111], v[128:131], v[198:201], v[108:111]
	v_mfma_f32_16x16x32_bf16 v[104:107], v[148:151], v[198:201], v[104:107]
	v_mfma_f32_16x16x32_bf16 v[92:95], v[128:131], v[220:223], v[92:95]
	v_mfma_f32_16x16x32_bf16 v[88:91], v[148:151], v[220:223], v[88:91]
	v_mfma_f32_16x16x32_bf16 v[76:79], v[128:131], v[232:235], v[76:79]
	v_mfma_f32_16x16x32_bf16 v[72:75], v[148:151], v[232:235], v[72:75]
	v_mfma_f32_16x16x32_bf16 v[124:127], v[132:135], v[194:197], v[124:127]
	v_mfma_f32_16x16x32_bf16 v[120:123], v[152:155], v[194:197], v[120:123]
	v_mfma_f32_16x16x32_bf16 v[108:111], v[132:135], v[202:205], v[108:111]
	v_mfma_f32_16x16x32_bf16 v[104:107], v[152:155], v[202:205], v[104:107]
	v_mfma_f32_16x16x32_bf16 v[92:95], v[132:135], v[228:231], v[92:95]
	v_mfma_f32_16x16x32_bf16 v[88:91], v[152:155], v[228:231], v[88:91]
	v_mfma_f32_16x16x32_bf16 v[76:79], v[132:135], v[236:239], v[76:79]
	v_mfma_f32_16x16x32_bf16 v[72:75], v[152:155], v[236:239], v[72:75]
	v_mfma_f32_16x16x32_bf16 v[116:119], v[174:177], v[190:193], v[116:119]
	v_mfma_f32_16x16x32_bf16 v[112:115], v[182:185], v[190:193], v[112:115]
	v_mfma_f32_16x16x32_bf16 v[100:103], v[174:177], v[198:201], v[100:103]
	v_mfma_f32_16x16x32_bf16 v[96:99], v[182:185], v[198:201], v[96:99]
	v_mfma_f32_16x16x32_bf16 v[84:87], v[174:177], v[220:223], v[84:87]
	v_mfma_f32_16x16x32_bf16 v[80:83], v[182:185], v[220:223], v[80:83]
	v_mfma_f32_16x16x32_bf16 v[68:71], v[174:177], v[232:235], v[68:71]
	v_mfma_f32_16x16x32_bf16 v[64:67], v[182:185], v[232:235], v[64:67]
	v_mfma_f32_16x16x32_bf16 v[116:119], v[178:181], v[194:197], v[116:119]
	v_mfma_f32_16x16x32_bf16 v[112:115], v[186:189], v[194:197], v[112:115]
	v_mfma_f32_16x16x32_bf16 v[100:103], v[178:181], v[202:205], v[100:103]
	v_mfma_f32_16x16x32_bf16 v[96:99], v[186:189], v[202:205], v[96:99]
	v_mfma_f32_16x16x32_bf16 v[84:87], v[178:181], v[228:231], v[84:87]
	v_mfma_f32_16x16x32_bf16 v[80:83], v[186:189], v[228:231], v[80:83]
	v_mfma_f32_16x16x32_bf16 v[68:71], v[178:181], v[236:239], v[68:71]
	v_mfma_f32_16x16x32_bf16 v[64:67], v[186:189], v[236:239], v[64:67]
	s_barrier
	s_add_i32 s83, s83, s22
	v_lshl_add_u64 v[136:137], s[68:69], 0, v[162:163]
	s_mov_b32 m0, s83
	ds_read_b128 v[190:193], v159 offset:16384
	ds_read_b128 v[194:197], v159 offset:17408
	ds_read_b128 v[198:201], v159 offset:18432
	ds_read_b128 v[202:205], v159 offset:19456
	ds_read_b128 v[220:223], v159 offset:20480
	ds_read_b128 v[228:231], v159 offset:21504
	ds_read_b128 v[232:235], v159 offset:22528
	ds_read_b128 v[236:239], v159 offset:23552
	global_load_lds_dwordx4 v[136:137], off
	s_add_i32 m0, s83, 0x2000
	s_add_u32 s84, s68, 0x20000
	v_lshl_add_u64 v[240:241], s[68:69], 0, v[138:139]
	s_addc_u32 s85, s69, 0
	s_add_i32 s61, s61, s22
	global_load_lds_dwordx4 v[240:241], off
	v_lshl_add_u64 v[242:243], s[84:85], 0, v[162:163]
	s_mov_b32 m0, s61
	v_lshl_add_u64 v[244:245], s[70:71], 0, v[140:141]
	global_load_lds_dwordx4 v[242:243], off
	v_lshl_add_u64 v[242:243], s[84:85], 0, v[138:139]
	s_add_i32 m0, s61, 0x2000
	s_nop 0
	global_load_lds_dwordx4 v[242:243], off
	v_lshl_add_u64 v[242:243], s[70:71], 0, v[142:143]
	s_mov_b32 m0, s25
	s_nop 0
	global_load_lds_dwordx4 v[242:243], off
	s_mov_b32 m0, s72
	s_nop 0
	global_load_lds_dwordx4 v[244:245], off
	s_waitcnt vmcnt(8)
	s_waitcnt lgkmcnt(0)
	s_barrier
	v_mfma_f32_16x16x32_bf16 v[60:63], v[128:131], v[190:193], v[60:63]
	v_mfma_f32_16x16x32_bf16 v[56:59], v[148:151], v[190:193], v[56:59]
	v_mfma_f32_16x16x32_bf16 v[44:47], v[128:131], v[198:201], v[44:47]
	v_mfma_f32_16x16x32_bf16 v[40:43], v[148:151], v[198:201], v[40:43]
	v_mfma_f32_16x16x32_bf16 v[28:31], v[128:131], v[220:223], v[28:31]
	v_mfma_f32_16x16x32_bf16 v[24:27], v[148:151], v[220:223], v[24:27]
	v_mfma_f32_16x16x32_bf16 v[12:15], v[128:131], v[232:235], v[12:15]
	v_mfma_f32_16x16x32_bf16 v[8:11], v[148:151], v[232:235], v[8:11]
	v_mfma_f32_16x16x32_bf16 v[60:63], v[132:135], v[194:197], v[60:63]
	v_mfma_f32_16x16x32_bf16 v[56:59], v[152:155], v[194:197], v[56:59]
	v_mfma_f32_16x16x32_bf16 v[44:47], v[132:135], v[202:205], v[44:47]
	v_mfma_f32_16x16x32_bf16 v[40:43], v[152:155], v[202:205], v[40:43]
	v_mfma_f32_16x16x32_bf16 v[28:31], v[132:135], v[228:231], v[28:31]
	v_mfma_f32_16x16x32_bf16 v[24:27], v[152:155], v[228:231], v[24:27]
	v_mfma_f32_16x16x32_bf16 v[12:15], v[132:135], v[236:239], v[12:15]
	v_mfma_f32_16x16x32_bf16 v[8:11], v[152:155], v[236:239], v[8:11]
	v_mfma_f32_16x16x32_bf16 v[52:55], v[174:177], v[190:193], v[52:55]
	v_mfma_f32_16x16x32_bf16 v[48:51], v[182:185], v[190:193], v[48:51]
	v_mfma_f32_16x16x32_bf16 v[36:39], v[174:177], v[198:201], v[36:39]
	v_mfma_f32_16x16x32_bf16 v[32:35], v[182:185], v[198:201], v[32:35]
	v_mfma_f32_16x16x32_bf16 v[20:23], v[174:177], v[220:223], v[20:23]
	v_mfma_f32_16x16x32_bf16 v[16:19], v[182:185], v[220:223], v[16:19]
	v_mfma_f32_16x16x32_bf16 v[4:7], v[174:177], v[232:235], v[4:7]
	v_mfma_f32_16x16x32_bf16 v[0:3], v[182:185], v[232:235], v[0:3]
	v_mfma_f32_16x16x32_bf16 v[52:55], v[178:181], v[194:197], v[52:55]
	v_mfma_f32_16x16x32_bf16 v[48:51], v[186:189], v[194:197], v[48:51]
	v_mfma_f32_16x16x32_bf16 v[36:39], v[178:181], v[202:205], v[36:39]
	v_mfma_f32_16x16x32_bf16 v[32:35], v[186:189], v[202:205], v[32:35]
	v_mfma_f32_16x16x32_bf16 v[20:23], v[178:181], v[228:231], v[20:23]
	v_mfma_f32_16x16x32_bf16 v[16:19], v[186:189], v[228:231], v[16:19]
	v_mfma_f32_16x16x32_bf16 v[4:7], v[178:181], v[236:239], v[4:7]
	v_mfma_f32_16x16x32_bf16 v[0:3], v[186:189], v[236:239], v[0:3]
	s_barrier
	s_add_i32 s61, 0, 0x18000
	s_add_i32 s83, 0, 0x1c000
	v_add_u32_e32 v152, s61, v157
	v_add_u32_e32 v186, s83, v157
	ds_read_b128 v[128:131], v152
	ds_read_b128 v[132:135], v152 offset:1024
	ds_read_b128 v[148:151], v152 offset:2048
	ds_read_b128 v[152:155], v152 offset:3072
	ds_read_b128 v[174:177], v186
	ds_read_b128 v[178:181], v186 offset:1024
	ds_read_b128 v[182:185], v186 offset:2048
	ds_read_b128 v[186:189], v186 offset:3072
	s_add_u32 s70, s70, 0x20000
	s_addc_u32 s71, s71, 0
	s_mov_b32 m0, s73
	v_lshl_add_u64 v[246:247], s[70:71], 0, v[142:143]
	ds_read_b128 v[190:193], v159 offset:32768
	ds_read_b128 v[194:197], v159 offset:33792
	ds_read_b128 v[198:201], v159 offset:34816
	ds_read_b128 v[202:205], v159 offset:35840
	ds_read_b128 v[220:223], v159 offset:36864
	ds_read_b128 v[228:231], v159 offset:37888
	ds_read_b128 v[232:235], v159 offset:38912
	ds_read_b128 v[236:239], v159 offset:39936
	global_load_lds_dwordx4 v[246:247], off
	v_lshl_add_u64 v[246:247], s[70:71], 0, v[140:141]
	s_mov_b32 m0, s74
	s_nop 0
	global_load_lds_dwordx4 v[246:247], off
	s_waitcnt vmcnt(8)
	s_waitcnt lgkmcnt(0)
	s_barrier
	v_mfma_f32_16x16x32_bf16 v[124:127], v[128:131], v[190:193], v[124:127]
	v_mfma_f32_16x16x32_bf16 v[120:123], v[148:151], v[190:193], v[120:123]
	v_mfma_f32_16x16x32_bf16 v[108:111], v[128:131], v[198:201], v[108:111]
	v_mfma_f32_16x16x32_bf16 v[104:107], v[148:151], v[198:201], v[104:107]
	v_mfma_f32_16x16x32_bf16 v[92:95], v[128:131], v[220:223], v[92:95]
	v_mfma_f32_16x16x32_bf16 v[88:91], v[148:151], v[220:223], v[88:91]
	v_mfma_f32_16x16x32_bf16 v[76:79], v[128:131], v[232:235], v[76:79]
	v_mfma_f32_16x16x32_bf16 v[72:75], v[148:151], v[232:235], v[72:75]
	v_mfma_f32_16x16x32_bf16 v[124:127], v[132:135], v[194:197], v[124:127]
	v_mfma_f32_16x16x32_bf16 v[120:123], v[152:155], v[194:197], v[120:123]
	v_mfma_f32_16x16x32_bf16 v[108:111], v[132:135], v[202:205], v[108:111]
	v_mfma_f32_16x16x32_bf16 v[104:107], v[152:155], v[202:205], v[104:107]
	v_mfma_f32_16x16x32_bf16 v[92:95], v[132:135], v[228:231], v[92:95]
	v_mfma_f32_16x16x32_bf16 v[88:91], v[152:155], v[228:231], v[88:91]
	v_mfma_f32_16x16x32_bf16 v[76:79], v[132:135], v[236:239], v[76:79]
	v_mfma_f32_16x16x32_bf16 v[72:75], v[152:155], v[236:239], v[72:75]
	v_mfma_f32_16x16x32_bf16 v[116:119], v[174:177], v[190:193], v[116:119]
	v_mfma_f32_16x16x32_bf16 v[112:115], v[182:185], v[190:193], v[112:115]
	v_mfma_f32_16x16x32_bf16 v[100:103], v[174:177], v[198:201], v[100:103]
	v_mfma_f32_16x16x32_bf16 v[96:99], v[182:185], v[198:201], v[96:99]
	v_mfma_f32_16x16x32_bf16 v[84:87], v[174:177], v[220:223], v[84:87]
	v_mfma_f32_16x16x32_bf16 v[80:83], v[182:185], v[220:223], v[80:83]
	v_mfma_f32_16x16x32_bf16 v[68:71], v[174:177], v[232:235], v[68:71]
	v_mfma_f32_16x16x32_bf16 v[64:67], v[182:185], v[232:235], v[64:67]
	v_mfma_f32_16x16x32_bf16 v[116:119], v[178:181], v[194:197], v[116:119]
	v_mfma_f32_16x16x32_bf16 v[112:115], v[186:189], v[194:197], v[112:115]
	v_mfma_f32_16x16x32_bf16 v[100:103], v[178:181], v[202:205], v[100:103]
	v_mfma_f32_16x16x32_bf16 v[96:99], v[186:189], v[202:205], v[96:99]
	v_mfma_f32_16x16x32_bf16 v[84:87], v[178:181], v[228:231], v[84:87]
	v_mfma_f32_16x16x32_bf16 v[80:83], v[186:189], v[228:231], v[80:83]
	v_mfma_f32_16x16x32_bf16 v[68:71], v[178:181], v[236:239], v[68:71]
	v_mfma_f32_16x16x32_bf16 v[64:67], v[186:189], v[236:239], v[64:67]
	s_barrier
	s_add_i32 s61, s61, s22
	v_lshl_add_u64 v[136:137], v[136:137], 0, s[4:5]
	s_mov_b32 m0, s61
	ds_read_b128 v[190:193], v159 offset:49152
	ds_read_b128 v[194:197], v159 offset:50176
	ds_read_b128 v[198:201], v159 offset:51200
	ds_read_b128 v[202:205], v159 offset:52224
	ds_read_b128 v[220:223], v159 offset:53248
	ds_read_b128 v[228:231], v159 offset:54272
	ds_read_b128 v[232:235], v159 offset:55296
	ds_read_b128 v[236:239], v159 offset:56320
	global_load_lds_dwordx4 v[136:137], off
	s_add_i32 m0, s61, 0x2000
	s_add_u32 s68, s68, 0x20080
	v_lshl_add_u64 v[136:137], v[240:241], 0, s[4:5]
	s_addc_u32 s69, s69, 0
	s_add_i32 s61, s83, s22
	global_load_lds_dwordx4 v[136:137], off
	v_lshl_add_u64 v[136:137], s[68:69], 0, v[162:163]
	s_mov_b32 m0, s61
	s_nop 0
	global_load_lds_dwordx4 v[136:137], off
	v_lshl_add_u64 v[136:137], s[68:69], 0, v[138:139]
	s_add_i32 m0, s61, 0x2000
	s_nop 0
	global_load_lds_dwordx4 v[136:137], off
	v_lshl_add_u64 v[136:137], v[242:243], 0, s[4:5]
	s_mov_b32 m0, s75
	s_nop 0
	global_load_lds_dwordx4 v[136:137], off
	v_lshl_add_u64 v[136:137], v[244:245], 0, s[4:5]
	s_mov_b32 m0, s76
	s_nop 0
	global_load_lds_dwordx4 v[136:137], off
	s_waitcnt vmcnt(8)
	s_waitcnt lgkmcnt(0)
	s_barrier
	v_mfma_f32_16x16x32_bf16 v[60:63], v[128:131], v[190:193], v[60:63]
	v_mfma_f32_16x16x32_bf16 v[56:59], v[148:151], v[190:193], v[56:59]
	v_mfma_f32_16x16x32_bf16 v[44:47], v[128:131], v[198:201], v[44:47]
	v_mfma_f32_16x16x32_bf16 v[40:43], v[148:151], v[198:201], v[40:43]
	v_mfma_f32_16x16x32_bf16 v[28:31], v[128:131], v[220:223], v[28:31]
	v_mfma_f32_16x16x32_bf16 v[24:27], v[148:151], v[220:223], v[24:27]
	v_mfma_f32_16x16x32_bf16 v[12:15], v[128:131], v[232:235], v[12:15]
	v_mfma_f32_16x16x32_bf16 v[8:11], v[148:151], v[232:235], v[8:11]
	v_mfma_f32_16x16x32_bf16 v[60:63], v[132:135], v[194:197], v[60:63]
	v_mfma_f32_16x16x32_bf16 v[56:59], v[152:155], v[194:197], v[56:59]
	v_mfma_f32_16x16x32_bf16 v[44:47], v[132:135], v[202:205], v[44:47]
	v_mfma_f32_16x16x32_bf16 v[40:43], v[152:155], v[202:205], v[40:43]
	v_mfma_f32_16x16x32_bf16 v[28:31], v[132:135], v[228:231], v[28:31]
	v_mfma_f32_16x16x32_bf16 v[24:27], v[152:155], v[228:231], v[24:27]
	v_mfma_f32_16x16x32_bf16 v[12:15], v[132:135], v[236:239], v[12:15]
	v_mfma_f32_16x16x32_bf16 v[8:11], v[152:155], v[236:239], v[8:11]
	v_mfma_f32_16x16x32_bf16 v[52:55], v[174:177], v[190:193], v[52:55]
	v_mfma_f32_16x16x32_bf16 v[48:51], v[182:185], v[190:193], v[48:51]
	v_mfma_f32_16x16x32_bf16 v[36:39], v[174:177], v[198:201], v[36:39]
	v_mfma_f32_16x16x32_bf16 v[32:35], v[182:185], v[198:201], v[32:35]
	v_mfma_f32_16x16x32_bf16 v[20:23], v[174:177], v[220:223], v[20:23]
	v_mfma_f32_16x16x32_bf16 v[16:19], v[182:185], v[220:223], v[16:19]
	v_mfma_f32_16x16x32_bf16 v[4:7], v[174:177], v[232:235], v[4:7]
	v_mfma_f32_16x16x32_bf16 v[0:3], v[182:185], v[232:235], v[0:3]
	v_mfma_f32_16x16x32_bf16 v[52:55], v[178:181], v[194:197], v[52:55]
	v_mfma_f32_16x16x32_bf16 v[48:51], v[186:189], v[194:197], v[48:51]
	v_mfma_f32_16x16x32_bf16 v[36:39], v[178:181], v[202:205], v[36:39]
	v_mfma_f32_16x16x32_bf16 v[32:35], v[186:189], v[202:205], v[32:35]
	v_mfma_f32_16x16x32_bf16 v[20:23], v[178:181], v[228:231], v[20:23]
	v_mfma_f32_16x16x32_bf16 v[16:19], v[186:189], v[228:231], v[16:19]
	v_mfma_f32_16x16x32_bf16 v[4:7], v[178:181], v[236:239], v[4:7]
	v_mfma_f32_16x16x32_bf16 v[0:3], v[186:189], v[236:239], v[0:3]
	s_barrier
	s_add_i32 s59, s59, 2
	s_add_u32 s66, s66, 0x100
	s_addc_u32 s67, s67, 0
	s_add_u32 s30, s30, 0x100
	s_addc_u32 s31, s31, 0
	s_cmp_gt_u32 s59, 5
	s_cbranch_scc0 .LBB0_858
	s_and_b64 vcc, exec, s[56:57]
	s_cbranch_vccz .LBB0_861
	s_barrier

.LBB0_975:
	s_add_u32 s29, s60, 0xfffc0080
	s_addc_u32 s30, s61, -1
	s_add_i32 s31, 0, 0x10000
	s_cmp_eq_u32 s28, 12
	s_cselect_b32 s65, s6, s30
	s_cselect_b32 s64, s7, s29
	v_add_u32_e32 v142, s31, v145
	s_cselect_b32 s63, s24, s27
	s_cselect_b32 s62, s25, s26
	s_add_i32 s29, 0, 0x14000
	ds_read_b128 v[138:141], v142
	ds_read_b128 v[148:151], v142 offset:1024
	ds_read_b128 v[152:155], v142 offset:2048
	ds_read_b128 v[156:159], v142 offset:3072
	v_add_u32_e32 v142, s29, v145
	ds_read_b128 v[174:177], v142
	ds_read_b128 v[178:181], v142 offset:1024
	ds_read_b128 v[182:185], v142 offset:2048
	ds_read_b128 v[186:189], v142 offset:3072
	v_lshl_add_u64 v[142:143], s[60:61], 0, v[134:135]
	s_add_i32 m0, s69, 0xc000
	ds_read_b128 v[190:193], v147
	ds_read_b128 v[194:197], v147 offset:1024
	ds_read_b128 v[198:201], v147 offset:2048
	ds_read_b128 v[202:205], v147 offset:3072
	ds_read_b128 v[220:223], v147 offset:4096
	ds_read_b128 v[228:231], v147 offset:5120
	ds_read_b128 v[232:235], v147 offset:6144
	ds_read_b128 v[236:239], v147 offset:7168
	global_load_lds_dwordx4 v[142:143], off
	v_lshl_add_u64 v[142:143], s[60:61], 0, v[136:137]
	s_add_i32 m0, s69, 0xe000
	s_nop 0
	global_load_lds_dwordx4 v[142:143], off
	s_waitcnt vmcnt(8)
	s_waitcnt lgkmcnt(0)
	s_barrier
	v_mfma_f32_16x16x32_bf16 v[124:127], v[138:141], v[190:193], v[124:127]
	v_mfma_f32_16x16x32_bf16 v[120:123], v[152:155], v[190:193], v[120:123]
	v_mfma_f32_16x16x32_bf16 v[108:111], v[138:141], v[198:201], v[108:111]
	v_mfma_f32_16x16x32_bf16 v[104:107], v[152:155], v[198:201], v[104:107]
	v_mfma_f32_16x16x32_bf16 v[92:95], v[138:141], v[220:223], v[92:95]
	v_mfma_f32_16x16x32_bf16 v[88:91], v[152:155], v[220:223], v[88:91]
	v_mfma_f32_16x16x32_bf16 v[76:79], v[138:141], v[232:235], v[76:79]
	v_mfma_f32_16x16x32_bf16 v[72:75], v[152:155], v[232:235], v[72:75]
	v_mfma_f32_16x16x32_bf16 v[124:127], v[148:151], v[194:197], v[124:127]
	v_mfma_f32_16x16x32_bf16 v[120:123], v[156:159], v[194:197], v[120:123]
	v_mfma_f32_16x16x32_bf16 v[108:111], v[148:151], v[202:205], v[108:111]
	v_mfma_f32_16x16x32_bf16 v[104:107], v[156:159], v[202:205], v[104:107]
	v_mfma_f32_16x16x32_bf16 v[92:95], v[148:151], v[228:231], v[92:95]
	v_mfma_f32_16x16x32_bf16 v[88:91], v[156:159], v[228:231], v[88:91]
	v_mfma_f32_16x16x32_bf16 v[76:79], v[148:151], v[236:239], v[76:79]
	v_mfma_f32_16x16x32_bf16 v[72:75], v[156:159], v[236:239], v[72:75]
	v_mfma_f32_16x16x32_bf16 v[116:119], v[174:177], v[190:193], v[116:119]
	v_mfma_f32_16x16x32_bf16 v[112:115], v[182:185], v[190:193], v[112:115]
	v_mfma_f32_16x16x32_bf16 v[100:103], v[174:177], v[198:201], v[100:103]
	v_mfma_f32_16x16x32_bf16 v[96:99], v[182:185], v[198:201], v[96:99]
	v_mfma_f32_16x16x32_bf16 v[84:87], v[174:177], v[220:223], v[84:87]
	v_mfma_f32_16x16x32_bf16 v[80:83], v[182:185], v[220:223], v[80:83]
	v_mfma_f32_16x16x32_bf16 v[68:71], v[174:177], v[232:235], v[68:71]
	v_mfma_f32_16x16x32_bf16 v[64:67], v[182:185], v[232:235], v[64:67]
	v_mfma_f32_16x16x32_bf16 v[116:119], v[178:181], v[194:197], v[116:119]
	v_mfma_f32_16x16x32_bf16 v[112:115], v[186:189], v[194:197], v[112:115]
	v_mfma_f32_16x16x32_bf16 v[100:103], v[178:181], v[202:205], v[100:103]
	v_mfma_f32_16x16x32_bf16 v[96:99], v[186:189], v[202:205], v[96:99]
	v_mfma_f32_16x16x32_bf16 v[84:87], v[178:181], v[228:231], v[84:87]
	v_mfma_f32_16x16x32_bf16 v[80:83], v[186:189], v[228:231], v[80:83]
	v_mfma_f32_16x16x32_bf16 v[68:71], v[178:181], v[236:239], v[68:71]
	v_mfma_f32_16x16x32_bf16 v[64:67], v[186:189], v[236:239], v[64:67]
	s_barrier
	s_add_i32 s30, s31, s68
	v_lshl_add_u64 v[142:143], s[62:63], 0, v[162:163]
	s_mov_b32 m0, s30
	ds_read_b128 v[190:193], v147 offset:16384
	ds_read_b128 v[194:197], v147 offset:17408
	ds_read_b128 v[198:201], v147 offset:18432
	ds_read_b128 v[202:205], v147 offset:19456
	ds_read_b128 v[220:223], v147 offset:20480
	ds_read_b128 v[228:231], v147 offset:21504
	ds_read_b128 v[232:235], v147 offset:22528
	ds_read_b128 v[236:239], v147 offset:23552
	global_load_lds_dwordx4 v[142:143], off
	s_add_i32 m0, s30, 0x2000
	s_add_u32 s30, s62, 0x40000
	v_lshl_add_u64 v[240:241], s[62:63], 0, v[128:129]
	s_addc_u32 s31, s63, 0
	s_add_i32 s29, s29, s68
	global_load_lds_dwordx4 v[240:241], off
	v_lshl_add_u64 v[242:243], s[30:31], 0, v[162:163]
	s_mov_b32 m0, s29
	v_lshl_add_u64 v[244:245], s[64:65], 0, v[130:131]
	global_load_lds_dwordx4 v[242:243], off
	v_lshl_add_u64 v[242:243], s[30:31], 0, v[128:129]
	s_add_i32 m0, s29, 0x2000
	s_nop 0
	global_load_lds_dwordx4 v[242:243], off
	v_lshl_add_u64 v[242:243], s[64:65], 0, v[132:133]
	s_mov_b32 m0, s69
	s_nop 0
	global_load_lds_dwordx4 v[242:243], off
	s_mov_b32 m0, s70
	s_nop 0
	global_load_lds_dwordx4 v[244:245], off
	s_waitcnt vmcnt(8)
	s_waitcnt lgkmcnt(0)
	s_barrier
	v_mfma_f32_16x16x32_bf16 v[60:63], v[138:141], v[190:193], v[60:63]
	v_mfma_f32_16x16x32_bf16 v[56:59], v[152:155], v[190:193], v[56:59]
	v_mfma_f32_16x16x32_bf16 v[44:47], v[138:141], v[198:201], v[44:47]
	v_mfma_f32_16x16x32_bf16 v[40:43], v[152:155], v[198:201], v[40:43]
	v_mfma_f32_16x16x32_bf16 v[28:31], v[138:141], v[220:223], v[28:31]
	v_mfma_f32_16x16x32_bf16 v[24:27], v[152:155], v[220:223], v[24:27]
	v_mfma_f32_16x16x32_bf16 v[12:15], v[138:141], v[232:235], v[12:15]
	v_mfma_f32_16x16x32_bf16 v[8:11], v[152:155], v[232:235], v[8:11]
	v_mfma_f32_16x16x32_bf16 v[60:63], v[148:151], v[194:197], v[60:63]
	v_mfma_f32_16x16x32_bf16 v[56:59], v[156:159], v[194:197], v[56:59]
	v_mfma_f32_16x16x32_bf16 v[44:47], v[148:151], v[202:205], v[44:47]
	v_mfma_f32_16x16x32_bf16 v[40:43], v[156:159], v[202:205], v[40:43]
	v_mfma_f32_16x16x32_bf16 v[28:31], v[148:151], v[228:231], v[28:31]
	v_mfma_f32_16x16x32_bf16 v[24:27], v[156:159], v[228:231], v[24:27]
	v_mfma_f32_16x16x32_bf16 v[12:15], v[148:151], v[236:239], v[12:15]
	v_mfma_f32_16x16x32_bf16 v[8:11], v[156:159], v[236:239], v[8:11]
	v_mfma_f32_16x16x32_bf16 v[52:55], v[174:177], v[190:193], v[52:55]
	v_mfma_f32_16x16x32_bf16 v[48:51], v[182:185], v[190:193], v[48:51]
	v_mfma_f32_16x16x32_bf16 v[36:39], v[174:177], v[198:201], v[36:39]
	v_mfma_f32_16x16x32_bf16 v[32:35], v[182:185], v[198:201], v[32:35]
	v_mfma_f32_16x16x32_bf16 v[20:23], v[174:177], v[220:223], v[20:23]
	v_mfma_f32_16x16x32_bf16 v[16:19], v[182:185], v[220:223], v[16:19]
	v_mfma_f32_16x16x32_bf16 v[4:7], v[174:177], v[232:235], v[4:7]
	v_mfma_f32_16x16x32_bf16 v[0:3], v[182:185], v[232:235], v[0:3]
	v_mfma_f32_16x16x32_bf16 v[52:55], v[178:181], v[194:197], v[52:55]
	v_mfma_f32_16x16x32_bf16 v[48:51], v[186:189], v[194:197], v[48:51]
	v_mfma_f32_16x16x32_bf16 v[36:39], v[178:181], v[202:205], v[36:39]
	v_mfma_f32_16x16x32_bf16 v[32:35], v[186:189], v[202:205], v[32:35]
	v_mfma_f32_16x16x32_bf16 v[20:23], v[178:181], v[228:231], v[20:23]
	v_mfma_f32_16x16x32_bf16 v[16:19], v[186:189], v[228:231], v[16:19]
	v_mfma_f32_16x16x32_bf16 v[4:7], v[178:181], v[236:239], v[4:7]
	v_mfma_f32_16x16x32_bf16 v[0:3], v[186:189], v[236:239], v[0:3]
	s_barrier
	s_add_i32 s29, 0, 0x18000
	s_add_i32 s53, 0, 0x1c000
	v_add_u32_e32 v156, s29, v145
	v_add_u32_e32 v186, s53, v145
	ds_read_b128 v[138:141], v156
	ds_read_b128 v[148:151], v156 offset:1024
	ds_read_b128 v[152:155], v156 offset:2048
	ds_read_b128 v[156:159], v156 offset:3072
	ds_read_b128 v[174:177], v186
	ds_read_b128 v[178:181], v186 offset:1024
	ds_read_b128 v[182:185], v186 offset:2048
	ds_read_b128 v[186:189], v186 offset:3072
	s_add_u32 s30, s64, 0x40000
	s_addc_u32 s31, s65, 0
	s_mov_b32 m0, s71
	v_lshl_add_u64 v[246:247], s[30:31], 0, v[132:133]
	ds_read_b128 v[190:193], v147 offset:32768
	ds_read_b128 v[194:197], v147 offset:33792
	ds_read_b128 v[198:201], v147 offset:34816
	ds_read_b128 v[202:205], v147 offset:35840
	ds_read_b128 v[220:223], v147 offset:36864
	ds_read_b128 v[228:231], v147 offset:37888
	ds_read_b128 v[232:235], v147 offset:38912
	ds_read_b128 v[236:239], v147 offset:39936
	global_load_lds_dwordx4 v[246:247], off
	v_lshl_add_u64 v[246:247], s[30:31], 0, v[130:131]
	s_mov_b32 m0, s72
	s_nop 0
	global_load_lds_dwordx4 v[246:247], off
	s_waitcnt vmcnt(8)
	s_waitcnt lgkmcnt(0)
	s_barrier
	v_mfma_f32_16x16x32_bf16 v[124:127], v[138:141], v[190:193], v[124:127]
	v_mfma_f32_16x16x32_bf16 v[120:123], v[152:155], v[190:193], v[120:123]
	v_mfma_f32_16x16x32_bf16 v[108:111], v[138:141], v[198:201], v[108:111]
	v_mfma_f32_16x16x32_bf16 v[104:107], v[152:155], v[198:201], v[104:107]
	v_mfma_f32_16x16x32_bf16 v[92:95], v[138:141], v[220:223], v[92:95]
	v_mfma_f32_16x16x32_bf16 v[88:91], v[152:155], v[220:223], v[88:91]
	v_mfma_f32_16x16x32_bf16 v[76:79], v[138:141], v[232:235], v[76:79]
	v_mfma_f32_16x16x32_bf16 v[72:75], v[152:155], v[232:235], v[72:75]
	v_mfma_f32_16x16x32_bf16 v[124:127], v[148:151], v[194:197], v[124:127]
	v_mfma_f32_16x16x32_bf16 v[120:123], v[156:159], v[194:197], v[120:123]
	v_mfma_f32_16x16x32_bf16 v[108:111], v[148:151], v[202:205], v[108:111]
	v_mfma_f32_16x16x32_bf16 v[104:107], v[156:159], v[202:205], v[104:107]
	v_mfma_f32_16x16x32_bf16 v[92:95], v[148:151], v[228:231], v[92:95]
	v_mfma_f32_16x16x32_bf16 v[88:91], v[156:159], v[228:231], v[88:91]
	v_mfma_f32_16x16x32_bf16 v[76:79], v[148:151], v[236:239], v[76:79]
	v_mfma_f32_16x16x32_bf16 v[72:75], v[156:159], v[236:239], v[72:75]
	v_mfma_f32_16x16x32_bf16 v[116:119], v[174:177], v[190:193], v[116:119]
	v_mfma_f32_16x16x32_bf16 v[112:115], v[182:185], v[190:193], v[112:115]
	v_mfma_f32_16x16x32_bf16 v[100:103], v[174:177], v[198:201], v[100:103]
	v_mfma_f32_16x16x32_bf16 v[96:99], v[182:185], v[198:201], v[96:99]
	v_mfma_f32_16x16x32_bf16 v[84:87], v[174:177], v[220:223], v[84:87]
	v_mfma_f32_16x16x32_bf16 v[80:83], v[182:185], v[220:223], v[80:83]
	v_mfma_f32_16x16x32_bf16 v[68:71], v[174:177], v[232:235], v[68:71]
	v_mfma_f32_16x16x32_bf16 v[64:67], v[182:185], v[232:235], v[64:67]
	v_mfma_f32_16x16x32_bf16 v[116:119], v[178:181], v[194:197], v[116:119]
	v_mfma_f32_16x16x32_bf16 v[112:115], v[186:189], v[194:197], v[112:115]
	v_mfma_f32_16x16x32_bf16 v[100:103], v[178:181], v[202:205], v[100:103]
	v_mfma_f32_16x16x32_bf16 v[96:99], v[186:189], v[202:205], v[96:99]
	v_mfma_f32_16x16x32_bf16 v[84:87], v[178:181], v[228:231], v[84:87]
	v_mfma_f32_16x16x32_bf16 v[80:83], v[186:189], v[228:231], v[80:83]
	v_mfma_f32_16x16x32_bf16 v[68:71], v[178:181], v[236:239], v[68:71]
	v_mfma_f32_16x16x32_bf16 v[64:67], v[186:189], v[236:239], v[64:67]
	s_barrier
	s_add_i32 s29, s29, s68
	v_lshl_add_u64 v[142:143], v[142:143], 0, s[4:5]
	s_mov_b32 m0, s29
	ds_read_b128 v[190:193], v147 offset:49152
	ds_read_b128 v[194:197], v147 offset:50176
	ds_read_b128 v[198:201], v147 offset:51200
	ds_read_b128 v[202:205], v147 offset:52224
	ds_read_b128 v[220:223], v147 offset:53248
	ds_read_b128 v[228:231], v147 offset:54272
	ds_read_b128 v[232:235], v147 offset:55296
	ds_read_b128 v[236:239], v147 offset:56320
	global_load_lds_dwordx4 v[142:143], off
	s_add_i32 m0, s29, 0x2000
	s_add_u32 s30, s62, 0x40080
	v_lshl_add_u64 v[142:143], v[240:241], 0, s[4:5]
	s_addc_u32 s31, s63, 0
	s_add_i32 s29, s53, s68
	global_load_lds_dwordx4 v[142:143], off
	v_lshl_add_u64 v[142:143], s[30:31], 0, v[162:163]
	s_mov_b32 m0, s29
	s_nop 0
	global_load_lds_dwordx4 v[142:143], off
	v_lshl_add_u64 v[142:143], s[30:31], 0, v[128:129]
	s_add_i32 m0, s29, 0x2000
	s_nop 0
	global_load_lds_dwordx4 v[142:143], off
	v_lshl_add_u64 v[142:143], v[242:243], 0, s[4:5]
	s_mov_b32 m0, s74
	s_nop 0
	global_load_lds_dwordx4 v[142:143], off
	v_lshl_add_u64 v[142:143], v[244:245], 0, s[4:5]
	s_mov_b32 m0, s75
	s_nop 0
	global_load_lds_dwordx4 v[142:143], off
	s_waitcnt vmcnt(8)
	s_waitcnt lgkmcnt(0)
	s_barrier
	v_mfma_f32_16x16x32_bf16 v[60:63], v[138:141], v[190:193], v[60:63]
	v_mfma_f32_16x16x32_bf16 v[56:59], v[152:155], v[190:193], v[56:59]
	v_mfma_f32_16x16x32_bf16 v[44:47], v[138:141], v[198:201], v[44:47]
	v_mfma_f32_16x16x32_bf16 v[40:43], v[152:155], v[198:201], v[40:43]
	v_mfma_f32_16x16x32_bf16 v[28:31], v[138:141], v[220:223], v[28:31]
	v_mfma_f32_16x16x32_bf16 v[24:27], v[152:155], v[220:223], v[24:27]
	v_mfma_f32_16x16x32_bf16 v[12:15], v[138:141], v[232:235], v[12:15]
	v_mfma_f32_16x16x32_bf16 v[8:11], v[152:155], v[232:235], v[8:11]
	v_mfma_f32_16x16x32_bf16 v[60:63], v[148:151], v[194:197], v[60:63]
	v_mfma_f32_16x16x32_bf16 v[56:59], v[156:159], v[194:197], v[56:59]
	v_mfma_f32_16x16x32_bf16 v[44:47], v[148:151], v[202:205], v[44:47]
	v_mfma_f32_16x16x32_bf16 v[40:43], v[156:159], v[202:205], v[40:43]
	v_mfma_f32_16x16x32_bf16 v[28:31], v[148:151], v[228:231], v[28:31]
	v_mfma_f32_16x16x32_bf16 v[24:27], v[156:159], v[228:231], v[24:27]
	v_mfma_f32_16x16x32_bf16 v[12:15], v[148:151], v[236:239], v[12:15]
	v_mfma_f32_16x16x32_bf16 v[8:11], v[156:159], v[236:239], v[8:11]
	v_mfma_f32_16x16x32_bf16 v[52:55], v[174:177], v[190:193], v[52:55]
	v_mfma_f32_16x16x32_bf16 v[48:51], v[182:185], v[190:193], v[48:51]
	v_mfma_f32_16x16x32_bf16 v[36:39], v[174:177], v[198:201], v[36:39]
	v_mfma_f32_16x16x32_bf16 v[32:35], v[182:185], v[198:201], v[32:35]
	v_mfma_f32_16x16x32_bf16 v[20:23], v[174:177], v[220:223], v[20:23]
	v_mfma_f32_16x16x32_bf16 v[16:19], v[182:185], v[220:223], v[16:19]
	v_mfma_f32_16x16x32_bf16 v[4:7], v[174:177], v[232:235], v[4:7]
	v_mfma_f32_16x16x32_bf16 v[0:3], v[182:185], v[232:235], v[0:3]
	v_mfma_f32_16x16x32_bf16 v[52:55], v[178:181], v[194:197], v[52:55]
	v_mfma_f32_16x16x32_bf16 v[48:51], v[186:189], v[194:197], v[48:51]
	v_mfma_f32_16x16x32_bf16 v[36:39], v[178:181], v[202:205], v[36:39]
	v_mfma_f32_16x16x32_bf16 v[32:35], v[186:189], v[202:205], v[32:35]
	v_mfma_f32_16x16x32_bf16 v[20:23], v[178:181], v[228:231], v[20:23]
	v_mfma_f32_16x16x32_bf16 v[16:19], v[186:189], v[228:231], v[16:19]
	v_mfma_f32_16x16x32_bf16 v[4:7], v[178:181], v[236:239], v[4:7]
	v_mfma_f32_16x16x32_bf16 v[0:3], v[186:189], v[236:239], v[0:3]
	s_barrier
	s_add_i32 s28, s28, 2
	s_add_u32 s60, s60, 0x100
	s_addc_u32 s61, s61, 0
	s_add_u32 s26, s26, 0x100
	s_addc_u32 s27, s27, 0
	s_cmp_gt_u32 s28, 13
	s_cbranch_scc0 .LBB0_975
	s_and_b64 vcc, exec, s[50:51]
	s_cbranch_vccz .LBB0_978
	s_barrier

.LBB0_1066:
	s_add_u32 s29, s58, 0xfffc0080
	s_addc_u32 s30, s59, -1
	s_add_i32 s31, 0, 0x10000
	s_cmp_eq_u32 s28, 12
	s_cselect_b32 s63, s6, s30
	s_cselect_b32 s62, s7, s29
	v_add_u32_e32 v142, s31, v144
	s_cselect_b32 s61, s24, s27
	s_cselect_b32 s60, s25, s26
	s_add_i32 s29, 0, 0x14000
	ds_read_b128 v[138:141], v142
	ds_read_b128 v[148:151], v142 offset:1024
	ds_read_b128 v[152:155], v142 offset:2048
	ds_read_b128 v[156:159], v142 offset:3072
	v_add_u32_e32 v142, s29, v144
	ds_read_b128 v[174:177], v142
	ds_read_b128 v[178:181], v142 offset:1024
	ds_read_b128 v[182:185], v142 offset:2048
	ds_read_b128 v[186:189], v142 offset:3072
	v_lshl_add_u64 v[240:241], s[58:59], 0, v[134:135]
	s_add_i32 m0, s67, 0xc000
	ds_read_b128 v[190:193], v146
	ds_read_b128 v[194:197], v146 offset:1024
	ds_read_b128 v[198:201], v146 offset:2048
	ds_read_b128 v[202:205], v146 offset:3072
	ds_read_b128 v[220:223], v146 offset:4096
	ds_read_b128 v[228:231], v146 offset:5120
	ds_read_b128 v[232:235], v146 offset:6144
	ds_read_b128 v[236:239], v146 offset:7168
	global_load_lds_dwordx4 v[240:241], off
	v_lshl_add_u64 v[240:241], s[58:59], 0, v[136:137]
	s_add_i32 m0, s67, 0xe000
	s_nop 0
	global_load_lds_dwordx4 v[240:241], off
	s_waitcnt vmcnt(8)
	s_waitcnt lgkmcnt(0)
	s_barrier
	v_mfma_f32_16x16x32_bf16 v[124:127], v[138:141], v[190:193], v[124:127]
	v_mfma_f32_16x16x32_bf16 v[120:123], v[152:155], v[190:193], v[120:123]
	v_mfma_f32_16x16x32_bf16 v[108:111], v[138:141], v[198:201], v[108:111]
	v_mfma_f32_16x16x32_bf16 v[104:107], v[152:155], v[198:201], v[104:107]
	v_mfma_f32_16x16x32_bf16 v[92:95], v[138:141], v[220:223], v[92:95]
	v_mfma_f32_16x16x32_bf16 v[88:91], v[152:155], v[220:223], v[88:91]
	v_mfma_f32_16x16x32_bf16 v[76:79], v[138:141], v[232:235], v[76:79]
	v_mfma_f32_16x16x32_bf16 v[72:75], v[152:155], v[232:235], v[72:75]
	v_mfma_f32_16x16x32_bf16 v[124:127], v[148:151], v[194:197], v[124:127]
	v_mfma_f32_16x16x32_bf16 v[120:123], v[156:159], v[194:197], v[120:123]
	v_mfma_f32_16x16x32_bf16 v[108:111], v[148:151], v[202:205], v[108:111]
	v_mfma_f32_16x16x32_bf16 v[104:107], v[156:159], v[202:205], v[104:107]
	v_mfma_f32_16x16x32_bf16 v[92:95], v[148:151], v[228:231], v[92:95]
	v_mfma_f32_16x16x32_bf16 v[88:91], v[156:159], v[228:231], v[88:91]
	v_mfma_f32_16x16x32_bf16 v[76:79], v[148:151], v[236:239], v[76:79]
	v_mfma_f32_16x16x32_bf16 v[72:75], v[156:159], v[236:239], v[72:75]
	v_mfma_f32_16x16x32_bf16 v[116:119], v[174:177], v[190:193], v[116:119]
	v_mfma_f32_16x16x32_bf16 v[112:115], v[182:185], v[190:193], v[112:115]
	v_mfma_f32_16x16x32_bf16 v[100:103], v[174:177], v[198:201], v[100:103]
	v_mfma_f32_16x16x32_bf16 v[96:99], v[182:185], v[198:201], v[96:99]
	v_mfma_f32_16x16x32_bf16 v[84:87], v[174:177], v[220:223], v[84:87]
	v_mfma_f32_16x16x32_bf16 v[80:83], v[182:185], v[220:223], v[80:83]
	v_mfma_f32_16x16x32_bf16 v[68:71], v[174:177], v[232:235], v[68:71]
	v_mfma_f32_16x16x32_bf16 v[64:67], v[182:185], v[232:235], v[64:67]
	v_mfma_f32_16x16x32_bf16 v[116:119], v[178:181], v[194:197], v[116:119]
	v_mfma_f32_16x16x32_bf16 v[112:115], v[186:189], v[194:197], v[112:115]
	v_mfma_f32_16x16x32_bf16 v[100:103], v[178:181], v[202:205], v[100:103]
	v_mfma_f32_16x16x32_bf16 v[96:99], v[186:189], v[202:205], v[96:99]
	v_mfma_f32_16x16x32_bf16 v[84:87], v[178:181], v[228:231], v[84:87]
	v_mfma_f32_16x16x32_bf16 v[80:83], v[186:189], v[228:231], v[80:83]
	v_mfma_f32_16x16x32_bf16 v[68:71], v[178:181], v[236:239], v[68:71]
	v_mfma_f32_16x16x32_bf16 v[64:67], v[186:189], v[236:239], v[64:67]
	s_barrier
	s_add_i32 s30, s31, s66
	v_lshl_add_u64 v[240:241], s[60:61], 0, v[162:163]
	s_mov_b32 m0, s30
	ds_read_b128 v[190:193], v146 offset:16384
	ds_read_b128 v[194:197], v146 offset:17408
	ds_read_b128 v[198:201], v146 offset:18432
	ds_read_b128 v[202:205], v146 offset:19456
	ds_read_b128 v[220:223], v146 offset:20480
	ds_read_b128 v[228:231], v146 offset:21504
	ds_read_b128 v[232:235], v146 offset:22528
	ds_read_b128 v[236:239], v146 offset:23552
	global_load_lds_dwordx4 v[240:241], off
	s_add_i32 m0, s30, 0x2000
	s_add_u32 s30, s60, 0x40000
	v_lshl_add_u64 v[242:243], s[60:61], 0, v[128:129]
	s_addc_u32 s31, s61, 0
	s_add_i32 s29, s29, s66
	global_load_lds_dwordx4 v[242:243], off
	v_lshl_add_u64 v[244:245], s[30:31], 0, v[162:163]
	s_mov_b32 m0, s29
	v_lshl_add_u64 v[246:247], s[62:63], 0, v[130:131]
	global_load_lds_dwordx4 v[244:245], off
	v_lshl_add_u64 v[244:245], s[30:31], 0, v[128:129]
	s_add_i32 m0, s29, 0x2000
	s_nop 0
	global_load_lds_dwordx4 v[244:245], off
	v_lshl_add_u64 v[244:245], s[62:63], 0, v[132:133]
	s_mov_b32 m0, s67
	s_nop 0
	global_load_lds_dwordx4 v[244:245], off
	s_mov_b32 m0, s68
	s_nop 0
	global_load_lds_dwordx4 v[246:247], off
	s_waitcnt vmcnt(8)
	s_waitcnt lgkmcnt(0)
	s_barrier
	v_mfma_f32_16x16x32_bf16 v[60:63], v[138:141], v[190:193], v[60:63]
	v_mfma_f32_16x16x32_bf16 v[56:59], v[152:155], v[190:193], v[56:59]
	v_mfma_f32_16x16x32_bf16 v[44:47], v[138:141], v[198:201], v[44:47]
	v_mfma_f32_16x16x32_bf16 v[40:43], v[152:155], v[198:201], v[40:43]
	v_mfma_f32_16x16x32_bf16 v[28:31], v[138:141], v[220:223], v[28:31]
	v_mfma_f32_16x16x32_bf16 v[24:27], v[152:155], v[220:223], v[24:27]
	v_mfma_f32_16x16x32_bf16 v[12:15], v[138:141], v[232:235], v[12:15]
	v_mfma_f32_16x16x32_bf16 v[8:11], v[152:155], v[232:235], v[8:11]
	v_mfma_f32_16x16x32_bf16 v[60:63], v[148:151], v[194:197], v[60:63]
	v_mfma_f32_16x16x32_bf16 v[56:59], v[156:159], v[194:197], v[56:59]
	v_mfma_f32_16x16x32_bf16 v[44:47], v[148:151], v[202:205], v[44:47]
	v_mfma_f32_16x16x32_bf16 v[40:43], v[156:159], v[202:205], v[40:43]
	v_mfma_f32_16x16x32_bf16 v[28:31], v[148:151], v[228:231], v[28:31]
	v_mfma_f32_16x16x32_bf16 v[24:27], v[156:159], v[228:231], v[24:27]
	v_mfma_f32_16x16x32_bf16 v[12:15], v[148:151], v[236:239], v[12:15]
	v_mfma_f32_16x16x32_bf16 v[8:11], v[156:159], v[236:239], v[8:11]
	v_mfma_f32_16x16x32_bf16 v[52:55], v[174:177], v[190:193], v[52:55]
	v_mfma_f32_16x16x32_bf16 v[48:51], v[182:185], v[190:193], v[48:51]
	v_mfma_f32_16x16x32_bf16 v[36:39], v[174:177], v[198:201], v[36:39]
	v_mfma_f32_16x16x32_bf16 v[32:35], v[182:185], v[198:201], v[32:35]
	v_mfma_f32_16x16x32_bf16 v[20:23], v[174:177], v[220:223], v[20:23]
	v_mfma_f32_16x16x32_bf16 v[16:19], v[182:185], v[220:223], v[16:19]
	v_mfma_f32_16x16x32_bf16 v[4:7], v[174:177], v[232:235], v[4:7]
	v_mfma_f32_16x16x32_bf16 v[0:3], v[182:185], v[232:235], v[0:3]
	v_mfma_f32_16x16x32_bf16 v[52:55], v[178:181], v[194:197], v[52:55]
	v_mfma_f32_16x16x32_bf16 v[48:51], v[186:189], v[194:197], v[48:51]
	v_mfma_f32_16x16x32_bf16 v[36:39], v[178:181], v[202:205], v[36:39]
	v_mfma_f32_16x16x32_bf16 v[32:35], v[186:189], v[202:205], v[32:35]
	v_mfma_f32_16x16x32_bf16 v[20:23], v[178:181], v[228:231], v[20:23]
	v_mfma_f32_16x16x32_bf16 v[16:19], v[186:189], v[228:231], v[16:19]
	v_mfma_f32_16x16x32_bf16 v[4:7], v[178:181], v[236:239], v[4:7]
	v_mfma_f32_16x16x32_bf16 v[0:3], v[186:189], v[236:239], v[0:3]
	s_barrier
	s_add_i32 s29, 0, 0x18000
	v_add_u32_e32 v142, s29, v144
	s_add_i32 s51, 0, 0x1c000
	ds_read_b128 v[138:141], v142
	ds_read_b128 v[148:151], v142 offset:1024
	ds_read_b128 v[152:155], v142 offset:2048
	ds_read_b128 v[156:159], v142 offset:3072
	v_add_u32_e32 v142, s51, v144
	ds_read_b128 v[174:177], v142
	ds_read_b128 v[178:181], v142 offset:1024
	ds_read_b128 v[182:185], v142 offset:2048
	ds_read_b128 v[186:189], v142 offset:3072
	s_add_u32 s30, s62, 0x40000
	s_addc_u32 s31, s63, 0
	s_mov_b32 m0, s69
	v_lshl_add_u64 v[248:249], s[30:31], 0, v[132:133]
	ds_read_b128 v[190:193], v146 offset:32768
	ds_read_b128 v[194:197], v146 offset:33792
	ds_read_b128 v[198:201], v146 offset:34816
	ds_read_b128 v[202:205], v146 offset:35840
	ds_read_b128 v[220:223], v146 offset:36864
	ds_read_b128 v[228:231], v146 offset:37888
	ds_read_b128 v[232:235], v146 offset:38912
	ds_read_b128 v[236:239], v146 offset:39936
	global_load_lds_dwordx4 v[248:249], off
	v_lshl_add_u64 v[248:249], s[30:31], 0, v[130:131]
	s_mov_b32 m0, s70
	s_nop 0
	global_load_lds_dwordx4 v[248:249], off
	s_waitcnt vmcnt(8)
	s_waitcnt lgkmcnt(0)
	s_barrier
	v_mfma_f32_16x16x32_bf16 v[124:127], v[138:141], v[190:193], v[124:127]
	v_mfma_f32_16x16x32_bf16 v[120:123], v[152:155], v[190:193], v[120:123]
	v_mfma_f32_16x16x32_bf16 v[108:111], v[138:141], v[198:201], v[108:111]
	v_mfma_f32_16x16x32_bf16 v[104:107], v[152:155], v[198:201], v[104:107]
	v_mfma_f32_16x16x32_bf16 v[92:95], v[138:141], v[220:223], v[92:95]
	v_mfma_f32_16x16x32_bf16 v[88:91], v[152:155], v[220:223], v[88:91]
	v_mfma_f32_16x16x32_bf16 v[76:79], v[138:141], v[232:235], v[76:79]
	v_mfma_f32_16x16x32_bf16 v[72:75], v[152:155], v[232:235], v[72:75]
	v_mfma_f32_16x16x32_bf16 v[124:127], v[148:151], v[194:197], v[124:127]
	v_mfma_f32_16x16x32_bf16 v[120:123], v[156:159], v[194:197], v[120:123]
	v_mfma_f32_16x16x32_bf16 v[108:111], v[148:151], v[202:205], v[108:111]
	v_mfma_f32_16x16x32_bf16 v[104:107], v[156:159], v[202:205], v[104:107]
	v_mfma_f32_16x16x32_bf16 v[92:95], v[148:151], v[228:231], v[92:95]
	v_mfma_f32_16x16x32_bf16 v[88:91], v[156:159], v[228:231], v[88:91]
	v_mfma_f32_16x16x32_bf16 v[76:79], v[148:151], v[236:239], v[76:79]
	v_mfma_f32_16x16x32_bf16 v[72:75], v[156:159], v[236:239], v[72:75]
	v_mfma_f32_16x16x32_bf16 v[116:119], v[174:177], v[190:193], v[116:119]
	v_mfma_f32_16x16x32_bf16 v[112:115], v[182:185], v[190:193], v[112:115]
	v_mfma_f32_16x16x32_bf16 v[100:103], v[174:177], v[198:201], v[100:103]
	v_mfma_f32_16x16x32_bf16 v[96:99], v[182:185], v[198:201], v[96:99]
	v_mfma_f32_16x16x32_bf16 v[84:87], v[174:177], v[220:223], v[84:87]
	v_mfma_f32_16x16x32_bf16 v[80:83], v[182:185], v[220:223], v[80:83]
	v_mfma_f32_16x16x32_bf16 v[68:71], v[174:177], v[232:235], v[68:71]
	v_mfma_f32_16x16x32_bf16 v[64:67], v[182:185], v[232:235], v[64:67]
	v_mfma_f32_16x16x32_bf16 v[116:119], v[178:181], v[194:197], v[116:119]
	v_mfma_f32_16x16x32_bf16 v[112:115], v[186:189], v[194:197], v[112:115]
	v_mfma_f32_16x16x32_bf16 v[100:103], v[178:181], v[202:205], v[100:103]
	v_mfma_f32_16x16x32_bf16 v[96:99], v[186:189], v[202:205], v[96:99]
	v_mfma_f32_16x16x32_bf16 v[84:87], v[178:181], v[228:231], v[84:87]
	v_mfma_f32_16x16x32_bf16 v[80:83], v[186:189], v[228:231], v[80:83]
	v_mfma_f32_16x16x32_bf16 v[68:71], v[178:181], v[236:239], v[68:71]
	v_mfma_f32_16x16x32_bf16 v[64:67], v[186:189], v[236:239], v[64:67]
	s_barrier
	s_add_i32 s29, s29, s66
	v_lshl_add_u64 v[240:241], v[240:241], 0, s[4:5]
	s_mov_b32 m0, s29
	ds_read_b128 v[190:193], v146 offset:49152
	ds_read_b128 v[194:197], v146 offset:50176
	ds_read_b128 v[198:201], v146 offset:51200
	ds_read_b128 v[202:205], v146 offset:52224
	ds_read_b128 v[220:223], v146 offset:53248
	ds_read_b128 v[228:231], v146 offset:54272
	ds_read_b128 v[232:235], v146 offset:55296
	ds_read_b128 v[236:239], v146 offset:56320
	global_load_lds_dwordx4 v[240:241], off
	s_add_i32 m0, s29, 0x2000
	s_add_u32 s30, s60, 0x40080
	v_lshl_add_u64 v[240:241], v[242:243], 0, s[4:5]
	s_addc_u32 s31, s61, 0
	s_add_i32 s29, s51, s66
	global_load_lds_dwordx4 v[240:241], off
	v_lshl_add_u64 v[240:241], s[30:31], 0, v[162:163]
	s_mov_b32 m0, s29
	s_nop 0
	global_load_lds_dwordx4 v[240:241], off
	v_lshl_add_u64 v[240:241], s[30:31], 0, v[128:129]
	s_add_i32 m0, s29, 0x2000
	s_nop 0
	global_load_lds_dwordx4 v[240:241], off
	v_lshl_add_u64 v[240:241], v[244:245], 0, s[4:5]
	s_mov_b32 m0, s71
	s_nop 0
	global_load_lds_dwordx4 v[240:241], off
	v_lshl_add_u64 v[240:241], v[246:247], 0, s[4:5]
	s_mov_b32 m0, s72
	s_nop 0
	global_load_lds_dwordx4 v[240:241], off
	s_waitcnt vmcnt(8)
	s_waitcnt lgkmcnt(0)
	s_barrier
	v_mfma_f32_16x16x32_bf16 v[60:63], v[138:141], v[190:193], v[60:63]
	v_mfma_f32_16x16x32_bf16 v[56:59], v[152:155], v[190:193], v[56:59]
	v_mfma_f32_16x16x32_bf16 v[44:47], v[138:141], v[198:201], v[44:47]
	v_mfma_f32_16x16x32_bf16 v[40:43], v[152:155], v[198:201], v[40:43]
	v_mfma_f32_16x16x32_bf16 v[28:31], v[138:141], v[220:223], v[28:31]
	v_mfma_f32_16x16x32_bf16 v[24:27], v[152:155], v[220:223], v[24:27]
	v_mfma_f32_16x16x32_bf16 v[12:15], v[138:141], v[232:235], v[12:15]
	v_mfma_f32_16x16x32_bf16 v[8:11], v[152:155], v[232:235], v[8:11]
	v_mfma_f32_16x16x32_bf16 v[60:63], v[148:151], v[194:197], v[60:63]
	v_mfma_f32_16x16x32_bf16 v[56:59], v[156:159], v[194:197], v[56:59]
	v_mfma_f32_16x16x32_bf16 v[44:47], v[148:151], v[202:205], v[44:47]
	v_mfma_f32_16x16x32_bf16 v[40:43], v[156:159], v[202:205], v[40:43]
	v_mfma_f32_16x16x32_bf16 v[28:31], v[148:151], v[228:231], v[28:31]
	v_mfma_f32_16x16x32_bf16 v[24:27], v[156:159], v[228:231], v[24:27]
	v_mfma_f32_16x16x32_bf16 v[12:15], v[148:151], v[236:239], v[12:15]
	v_mfma_f32_16x16x32_bf16 v[8:11], v[156:159], v[236:239], v[8:11]
	v_mfma_f32_16x16x32_bf16 v[52:55], v[174:177], v[190:193], v[52:55]
	v_mfma_f32_16x16x32_bf16 v[48:51], v[182:185], v[190:193], v[48:51]
	v_mfma_f32_16x16x32_bf16 v[36:39], v[174:177], v[198:201], v[36:39]
	v_mfma_f32_16x16x32_bf16 v[32:35], v[182:185], v[198:201], v[32:35]
	v_mfma_f32_16x16x32_bf16 v[20:23], v[174:177], v[220:223], v[20:23]
	v_mfma_f32_16x16x32_bf16 v[16:19], v[182:185], v[220:223], v[16:19]
	v_mfma_f32_16x16x32_bf16 v[4:7], v[174:177], v[232:235], v[4:7]
	v_mfma_f32_16x16x32_bf16 v[0:3], v[182:185], v[232:235], v[0:3]
	v_mfma_f32_16x16x32_bf16 v[52:55], v[178:181], v[194:197], v[52:55]
	v_mfma_f32_16x16x32_bf16 v[48:51], v[186:189], v[194:197], v[48:51]
	v_mfma_f32_16x16x32_bf16 v[36:39], v[178:181], v[202:205], v[36:39]
	v_mfma_f32_16x16x32_bf16 v[32:35], v[186:189], v[202:205], v[32:35]
	v_mfma_f32_16x16x32_bf16 v[20:23], v[178:181], v[228:231], v[20:23]
	v_mfma_f32_16x16x32_bf16 v[16:19], v[186:189], v[228:231], v[16:19]
	v_mfma_f32_16x16x32_bf16 v[4:7], v[178:181], v[236:239], v[4:7]
	v_mfma_f32_16x16x32_bf16 v[0:3], v[186:189], v[236:239], v[0:3]
	s_barrier
	s_add_i32 s28, s28, 2
	s_add_u32 s58, s58, 0x100
	s_addc_u32 s59, s59, 0
	s_add_u32 s26, s26, 0x100
	s_addc_u32 s27, s27, 0
	s_cmp_gt_u32 s28, 13
	s_cbranch_scc0 .LBB0_1066
	s_and_b64 vcc, exec, s[48:49]
	s_cbranch_vccz .LBB0_1069
	s_barrier

.LBB0_1280:
	s_add_u32 s60, s58, 0x100
	s_addc_u32 s61, s59, 0
	s_add_i32 s25, 0, 0x10000
	s_cmp_eq_u32 s24, 40
	s_cselect_b32 s65, s45, s61
	s_cselect_b32 s64, s44, s60
	v_add_u32_e32 v142, s25, v145
	s_cselect_b32 s63, s57, s7
	s_cselect_b32 s62, s56, s6
	s_add_i32 s28, 0, 0x14000
	ds_read_b128 v[138:141], v142
	ds_read_b128 v[148:151], v142 offset:1024
	ds_read_b128 v[152:155], v142 offset:2048
	ds_read_b128 v[156:159], v142 offset:3072
	v_add_u32_e32 v142, s28, v145
	ds_read_b128 v[174:177], v142
	ds_read_b128 v[178:181], v142 offset:1024
	ds_read_b128 v[182:185], v142 offset:2048
	ds_read_b128 v[186:189], v142 offset:3072
	v_lshl_add_u64 v[142:143], s[58:59], 0, v[134:135]
	s_add_i32 m0, s68, 0xc000
	ds_read_b128 v[190:193], v147
	ds_read_b128 v[194:197], v147 offset:1024
	ds_read_b128 v[198:201], v147 offset:2048
	ds_read_b128 v[202:205], v147 offset:3072
	ds_read_b128 v[220:223], v147 offset:4096
	ds_read_b128 v[228:231], v147 offset:5120
	ds_read_b128 v[232:235], v147 offset:6144
	ds_read_b128 v[236:239], v147 offset:7168
	global_load_lds_dwordx4 v[142:143], off
	v_lshl_add_u64 v[142:143], s[58:59], 0, v[136:137]
	s_add_i32 m0, s68, 0xe000
	s_nop 0
	global_load_lds_dwordx4 v[142:143], off
	s_waitcnt vmcnt(8)
	s_waitcnt lgkmcnt(0)
	s_barrier
	v_mfma_f32_16x16x32_bf16 v[124:127], v[138:141], v[190:193], v[124:127]
	v_mfma_f32_16x16x32_bf16 v[120:123], v[152:155], v[190:193], v[120:123]
	v_mfma_f32_16x16x32_bf16 v[108:111], v[138:141], v[198:201], v[108:111]
	v_mfma_f32_16x16x32_bf16 v[104:107], v[152:155], v[198:201], v[104:107]
	v_mfma_f32_16x16x32_bf16 v[92:95], v[138:141], v[220:223], v[92:95]
	v_mfma_f32_16x16x32_bf16 v[88:91], v[152:155], v[220:223], v[88:91]
	v_mfma_f32_16x16x32_bf16 v[76:79], v[138:141], v[232:235], v[76:79]
	v_mfma_f32_16x16x32_bf16 v[72:75], v[152:155], v[232:235], v[72:75]
	v_mfma_f32_16x16x32_bf16 v[124:127], v[148:151], v[194:197], v[124:127]
	v_mfma_f32_16x16x32_bf16 v[120:123], v[156:159], v[194:197], v[120:123]
	v_mfma_f32_16x16x32_bf16 v[108:111], v[148:151], v[202:205], v[108:111]
	v_mfma_f32_16x16x32_bf16 v[104:107], v[156:159], v[202:205], v[104:107]
	v_mfma_f32_16x16x32_bf16 v[92:95], v[148:151], v[228:231], v[92:95]
	v_mfma_f32_16x16x32_bf16 v[88:91], v[156:159], v[228:231], v[88:91]
	v_mfma_f32_16x16x32_bf16 v[76:79], v[148:151], v[236:239], v[76:79]
	v_mfma_f32_16x16x32_bf16 v[72:75], v[156:159], v[236:239], v[72:75]
	v_mfma_f32_16x16x32_bf16 v[116:119], v[174:177], v[190:193], v[116:119]
	v_mfma_f32_16x16x32_bf16 v[112:115], v[182:185], v[190:193], v[112:115]
	v_mfma_f32_16x16x32_bf16 v[100:103], v[174:177], v[198:201], v[100:103]
	v_mfma_f32_16x16x32_bf16 v[96:99], v[182:185], v[198:201], v[96:99]
	v_mfma_f32_16x16x32_bf16 v[84:87], v[174:177], v[220:223], v[84:87]
	v_mfma_f32_16x16x32_bf16 v[80:83], v[182:185], v[220:223], v[80:83]
	v_mfma_f32_16x16x32_bf16 v[68:71], v[174:177], v[232:235], v[68:71]
	v_mfma_f32_16x16x32_bf16 v[64:67], v[182:185], v[232:235], v[64:67]
	v_mfma_f32_16x16x32_bf16 v[116:119], v[178:181], v[194:197], v[116:119]
	v_mfma_f32_16x16x32_bf16 v[112:115], v[186:189], v[194:197], v[112:115]
	v_mfma_f32_16x16x32_bf16 v[100:103], v[178:181], v[202:205], v[100:103]
	v_mfma_f32_16x16x32_bf16 v[96:99], v[186:189], v[202:205], v[96:99]
	v_mfma_f32_16x16x32_bf16 v[84:87], v[178:181], v[228:231], v[84:87]
	v_mfma_f32_16x16x32_bf16 v[80:83], v[186:189], v[228:231], v[80:83]
	v_mfma_f32_16x16x32_bf16 v[68:71], v[178:181], v[236:239], v[68:71]
	v_mfma_f32_16x16x32_bf16 v[64:67], v[186:189], v[236:239], v[64:67]
	s_barrier
	s_add_i32 s25, s25, s67
	v_lshl_add_u64 v[142:143], s[62:63], 0, v[162:163]
	s_mov_b32 m0, s25
	ds_read_b128 v[190:193], v147 offset:16384
	ds_read_b128 v[194:197], v147 offset:17408
	ds_read_b128 v[198:201], v147 offset:18432
	ds_read_b128 v[202:205], v147 offset:19456
	ds_read_b128 v[220:223], v147 offset:20480
	ds_read_b128 v[228:231], v147 offset:21504
	ds_read_b128 v[232:235], v147 offset:22528
	ds_read_b128 v[236:239], v147 offset:23552
	global_load_lds_dwordx4 v[142:143], off
	s_add_i32 m0, s25, 0x2000
	s_add_u32 s26, s62, 0xb0000
	v_lshl_add_u64 v[240:241], s[62:63], 0, v[128:129]
	s_addc_u32 s27, s63, 0
	s_add_i32 s25, s28, s67
	global_load_lds_dwordx4 v[240:241], off
	v_lshl_add_u64 v[242:243], s[26:27], 0, v[162:163]
	s_mov_b32 m0, s25
	v_lshl_add_u64 v[244:245], s[64:65], 0, v[130:131]
	global_load_lds_dwordx4 v[242:243], off
	v_lshl_add_u64 v[242:243], s[26:27], 0, v[128:129]
	s_add_i32 m0, s25, 0x2000
	s_nop 0
	global_load_lds_dwordx4 v[242:243], off
	v_lshl_add_u64 v[242:243], s[64:65], 0, v[132:133]
	s_mov_b32 m0, s68
	s_nop 0
	global_load_lds_dwordx4 v[242:243], off
	s_mov_b32 m0, s69
	s_nop 0
	global_load_lds_dwordx4 v[244:245], off
	s_waitcnt vmcnt(8)
	s_waitcnt lgkmcnt(0)
	s_barrier
	v_mfma_f32_16x16x32_bf16 v[60:63], v[138:141], v[190:193], v[60:63]
	v_mfma_f32_16x16x32_bf16 v[56:59], v[152:155], v[190:193], v[56:59]
	v_mfma_f32_16x16x32_bf16 v[44:47], v[138:141], v[198:201], v[44:47]
	v_mfma_f32_16x16x32_bf16 v[40:43], v[152:155], v[198:201], v[40:43]
	v_mfma_f32_16x16x32_bf16 v[28:31], v[138:141], v[220:223], v[28:31]
	v_mfma_f32_16x16x32_bf16 v[24:27], v[152:155], v[220:223], v[24:27]
	v_mfma_f32_16x16x32_bf16 v[12:15], v[138:141], v[232:235], v[12:15]
	v_mfma_f32_16x16x32_bf16 v[8:11], v[152:155], v[232:235], v[8:11]
	v_mfma_f32_16x16x32_bf16 v[60:63], v[148:151], v[194:197], v[60:63]
	v_mfma_f32_16x16x32_bf16 v[56:59], v[156:159], v[194:197], v[56:59]
	v_mfma_f32_16x16x32_bf16 v[44:47], v[148:151], v[202:205], v[44:47]
	v_mfma_f32_16x16x32_bf16 v[40:43], v[156:159], v[202:205], v[40:43]
	v_mfma_f32_16x16x32_bf16 v[28:31], v[148:151], v[228:231], v[28:31]
	v_mfma_f32_16x16x32_bf16 v[24:27], v[156:159], v[228:231], v[24:27]
	v_mfma_f32_16x16x32_bf16 v[12:15], v[148:151], v[236:239], v[12:15]
	v_mfma_f32_16x16x32_bf16 v[8:11], v[156:159], v[236:239], v[8:11]
	v_mfma_f32_16x16x32_bf16 v[52:55], v[174:177], v[190:193], v[52:55]
	v_mfma_f32_16x16x32_bf16 v[48:51], v[182:185], v[190:193], v[48:51]
	v_mfma_f32_16x16x32_bf16 v[36:39], v[174:177], v[198:201], v[36:39]
	v_mfma_f32_16x16x32_bf16 v[32:35], v[182:185], v[198:201], v[32:35]
	v_mfma_f32_16x16x32_bf16 v[20:23], v[174:177], v[220:223], v[20:23]
	v_mfma_f32_16x16x32_bf16 v[16:19], v[182:185], v[220:223], v[16:19]
	v_mfma_f32_16x16x32_bf16 v[4:7], v[174:177], v[232:235], v[4:7]
	v_mfma_f32_16x16x32_bf16 v[0:3], v[182:185], v[232:235], v[0:3]
	v_mfma_f32_16x16x32_bf16 v[52:55], v[178:181], v[194:197], v[52:55]
	v_mfma_f32_16x16x32_bf16 v[48:51], v[186:189], v[194:197], v[48:51]
	v_mfma_f32_16x16x32_bf16 v[36:39], v[178:181], v[202:205], v[36:39]
	v_mfma_f32_16x16x32_bf16 v[32:35], v[186:189], v[202:205], v[32:35]
	v_mfma_f32_16x16x32_bf16 v[20:23], v[178:181], v[228:231], v[20:23]
	v_mfma_f32_16x16x32_bf16 v[16:19], v[186:189], v[228:231], v[16:19]
	v_mfma_f32_16x16x32_bf16 v[4:7], v[178:181], v[236:239], v[4:7]
	v_mfma_f32_16x16x32_bf16 v[0:3], v[186:189], v[236:239], v[0:3]
	s_barrier
	s_add_i32 s25, 0, 0x18000
	s_add_i32 s28, 0, 0x1c000
	v_add_u32_e32 v156, s25, v145
	v_add_u32_e32 v186, s28, v145
	ds_read_b128 v[138:141], v156
	ds_read_b128 v[148:151], v156 offset:1024
	ds_read_b128 v[152:155], v156 offset:2048
	ds_read_b128 v[156:159], v156 offset:3072
	ds_read_b128 v[174:177], v186
	ds_read_b128 v[178:181], v186 offset:1024
	ds_read_b128 v[182:185], v186 offset:2048
	ds_read_b128 v[186:189], v186 offset:3072
	s_add_u32 s26, s64, 0xb0000
	s_addc_u32 s27, s65, 0
	s_mov_b32 m0, s70
	v_lshl_add_u64 v[246:247], s[26:27], 0, v[132:133]
	ds_read_b128 v[190:193], v147 offset:32768
	ds_read_b128 v[194:197], v147 offset:33792
	ds_read_b128 v[198:201], v147 offset:34816
	ds_read_b128 v[202:205], v147 offset:35840
	ds_read_b128 v[220:223], v147 offset:36864
	ds_read_b128 v[228:231], v147 offset:37888
	ds_read_b128 v[232:235], v147 offset:38912
	ds_read_b128 v[236:239], v147 offset:39936
	global_load_lds_dwordx4 v[246:247], off
	v_lshl_add_u64 v[246:247], s[26:27], 0, v[130:131]
	s_mov_b32 m0, s71
	s_nop 0
	global_load_lds_dwordx4 v[246:247], off
	s_waitcnt vmcnt(8)
	s_waitcnt lgkmcnt(0)
	s_barrier
	v_mfma_f32_16x16x32_bf16 v[124:127], v[138:141], v[190:193], v[124:127]
	v_mfma_f32_16x16x32_bf16 v[120:123], v[152:155], v[190:193], v[120:123]
	v_mfma_f32_16x16x32_bf16 v[108:111], v[138:141], v[198:201], v[108:111]
	v_mfma_f32_16x16x32_bf16 v[104:107], v[152:155], v[198:201], v[104:107]
	v_mfma_f32_16x16x32_bf16 v[92:95], v[138:141], v[220:223], v[92:95]
	v_mfma_f32_16x16x32_bf16 v[88:91], v[152:155], v[220:223], v[88:91]
	v_mfma_f32_16x16x32_bf16 v[76:79], v[138:141], v[232:235], v[76:79]
	v_mfma_f32_16x16x32_bf16 v[72:75], v[152:155], v[232:235], v[72:75]
	v_mfma_f32_16x16x32_bf16 v[124:127], v[148:151], v[194:197], v[124:127]
	v_mfma_f32_16x16x32_bf16 v[120:123], v[156:159], v[194:197], v[120:123]
	v_mfma_f32_16x16x32_bf16 v[108:111], v[148:151], v[202:205], v[108:111]
	v_mfma_f32_16x16x32_bf16 v[104:107], v[156:159], v[202:205], v[104:107]
	v_mfma_f32_16x16x32_bf16 v[92:95], v[148:151], v[228:231], v[92:95]
	v_mfma_f32_16x16x32_bf16 v[88:91], v[156:159], v[228:231], v[88:91]
	v_mfma_f32_16x16x32_bf16 v[76:79], v[148:151], v[236:239], v[76:79]
	v_mfma_f32_16x16x32_bf16 v[72:75], v[156:159], v[236:239], v[72:75]
	v_mfma_f32_16x16x32_bf16 v[116:119], v[174:177], v[190:193], v[116:119]
	v_mfma_f32_16x16x32_bf16 v[112:115], v[182:185], v[190:193], v[112:115]
	v_mfma_f32_16x16x32_bf16 v[100:103], v[174:177], v[198:201], v[100:103]
	v_mfma_f32_16x16x32_bf16 v[96:99], v[182:185], v[198:201], v[96:99]
	v_mfma_f32_16x16x32_bf16 v[84:87], v[174:177], v[220:223], v[84:87]
	v_mfma_f32_16x16x32_bf16 v[80:83], v[182:185], v[220:223], v[80:83]
	v_mfma_f32_16x16x32_bf16 v[68:71], v[174:177], v[232:235], v[68:71]
	v_mfma_f32_16x16x32_bf16 v[64:67], v[182:185], v[232:235], v[64:67]
	v_mfma_f32_16x16x32_bf16 v[116:119], v[178:181], v[194:197], v[116:119]
	v_mfma_f32_16x16x32_bf16 v[112:115], v[186:189], v[194:197], v[112:115]
	v_mfma_f32_16x16x32_bf16 v[100:103], v[178:181], v[202:205], v[100:103]
	v_mfma_f32_16x16x32_bf16 v[96:99], v[186:189], v[202:205], v[96:99]
	v_mfma_f32_16x16x32_bf16 v[84:87], v[178:181], v[228:231], v[84:87]
	v_mfma_f32_16x16x32_bf16 v[80:83], v[186:189], v[228:231], v[80:83]
	v_mfma_f32_16x16x32_bf16 v[68:71], v[178:181], v[236:239], v[68:71]
	v_mfma_f32_16x16x32_bf16 v[64:67], v[186:189], v[236:239], v[64:67]
	s_barrier
	s_add_i32 s25, s25, s67
	v_lshl_add_u64 v[142:143], v[142:143], 0, s[4:5]
	s_mov_b32 m0, s25
	ds_read_b128 v[190:193], v147 offset:49152
	ds_read_b128 v[194:197], v147 offset:50176
	ds_read_b128 v[198:201], v147 offset:51200
	ds_read_b128 v[202:205], v147 offset:52224
	ds_read_b128 v[220:223], v147 offset:53248
	ds_read_b128 v[228:231], v147 offset:54272
	ds_read_b128 v[232:235], v147 offset:55296
	ds_read_b128 v[236:239], v147 offset:56320
	global_load_lds_dwordx4 v[142:143], off
	s_add_i32 m0, s25, 0x2000
	s_add_u32 s26, s62, 0xb0080
	v_lshl_add_u64 v[142:143], v[240:241], 0, s[4:5]
	s_addc_u32 s27, s63, 0
	s_add_i32 s25, s28, s67
	global_load_lds_dwordx4 v[142:143], off
	v_lshl_add_u64 v[142:143], s[26:27], 0, v[162:163]
	s_mov_b32 m0, s25
	s_nop 0
	global_load_lds_dwordx4 v[142:143], off
	v_lshl_add_u64 v[142:143], s[26:27], 0, v[128:129]
	s_add_i32 m0, s25, 0x2000
	s_nop 0
	global_load_lds_dwordx4 v[142:143], off
	v_lshl_add_u64 v[142:143], v[242:243], 0, s[4:5]
	s_mov_b32 m0, s73
	s_nop 0
	global_load_lds_dwordx4 v[142:143], off
	v_lshl_add_u64 v[142:143], v[244:245], 0, s[4:5]
	s_mov_b32 m0, s74
	s_nop 0
	global_load_lds_dwordx4 v[142:143], off
	s_waitcnt vmcnt(8)
	s_waitcnt lgkmcnt(0)
	s_barrier
	v_mfma_f32_16x16x32_bf16 v[60:63], v[138:141], v[190:193], v[60:63]
	v_mfma_f32_16x16x32_bf16 v[56:59], v[152:155], v[190:193], v[56:59]
	v_mfma_f32_16x16x32_bf16 v[44:47], v[138:141], v[198:201], v[44:47]
	v_mfma_f32_16x16x32_bf16 v[40:43], v[152:155], v[198:201], v[40:43]
	v_mfma_f32_16x16x32_bf16 v[28:31], v[138:141], v[220:223], v[28:31]
	v_mfma_f32_16x16x32_bf16 v[24:27], v[152:155], v[220:223], v[24:27]
	v_mfma_f32_16x16x32_bf16 v[12:15], v[138:141], v[232:235], v[12:15]
	v_mfma_f32_16x16x32_bf16 v[8:11], v[152:155], v[232:235], v[8:11]
	v_mfma_f32_16x16x32_bf16 v[60:63], v[148:151], v[194:197], v[60:63]
	v_mfma_f32_16x16x32_bf16 v[56:59], v[156:159], v[194:197], v[56:59]
	v_mfma_f32_16x16x32_bf16 v[44:47], v[148:151], v[202:205], v[44:47]
	v_mfma_f32_16x16x32_bf16 v[40:43], v[156:159], v[202:205], v[40:43]
	v_mfma_f32_16x16x32_bf16 v[28:31], v[148:151], v[228:231], v[28:31]
	v_mfma_f32_16x16x32_bf16 v[24:27], v[156:159], v[228:231], v[24:27]
	v_mfma_f32_16x16x32_bf16 v[12:15], v[148:151], v[236:239], v[12:15]
	v_mfma_f32_16x16x32_bf16 v[8:11], v[156:159], v[236:239], v[8:11]
	v_mfma_f32_16x16x32_bf16 v[52:55], v[174:177], v[190:193], v[52:55]
	v_mfma_f32_16x16x32_bf16 v[48:51], v[182:185], v[190:193], v[48:51]
	v_mfma_f32_16x16x32_bf16 v[36:39], v[174:177], v[198:201], v[36:39]
	v_mfma_f32_16x16x32_bf16 v[32:35], v[182:185], v[198:201], v[32:35]
	v_mfma_f32_16x16x32_bf16 v[20:23], v[174:177], v[220:223], v[20:23]
	v_mfma_f32_16x16x32_bf16 v[16:19], v[182:185], v[220:223], v[16:19]
	v_mfma_f32_16x16x32_bf16 v[4:7], v[174:177], v[232:235], v[4:7]
	v_mfma_f32_16x16x32_bf16 v[0:3], v[182:185], v[232:235], v[0:3]
	v_mfma_f32_16x16x32_bf16 v[52:55], v[178:181], v[194:197], v[52:55]
	v_mfma_f32_16x16x32_bf16 v[48:51], v[186:189], v[194:197], v[48:51]
	v_mfma_f32_16x16x32_bf16 v[36:39], v[178:181], v[202:205], v[36:39]
	v_mfma_f32_16x16x32_bf16 v[32:35], v[186:189], v[202:205], v[32:35]
	v_mfma_f32_16x16x32_bf16 v[20:23], v[178:181], v[228:231], v[20:23]
	v_mfma_f32_16x16x32_bf16 v[16:19], v[186:189], v[228:231], v[16:19]
	v_mfma_f32_16x16x32_bf16 v[4:7], v[178:181], v[236:239], v[4:7]
	v_mfma_f32_16x16x32_bf16 v[0:3], v[186:189], v[236:239], v[0:3]
	s_barrier
	s_add_i32 s24, s24, 2
	s_add_u32 s6, s6, 0x100
	s_addc_u32 s7, s7, 0
	s_cmp_gt_u32 s24, 41
	s_mov_b64 s[58:59], s[60:61]
	s_cbranch_scc0 .LBB0_1280
	s_and_b64 vcc, exec, s[54:55]
	s_cbranch_vccz .LBB0_1283
	s_barrier
